# stack of the individually neutral instruction-count cuts on the no-setprio version: SGPR-base DMA addresses, dead M0 save/restore, DPP reductions, cached ws pointer, merged GEMM waits, attention step-
# speedup vs baseline: 1.0023x; 1.0023x over previous
.LBB0_342:
	s_and_b64 s[10:11], s[48:49], exec
	s_cselect_b32 s50, s45, s5
	s_cselect_b32 s51, s44, s4
	s_cselect_b32 s53, s47, s9
	s_cselect_b32 s54, s46, s8
	s_add_u32 s55, s8, 0x100
	s_addc_u32 s78, s9, 0
	s_add_u32 s4, s4, 0x40080
	v_mov_b32_e32 v0, 0
	s_addc_u32 s5, s5, 0
	s_mov_b32 s79, -2
	ds_read_b128 v[128:131], v169
	ds_read_b128 v[132:135], v169 offset:1024
	ds_read_b128 v[136:139], v169 offset:2048
	ds_read_b128 v[140:143], v169 offset:3072
	ds_read_b128 v[158:161], v170
	ds_read_b128 v[162:165], v170 offset:1024
	ds_read_b128 v[178:181], v170 offset:2048
	ds_read_b128 v[182:185], v170 offset:3072
	s_add_u32 s8, s4, 0xfffc0080
	s_addc_u32 s9, s5, -1
	s_cmp_eq_u32 s79, 12
	s_cselect_b32 s11, s50, s9
	s_cselect_b32 s10, s51, s8
	s_cselect_b32 s9, s53, s78
	s_cselect_b32 s8, s54, s55
	s_add_i32 m0, s28, 0xc000
	ds_read_b128 v[186:189], v171
	ds_read_b128 v[190:193], v171 offset:1024
	ds_read_b128 v[194:197], v171 offset:2048
	ds_read_b128 v[198:201], v171 offset:3072
	ds_read_b128 v[202:205], v171 offset:4096
	ds_read_b128 v[206:209], v171 offset:5120
	ds_read_b128 v[210:213], v171 offset:6144
	ds_read_b128 v[214:217], v171 offset:7168
	global_load_lds_dwordx4 v156, s[4:5]
	s_add_i32 m0, s28, 0xe000
	s_nop 0
	global_load_lds_dwordx4 v154, s[4:5]
	s_waitcnt vmcnt(8) lgkmcnt(0)
	s_barrier
	v_mfma_f32_16x16x32_bf16 v[124:127], v[128:131], v[186:189], 0
	v_mfma_f32_16x16x32_bf16 v[120:123], v[136:139], v[186:189], 0
	v_mfma_f32_16x16x32_bf16 v[108:111], v[128:131], v[194:197], 0
	v_mfma_f32_16x16x32_bf16 v[104:107], v[136:139], v[194:197], 0
	v_mfma_f32_16x16x32_bf16 v[92:95], v[128:131], v[202:205], 0
	v_mfma_f32_16x16x32_bf16 v[88:91], v[136:139], v[202:205], 0
	v_mfma_f32_16x16x32_bf16 v[76:79], v[128:131], v[210:213], 0
	v_mfma_f32_16x16x32_bf16 v[72:75], v[136:139], v[210:213], 0
	v_mfma_f32_16x16x32_bf16 v[124:127], v[132:135], v[190:193], v[124:127]
	v_mfma_f32_16x16x32_bf16 v[120:123], v[140:143], v[190:193], v[120:123]
	v_mfma_f32_16x16x32_bf16 v[108:111], v[132:135], v[198:201], v[108:111]
	v_mfma_f32_16x16x32_bf16 v[104:107], v[140:143], v[198:201], v[104:107]
	v_mfma_f32_16x16x32_bf16 v[92:95], v[132:135], v[206:209], v[92:95]
	v_mfma_f32_16x16x32_bf16 v[88:91], v[140:143], v[206:209], v[88:91]
	v_mfma_f32_16x16x32_bf16 v[76:79], v[132:135], v[214:217], v[76:79]
	v_mfma_f32_16x16x32_bf16 v[72:75], v[140:143], v[214:217], v[72:75]
	v_mfma_f32_16x16x32_bf16 v[116:119], v[158:161], v[186:189], 0
	v_mfma_f32_16x16x32_bf16 v[112:115], v[178:181], v[186:189], 0
	v_mfma_f32_16x16x32_bf16 v[100:103], v[158:161], v[194:197], 0
	v_mfma_f32_16x16x32_bf16 v[96:99], v[178:181], v[194:197], 0
	v_mfma_f32_16x16x32_bf16 v[84:87], v[158:161], v[202:205], 0
	v_mfma_f32_16x16x32_bf16 v[80:83], v[178:181], v[202:205], 0
	v_mfma_f32_16x16x32_bf16 v[68:71], v[158:161], v[210:213], 0
	v_mfma_f32_16x16x32_bf16 v[64:67], v[178:181], v[210:213], 0
	v_mfma_f32_16x16x32_bf16 v[116:119], v[162:165], v[190:193], v[116:119]
	v_mfma_f32_16x16x32_bf16 v[112:115], v[182:185], v[190:193], v[112:115]
	v_mfma_f32_16x16x32_bf16 v[100:103], v[162:165], v[198:201], v[100:103]
	v_mfma_f32_16x16x32_bf16 v[96:99], v[182:185], v[198:201], v[96:99]
	v_mfma_f32_16x16x32_bf16 v[84:87], v[162:165], v[206:209], v[84:87]
	v_mfma_f32_16x16x32_bf16 v[80:83], v[182:185], v[206:209], v[80:83]
	v_mfma_f32_16x16x32_bf16 v[68:71], v[162:165], v[214:217], v[68:71]
	v_mfma_f32_16x16x32_bf16 v[64:67], v[182:185], v[214:217], v[64:67]
	s_barrier
	s_add_i32 s26, s63, s13
	v_lshl_add_u64 v[218:219], s[8:9], 0, v[146:147]
	s_mov_b32 m0, s26
	ds_read_b128 v[186:189], v171 offset:16384
	ds_read_b128 v[190:193], v171 offset:17408
	ds_read_b128 v[194:197], v171 offset:18432
	ds_read_b128 v[198:201], v171 offset:19456
	ds_read_b128 v[202:205], v171 offset:20480
	ds_read_b128 v[206:209], v171 offset:21504
	ds_read_b128 v[210:213], v171 offset:22528
	ds_read_b128 v[214:217], v171 offset:23552
	global_load_lds_dwordx4 v[218:219], off
	s_add_i32 m0, s26, 0x2000
	s_add_u32 s26, s8, 0x40000
	v_lshl_add_u64 v[220:221], s[8:9], 0, v[150:151]
	s_addc_u32 s27, s9, 0
	s_add_i32 s77, s64, s13
	global_load_lds_dwordx4 v[220:221], off
	s_mov_b32 m0, s77
	v_lshl_add_u64 v[224:225], s[10:11], 0, v[148:149]
	global_load_lds_dwordx4 v146, s[26:27]
	s_add_i32 m0, s77, 0x2000
	s_nop 0
	global_load_lds_dwordx4 v150, s[26:27]
	v_lshl_add_u64 v[222:223], s[10:11], 0, v[144:145]
	s_mov_b32 m0, s28
	s_nop 0
	global_load_lds_dwordx4 v[222:223], off
	s_mov_b32 m0, s29
	s_nop 0
	global_load_lds_dwordx4 v[224:225], off
	s_waitcnt vmcnt(8) lgkmcnt(0)
	s_barrier
	v_mfma_f32_16x16x32_bf16 v[60:63], v[128:131], v[186:189], 0
	v_mfma_f32_16x16x32_bf16 v[56:59], v[136:139], v[186:189], 0
	v_mfma_f32_16x16x32_bf16 v[44:47], v[128:131], v[194:197], 0
	v_mfma_f32_16x16x32_bf16 v[40:43], v[136:139], v[194:197], 0
	v_mfma_f32_16x16x32_bf16 v[28:31], v[128:131], v[202:205], 0
	v_mfma_f32_16x16x32_bf16 v[24:27], v[136:139], v[202:205], 0
	v_mfma_f32_16x16x32_bf16 v[12:15], v[128:131], v[210:213], 0
	v_mfma_f32_16x16x32_bf16 v[8:11], v[136:139], v[210:213], 0
	v_mfma_f32_16x16x32_bf16 v[60:63], v[132:135], v[190:193], v[60:63]
	v_mfma_f32_16x16x32_bf16 v[56:59], v[140:143], v[190:193], v[56:59]
	v_mfma_f32_16x16x32_bf16 v[44:47], v[132:135], v[198:201], v[44:47]
	v_mfma_f32_16x16x32_bf16 v[40:43], v[140:143], v[198:201], v[40:43]
	v_mfma_f32_16x16x32_bf16 v[28:31], v[132:135], v[206:209], v[28:31]
	v_mfma_f32_16x16x32_bf16 v[24:27], v[140:143], v[206:209], v[24:27]
	v_mfma_f32_16x16x32_bf16 v[12:15], v[132:135], v[214:217], v[12:15]
	v_mfma_f32_16x16x32_bf16 v[8:11], v[140:143], v[214:217], v[8:11]
	v_mfma_f32_16x16x32_bf16 v[52:55], v[158:161], v[186:189], 0
	v_mfma_f32_16x16x32_bf16 v[48:51], v[178:181], v[186:189], 0
	v_mfma_f32_16x16x32_bf16 v[36:39], v[158:161], v[194:197], 0
	v_mfma_f32_16x16x32_bf16 v[32:35], v[178:181], v[194:197], 0
	v_mfma_f32_16x16x32_bf16 v[20:23], v[158:161], v[202:205], 0
	v_mfma_f32_16x16x32_bf16 v[16:19], v[178:181], v[202:205], 0
	v_mfma_f32_16x16x32_bf16 v[4:7], v[158:161], v[210:213], 0
	v_mfma_f32_16x16x32_bf16 v[0:3], v[178:181], v[210:213], 0
	v_mfma_f32_16x16x32_bf16 v[52:55], v[162:165], v[190:193], v[52:55]
	v_mfma_f32_16x16x32_bf16 v[48:51], v[182:185], v[190:193], v[48:51]
	v_mfma_f32_16x16x32_bf16 v[36:39], v[162:165], v[198:201], v[36:39]
	v_mfma_f32_16x16x32_bf16 v[32:35], v[182:185], v[198:201], v[32:35]
	v_mfma_f32_16x16x32_bf16 v[20:23], v[162:165], v[206:209], v[20:23]
	v_mfma_f32_16x16x32_bf16 v[16:19], v[182:185], v[206:209], v[16:19]
	v_mfma_f32_16x16x32_bf16 v[4:7], v[162:165], v[214:217], v[4:7]
	v_mfma_f32_16x16x32_bf16 v[0:3], v[182:185], v[214:217], v[0:3]
	s_barrier
	s_add_i32 s26, 0, 0x18000
	s_add_i32 s27, 0, 0x1c000
	v_add_u32_e32 v140, s26, v168
	v_add_u32_e32 v152, s27, v168
	ds_read_b128 v[128:131], v140
	ds_read_b128 v[132:135], v140 offset:1024
	ds_read_b128 v[136:139], v140 offset:2048
	ds_read_b128 v[140:143], v140 offset:3072
	ds_read_b128 v[158:161], v152
	ds_read_b128 v[162:165], v152 offset:1024
	ds_read_b128 v[178:181], v152 offset:2048
	ds_read_b128 v[182:185], v152 offset:3072
	s_add_u32 s10, s10, 0x40000
	s_addc_u32 s11, s11, 0
	s_mov_b32 m0, s56
	ds_read_b128 v[186:189], v171 offset:32768
	ds_read_b128 v[190:193], v171 offset:33792
	ds_read_b128 v[194:197], v171 offset:34816
	ds_read_b128 v[198:201], v171 offset:35840
	ds_read_b128 v[202:205], v171 offset:36864
	ds_read_b128 v[206:209], v171 offset:37888
	ds_read_b128 v[210:213], v171 offset:38912
	ds_read_b128 v[214:217], v171 offset:39936
	global_load_lds_dwordx4 v144, s[10:11]
	s_mov_b32 m0, s57
	s_nop 0
	global_load_lds_dwordx4 v148, s[10:11]
	s_waitcnt vmcnt(8) lgkmcnt(0)
	s_barrier
	v_mfma_f32_16x16x32_bf16 v[124:127], v[128:131], v[186:189], v[124:127]
	v_mfma_f32_16x16x32_bf16 v[120:123], v[136:139], v[186:189], v[120:123]
	v_mfma_f32_16x16x32_bf16 v[108:111], v[128:131], v[194:197], v[108:111]
	v_mfma_f32_16x16x32_bf16 v[104:107], v[136:139], v[194:197], v[104:107]
	v_mfma_f32_16x16x32_bf16 v[92:95], v[128:131], v[202:205], v[92:95]
	v_mfma_f32_16x16x32_bf16 v[88:91], v[136:139], v[202:205], v[88:91]
	v_mfma_f32_16x16x32_bf16 v[76:79], v[128:131], v[210:213], v[76:79]
	v_mfma_f32_16x16x32_bf16 v[72:75], v[136:139], v[210:213], v[72:75]
	v_mfma_f32_16x16x32_bf16 v[124:127], v[132:135], v[190:193], v[124:127]
	v_mfma_f32_16x16x32_bf16 v[120:123], v[140:143], v[190:193], v[120:123]
	v_mfma_f32_16x16x32_bf16 v[108:111], v[132:135], v[198:201], v[108:111]
	v_mfma_f32_16x16x32_bf16 v[104:107], v[140:143], v[198:201], v[104:107]
	v_mfma_f32_16x16x32_bf16 v[92:95], v[132:135], v[206:209], v[92:95]
	v_mfma_f32_16x16x32_bf16 v[88:91], v[140:143], v[206:209], v[88:91]
	v_mfma_f32_16x16x32_bf16 v[76:79], v[132:135], v[214:217], v[76:79]
	v_mfma_f32_16x16x32_bf16 v[72:75], v[140:143], v[214:217], v[72:75]
	v_mfma_f32_16x16x32_bf16 v[116:119], v[158:161], v[186:189], v[116:119]
	v_mfma_f32_16x16x32_bf16 v[112:115], v[178:181], v[186:189], v[112:115]
	v_mfma_f32_16x16x32_bf16 v[100:103], v[158:161], v[194:197], v[100:103]
	v_mfma_f32_16x16x32_bf16 v[96:99], v[178:181], v[194:197], v[96:99]
	v_mfma_f32_16x16x32_bf16 v[84:87], v[158:161], v[202:205], v[84:87]
	v_mfma_f32_16x16x32_bf16 v[80:83], v[178:181], v[202:205], v[80:83]
	v_mfma_f32_16x16x32_bf16 v[68:71], v[158:161], v[210:213], v[68:71]
	v_mfma_f32_16x16x32_bf16 v[64:67], v[178:181], v[210:213], v[64:67]
	v_mfma_f32_16x16x32_bf16 v[116:119], v[162:165], v[190:193], v[116:119]
	v_mfma_f32_16x16x32_bf16 v[112:115], v[182:185], v[190:193], v[112:115]
	v_mfma_f32_16x16x32_bf16 v[100:103], v[162:165], v[198:201], v[100:103]
	v_mfma_f32_16x16x32_bf16 v[96:99], v[182:185], v[198:201], v[96:99]
	v_mfma_f32_16x16x32_bf16 v[84:87], v[162:165], v[206:209], v[84:87]
	v_mfma_f32_16x16x32_bf16 v[80:83], v[182:185], v[206:209], v[80:83]
	v_mfma_f32_16x16x32_bf16 v[68:71], v[162:165], v[214:217], v[68:71]
	v_mfma_f32_16x16x32_bf16 v[64:67], v[182:185], v[214:217], v[64:67]
	s_barrier
	s_add_i32 s10, s26, s13
	v_lshl_add_u64 v[218:219], v[218:219], 0, s[34:35]
	s_mov_b32 m0, s10
	ds_read_b128 v[186:189], v171 offset:49152
	ds_read_b128 v[190:193], v171 offset:50176
	ds_read_b128 v[194:197], v171 offset:51200
	ds_read_b128 v[198:201], v171 offset:52224
	ds_read_b128 v[202:205], v171 offset:53248
	ds_read_b128 v[206:209], v171 offset:54272
	ds_read_b128 v[210:213], v171 offset:55296
	ds_read_b128 v[214:217], v171 offset:56320
	global_load_lds_dwordx4 v[218:219], off
	s_add_i32 m0, s10, 0x2000
	s_add_u32 s8, s8, 0x40080
	v_lshl_add_u64 v[218:219], v[220:221], 0, s[34:35]
	s_addc_u32 s9, s9, 0
	s_add_i32 s10, s27, s13
	global_load_lds_dwordx4 v[218:219], off
	s_mov_b32 m0, s10
	s_nop 0
	global_load_lds_dwordx4 v146, s[8:9]
	s_add_i32 m0, s10, 0x2000
	s_nop 0
	global_load_lds_dwordx4 v150, s[8:9]
	v_lshl_add_u64 v[218:219], v[222:223], 0, s[34:35]
	s_mov_b32 m0, s61
	s_nop 0
	global_load_lds_dwordx4 v[218:219], off
	v_lshl_add_u64 v[218:219], v[224:225], 0, s[34:35]
	s_mov_b32 m0, s62
	s_nop 0
	global_load_lds_dwordx4 v[218:219], off
	s_waitcnt vmcnt(8) lgkmcnt(0)
	s_barrier
	v_mfma_f32_16x16x32_bf16 v[60:63], v[128:131], v[186:189], v[60:63]
	v_mfma_f32_16x16x32_bf16 v[56:59], v[136:139], v[186:189], v[56:59]
	v_mfma_f32_16x16x32_bf16 v[44:47], v[128:131], v[194:197], v[44:47]
	v_mfma_f32_16x16x32_bf16 v[40:43], v[136:139], v[194:197], v[40:43]
	v_mfma_f32_16x16x32_bf16 v[28:31], v[128:131], v[202:205], v[28:31]
	v_mfma_f32_16x16x32_bf16 v[24:27], v[136:139], v[202:205], v[24:27]
	v_mfma_f32_16x16x32_bf16 v[12:15], v[128:131], v[210:213], v[12:15]
	v_mfma_f32_16x16x32_bf16 v[8:11], v[136:139], v[210:213], v[8:11]
	v_mfma_f32_16x16x32_bf16 v[60:63], v[132:135], v[190:193], v[60:63]
	v_mfma_f32_16x16x32_bf16 v[56:59], v[140:143], v[190:193], v[56:59]
	v_mfma_f32_16x16x32_bf16 v[44:47], v[132:135], v[198:201], v[44:47]
	v_mfma_f32_16x16x32_bf16 v[40:43], v[140:143], v[198:201], v[40:43]
	v_mfma_f32_16x16x32_bf16 v[28:31], v[132:135], v[206:209], v[28:31]
	v_mfma_f32_16x16x32_bf16 v[24:27], v[140:143], v[206:209], v[24:27]
	v_mfma_f32_16x16x32_bf16 v[12:15], v[132:135], v[214:217], v[12:15]
	v_mfma_f32_16x16x32_bf16 v[8:11], v[140:143], v[214:217], v[8:11]
	v_mfma_f32_16x16x32_bf16 v[52:55], v[158:161], v[186:189], v[52:55]
	v_mfma_f32_16x16x32_bf16 v[48:51], v[178:181], v[186:189], v[48:51]
	v_mfma_f32_16x16x32_bf16 v[36:39], v[158:161], v[194:197], v[36:39]
	v_mfma_f32_16x16x32_bf16 v[32:35], v[178:181], v[194:197], v[32:35]
	v_mfma_f32_16x16x32_bf16 v[20:23], v[158:161], v[202:205], v[20:23]
	v_mfma_f32_16x16x32_bf16 v[16:19], v[178:181], v[202:205], v[16:19]
	v_mfma_f32_16x16x32_bf16 v[4:7], v[158:161], v[210:213], v[4:7]
	v_mfma_f32_16x16x32_bf16 v[0:3], v[178:181], v[210:213], v[0:3]
	v_mfma_f32_16x16x32_bf16 v[52:55], v[162:165], v[190:193], v[52:55]
	v_mfma_f32_16x16x32_bf16 v[48:51], v[182:185], v[190:193], v[48:51]
	v_mfma_f32_16x16x32_bf16 v[36:39], v[162:165], v[198:201], v[36:39]
	v_mfma_f32_16x16x32_bf16 v[32:35], v[182:185], v[198:201], v[32:35]
	v_mfma_f32_16x16x32_bf16 v[20:23], v[162:165], v[206:209], v[20:23]
	v_mfma_f32_16x16x32_bf16 v[16:19], v[182:185], v[206:209], v[16:19]
	v_mfma_f32_16x16x32_bf16 v[4:7], v[162:165], v[214:217], v[4:7]
	v_mfma_f32_16x16x32_bf16 v[0:3], v[182:185], v[214:217], v[0:3]
	s_barrier
	s_add_i32 s79, s79, 2
	s_add_u32 s55, s55, 0x100
	s_addc_u32 s78, s78, 0
	s_add_u32 s4, s4, 0x100
	s_addc_u32 s5, s5, 0
.LBB0_343:
	ds_read_b128 v[128:131], v169
	ds_read_b128 v[132:135], v169 offset:1024
	ds_read_b128 v[136:139], v169 offset:2048
	ds_read_b128 v[140:143], v169 offset:3072
	ds_read_b128 v[158:161], v170
	ds_read_b128 v[162:165], v170 offset:1024
	ds_read_b128 v[178:181], v170 offset:2048
	ds_read_b128 v[182:185], v170 offset:3072
	s_add_u32 s8, s4, 0xfffc0080
	s_addc_u32 s9, s5, -1
	s_cmp_eq_u32 s79, 12
	s_cselect_b32 s11, s50, s9
	s_cselect_b32 s10, s51, s8
	s_cselect_b32 s9, s53, s78
	s_cselect_b32 s8, s54, s55
	s_add_i32 m0, s28, 0xc000
	ds_read_b128 v[186:189], v171
	ds_read_b128 v[190:193], v171 offset:1024
	ds_read_b128 v[194:197], v171 offset:2048
	ds_read_b128 v[198:201], v171 offset:3072
	ds_read_b128 v[202:205], v171 offset:4096
	ds_read_b128 v[206:209], v171 offset:5120
	ds_read_b128 v[210:213], v171 offset:6144
	ds_read_b128 v[214:217], v171 offset:7168
	global_load_lds_dwordx4 v156, s[4:5]
	s_add_i32 m0, s28, 0xe000
	s_nop 0
	global_load_lds_dwordx4 v154, s[4:5]
	s_waitcnt vmcnt(8) lgkmcnt(0)
	s_barrier
	v_mfma_f32_16x16x32_bf16 v[124:127], v[128:131], v[186:189], v[124:127]
	v_mfma_f32_16x16x32_bf16 v[120:123], v[136:139], v[186:189], v[120:123]
	v_mfma_f32_16x16x32_bf16 v[108:111], v[128:131], v[194:197], v[108:111]
	v_mfma_f32_16x16x32_bf16 v[104:107], v[136:139], v[194:197], v[104:107]
	v_mfma_f32_16x16x32_bf16 v[92:95], v[128:131], v[202:205], v[92:95]
	v_mfma_f32_16x16x32_bf16 v[88:91], v[136:139], v[202:205], v[88:91]
	v_mfma_f32_16x16x32_bf16 v[76:79], v[128:131], v[210:213], v[76:79]
	v_mfma_f32_16x16x32_bf16 v[72:75], v[136:139], v[210:213], v[72:75]
	v_mfma_f32_16x16x32_bf16 v[124:127], v[132:135], v[190:193], v[124:127]
	v_mfma_f32_16x16x32_bf16 v[120:123], v[140:143], v[190:193], v[120:123]
	v_mfma_f32_16x16x32_bf16 v[108:111], v[132:135], v[198:201], v[108:111]
	v_mfma_f32_16x16x32_bf16 v[104:107], v[140:143], v[198:201], v[104:107]
	v_mfma_f32_16x16x32_bf16 v[92:95], v[132:135], v[206:209], v[92:95]
	v_mfma_f32_16x16x32_bf16 v[88:91], v[140:143], v[206:209], v[88:91]
	v_mfma_f32_16x16x32_bf16 v[76:79], v[132:135], v[214:217], v[76:79]
	v_mfma_f32_16x16x32_bf16 v[72:75], v[140:143], v[214:217], v[72:75]
	v_mfma_f32_16x16x32_bf16 v[116:119], v[158:161], v[186:189], v[116:119]
	v_mfma_f32_16x16x32_bf16 v[112:115], v[178:181], v[186:189], v[112:115]
	v_mfma_f32_16x16x32_bf16 v[100:103], v[158:161], v[194:197], v[100:103]
	v_mfma_f32_16x16x32_bf16 v[96:99], v[178:181], v[194:197], v[96:99]
	v_mfma_f32_16x16x32_bf16 v[84:87], v[158:161], v[202:205], v[84:87]
	v_mfma_f32_16x16x32_bf16 v[80:83], v[178:181], v[202:205], v[80:83]
	v_mfma_f32_16x16x32_bf16 v[68:71], v[158:161], v[210:213], v[68:71]
	v_mfma_f32_16x16x32_bf16 v[64:67], v[178:181], v[210:213], v[64:67]
	v_mfma_f32_16x16x32_bf16 v[116:119], v[162:165], v[190:193], v[116:119]
	v_mfma_f32_16x16x32_bf16 v[112:115], v[182:185], v[190:193], v[112:115]
	v_mfma_f32_16x16x32_bf16 v[100:103], v[162:165], v[198:201], v[100:103]
	v_mfma_f32_16x16x32_bf16 v[96:99], v[182:185], v[198:201], v[96:99]
	v_mfma_f32_16x16x32_bf16 v[84:87], v[162:165], v[206:209], v[84:87]
	v_mfma_f32_16x16x32_bf16 v[80:83], v[182:185], v[206:209], v[80:83]
	v_mfma_f32_16x16x32_bf16 v[68:71], v[162:165], v[214:217], v[68:71]
	v_mfma_f32_16x16x32_bf16 v[64:67], v[182:185], v[214:217], v[64:67]
	s_barrier
	s_add_i32 s26, s63, s13
	v_lshl_add_u64 v[218:219], s[8:9], 0, v[146:147]
	s_mov_b32 m0, s26
	ds_read_b128 v[186:189], v171 offset:16384
	ds_read_b128 v[190:193], v171 offset:17408
	ds_read_b128 v[194:197], v171 offset:18432
	ds_read_b128 v[198:201], v171 offset:19456
	ds_read_b128 v[202:205], v171 offset:20480
	ds_read_b128 v[206:209], v171 offset:21504
	ds_read_b128 v[210:213], v171 offset:22528
	ds_read_b128 v[214:217], v171 offset:23552
	global_load_lds_dwordx4 v[218:219], off
	s_add_i32 m0, s26, 0x2000
	s_add_u32 s26, s8, 0x40000
	v_lshl_add_u64 v[220:221], s[8:9], 0, v[150:151]
	s_addc_u32 s27, s9, 0
	s_add_i32 s77, s64, s13
	global_load_lds_dwordx4 v[220:221], off
	s_mov_b32 m0, s77
	v_lshl_add_u64 v[224:225], s[10:11], 0, v[148:149]
	global_load_lds_dwordx4 v146, s[26:27]
	s_add_i32 m0, s77, 0x2000
	s_nop 0
	global_load_lds_dwordx4 v150, s[26:27]
	v_lshl_add_u64 v[222:223], s[10:11], 0, v[144:145]
	s_mov_b32 m0, s28
	s_nop 0
	global_load_lds_dwordx4 v[222:223], off
	s_mov_b32 m0, s29
	s_nop 0
	global_load_lds_dwordx4 v[224:225], off
	s_waitcnt vmcnt(8) lgkmcnt(0)
	s_barrier
	v_mfma_f32_16x16x32_bf16 v[60:63], v[128:131], v[186:189], v[60:63]
	v_mfma_f32_16x16x32_bf16 v[56:59], v[136:139], v[186:189], v[56:59]
	v_mfma_f32_16x16x32_bf16 v[44:47], v[128:131], v[194:197], v[44:47]
	v_mfma_f32_16x16x32_bf16 v[40:43], v[136:139], v[194:197], v[40:43]
	v_mfma_f32_16x16x32_bf16 v[28:31], v[128:131], v[202:205], v[28:31]
	v_mfma_f32_16x16x32_bf16 v[24:27], v[136:139], v[202:205], v[24:27]
	v_mfma_f32_16x16x32_bf16 v[12:15], v[128:131], v[210:213], v[12:15]
	v_mfma_f32_16x16x32_bf16 v[8:11], v[136:139], v[210:213], v[8:11]
	v_mfma_f32_16x16x32_bf16 v[60:63], v[132:135], v[190:193], v[60:63]
	v_mfma_f32_16x16x32_bf16 v[56:59], v[140:143], v[190:193], v[56:59]
	v_mfma_f32_16x16x32_bf16 v[44:47], v[132:135], v[198:201], v[44:47]
	v_mfma_f32_16x16x32_bf16 v[40:43], v[140:143], v[198:201], v[40:43]
	v_mfma_f32_16x16x32_bf16 v[28:31], v[132:135], v[206:209], v[28:31]
	v_mfma_f32_16x16x32_bf16 v[24:27], v[140:143], v[206:209], v[24:27]
	v_mfma_f32_16x16x32_bf16 v[12:15], v[132:135], v[214:217], v[12:15]
	v_mfma_f32_16x16x32_bf16 v[8:11], v[140:143], v[214:217], v[8:11]
	v_mfma_f32_16x16x32_bf16 v[52:55], v[158:161], v[186:189], v[52:55]
	v_mfma_f32_16x16x32_bf16 v[48:51], v[178:181], v[186:189], v[48:51]
	v_mfma_f32_16x16x32_bf16 v[36:39], v[158:161], v[194:197], v[36:39]
	v_mfma_f32_16x16x32_bf16 v[32:35], v[178:181], v[194:197], v[32:35]
	v_mfma_f32_16x16x32_bf16 v[20:23], v[158:161], v[202:205], v[20:23]
	v_mfma_f32_16x16x32_bf16 v[16:19], v[178:181], v[202:205], v[16:19]
	v_mfma_f32_16x16x32_bf16 v[4:7], v[158:161], v[210:213], v[4:7]
	v_mfma_f32_16x16x32_bf16 v[0:3], v[178:181], v[210:213], v[0:3]
	v_mfma_f32_16x16x32_bf16 v[52:55], v[162:165], v[190:193], v[52:55]
	v_mfma_f32_16x16x32_bf16 v[48:51], v[182:185], v[190:193], v[48:51]
	v_mfma_f32_16x16x32_bf16 v[36:39], v[162:165], v[198:201], v[36:39]
	v_mfma_f32_16x16x32_bf16 v[32:35], v[182:185], v[198:201], v[32:35]
	v_mfma_f32_16x16x32_bf16 v[20:23], v[162:165], v[206:209], v[20:23]
	v_mfma_f32_16x16x32_bf16 v[16:19], v[182:185], v[206:209], v[16:19]
	v_mfma_f32_16x16x32_bf16 v[4:7], v[162:165], v[214:217], v[4:7]
	v_mfma_f32_16x16x32_bf16 v[0:3], v[182:185], v[214:217], v[0:3]
	s_barrier
	s_add_i32 s26, 0, 0x18000
	s_add_i32 s27, 0, 0x1c000
	v_add_u32_e32 v140, s26, v168
	v_add_u32_e32 v152, s27, v168
	ds_read_b128 v[128:131], v140
	ds_read_b128 v[132:135], v140 offset:1024
	ds_read_b128 v[136:139], v140 offset:2048
	ds_read_b128 v[140:143], v140 offset:3072
	ds_read_b128 v[158:161], v152
	ds_read_b128 v[162:165], v152 offset:1024
	ds_read_b128 v[178:181], v152 offset:2048
	ds_read_b128 v[182:185], v152 offset:3072
	s_add_u32 s10, s10, 0x40000
	s_addc_u32 s11, s11, 0
	s_mov_b32 m0, s56
	ds_read_b128 v[186:189], v171 offset:32768
	ds_read_b128 v[190:193], v171 offset:33792
	ds_read_b128 v[194:197], v171 offset:34816
	ds_read_b128 v[198:201], v171 offset:35840
	ds_read_b128 v[202:205], v171 offset:36864
	ds_read_b128 v[206:209], v171 offset:37888
	ds_read_b128 v[210:213], v171 offset:38912
	ds_read_b128 v[214:217], v171 offset:39936
	global_load_lds_dwordx4 v144, s[10:11]
	v_lshl_add_u64 v[226:227], s[10:11], 0, v[148:149]
	s_mov_b32 m0, s57
	s_nop 0
	global_load_lds_dwordx4 v[226:227], off
	s_waitcnt vmcnt(8) lgkmcnt(0)
	s_barrier
	v_mfma_f32_16x16x32_bf16 v[124:127], v[128:131], v[186:189], v[124:127]
	v_mfma_f32_16x16x32_bf16 v[120:123], v[136:139], v[186:189], v[120:123]
	v_mfma_f32_16x16x32_bf16 v[108:111], v[128:131], v[194:197], v[108:111]
	v_mfma_f32_16x16x32_bf16 v[104:107], v[136:139], v[194:197], v[104:107]
	v_mfma_f32_16x16x32_bf16 v[92:95], v[128:131], v[202:205], v[92:95]
	v_mfma_f32_16x16x32_bf16 v[88:91], v[136:139], v[202:205], v[88:91]
	v_mfma_f32_16x16x32_bf16 v[76:79], v[128:131], v[210:213], v[76:79]
	v_mfma_f32_16x16x32_bf16 v[72:75], v[136:139], v[210:213], v[72:75]
	v_mfma_f32_16x16x32_bf16 v[124:127], v[132:135], v[190:193], v[124:127]
	v_mfma_f32_16x16x32_bf16 v[120:123], v[140:143], v[190:193], v[120:123]
	v_mfma_f32_16x16x32_bf16 v[108:111], v[132:135], v[198:201], v[108:111]
	v_mfma_f32_16x16x32_bf16 v[104:107], v[140:143], v[198:201], v[104:107]
	v_mfma_f32_16x16x32_bf16 v[92:95], v[132:135], v[206:209], v[92:95]
	v_mfma_f32_16x16x32_bf16 v[88:91], v[140:143], v[206:209], v[88:91]
	v_mfma_f32_16x16x32_bf16 v[76:79], v[132:135], v[214:217], v[76:79]
	v_mfma_f32_16x16x32_bf16 v[72:75], v[140:143], v[214:217], v[72:75]
	v_mfma_f32_16x16x32_bf16 v[116:119], v[158:161], v[186:189], v[116:119]
	v_mfma_f32_16x16x32_bf16 v[112:115], v[178:181], v[186:189], v[112:115]
	v_mfma_f32_16x16x32_bf16 v[100:103], v[158:161], v[194:197], v[100:103]
	v_mfma_f32_16x16x32_bf16 v[96:99], v[178:181], v[194:197], v[96:99]
	v_mfma_f32_16x16x32_bf16 v[84:87], v[158:161], v[202:205], v[84:87]
	v_mfma_f32_16x16x32_bf16 v[80:83], v[178:181], v[202:205], v[80:83]
	v_mfma_f32_16x16x32_bf16 v[68:71], v[158:161], v[210:213], v[68:71]
	v_mfma_f32_16x16x32_bf16 v[64:67], v[178:181], v[210:213], v[64:67]
	v_mfma_f32_16x16x32_bf16 v[116:119], v[162:165], v[190:193], v[116:119]
	v_mfma_f32_16x16x32_bf16 v[112:115], v[182:185], v[190:193], v[112:115]
	v_mfma_f32_16x16x32_bf16 v[100:103], v[162:165], v[198:201], v[100:103]
	v_mfma_f32_16x16x32_bf16 v[96:99], v[182:185], v[198:201], v[96:99]
	v_mfma_f32_16x16x32_bf16 v[84:87], v[162:165], v[206:209], v[84:87]
	v_mfma_f32_16x16x32_bf16 v[80:83], v[182:185], v[206:209], v[80:83]
	v_mfma_f32_16x16x32_bf16 v[68:71], v[162:165], v[214:217], v[68:71]
	v_mfma_f32_16x16x32_bf16 v[64:67], v[182:185], v[214:217], v[64:67]
	s_barrier
	s_add_i32 s10, s26, s13
	v_lshl_add_u64 v[218:219], v[218:219], 0, s[34:35]
	s_mov_b32 m0, s10
	ds_read_b128 v[186:189], v171 offset:49152
	ds_read_b128 v[190:193], v171 offset:50176
	ds_read_b128 v[194:197], v171 offset:51200
	ds_read_b128 v[198:201], v171 offset:52224
	ds_read_b128 v[202:205], v171 offset:53248
	ds_read_b128 v[206:209], v171 offset:54272
	ds_read_b128 v[210:213], v171 offset:55296
	ds_read_b128 v[214:217], v171 offset:56320
	global_load_lds_dwordx4 v[218:219], off
	s_add_i32 m0, s10, 0x2000
	s_add_u32 s8, s8, 0x40080
	v_lshl_add_u64 v[218:219], v[220:221], 0, s[34:35]
	s_addc_u32 s9, s9, 0
	s_add_i32 s10, s27, s13
	global_load_lds_dwordx4 v[218:219], off
	s_mov_b32 m0, s10
	s_nop 0
	global_load_lds_dwordx4 v146, s[8:9]
	s_add_i32 m0, s10, 0x2000
	s_nop 0
	global_load_lds_dwordx4 v150, s[8:9]
	v_lshl_add_u64 v[218:219], v[222:223], 0, s[34:35]
	s_mov_b32 m0, s61
	s_nop 0
	global_load_lds_dwordx4 v[218:219], off
	v_lshl_add_u64 v[218:219], v[224:225], 0, s[34:35]
	s_mov_b32 m0, s62
	s_nop 0
	global_load_lds_dwordx4 v[218:219], off
	s_waitcnt vmcnt(8) lgkmcnt(0)
	s_barrier
	v_mfma_f32_16x16x32_bf16 v[60:63], v[128:131], v[186:189], v[60:63]
	v_mfma_f32_16x16x32_bf16 v[56:59], v[136:139], v[186:189], v[56:59]
	v_mfma_f32_16x16x32_bf16 v[44:47], v[128:131], v[194:197], v[44:47]
	v_mfma_f32_16x16x32_bf16 v[40:43], v[136:139], v[194:197], v[40:43]
	v_mfma_f32_16x16x32_bf16 v[28:31], v[128:131], v[202:205], v[28:31]
	v_mfma_f32_16x16x32_bf16 v[24:27], v[136:139], v[202:205], v[24:27]
	v_mfma_f32_16x16x32_bf16 v[12:15], v[128:131], v[210:213], v[12:15]
	v_mfma_f32_16x16x32_bf16 v[8:11], v[136:139], v[210:213], v[8:11]
	v_mfma_f32_16x16x32_bf16 v[60:63], v[132:135], v[190:193], v[60:63]
	v_mfma_f32_16x16x32_bf16 v[56:59], v[140:143], v[190:193], v[56:59]
	v_mfma_f32_16x16x32_bf16 v[44:47], v[132:135], v[198:201], v[44:47]
	v_mfma_f32_16x16x32_bf16 v[40:43], v[140:143], v[198:201], v[40:43]
	v_mfma_f32_16x16x32_bf16 v[28:31], v[132:135], v[206:209], v[28:31]
	v_mfma_f32_16x16x32_bf16 v[24:27], v[140:143], v[206:209], v[24:27]
	v_mfma_f32_16x16x32_bf16 v[12:15], v[132:135], v[214:217], v[12:15]
	v_mfma_f32_16x16x32_bf16 v[8:11], v[140:143], v[214:217], v[8:11]
	v_mfma_f32_16x16x32_bf16 v[52:55], v[158:161], v[186:189], v[52:55]
	v_mfma_f32_16x16x32_bf16 v[48:51], v[178:181], v[186:189], v[48:51]
	v_mfma_f32_16x16x32_bf16 v[36:39], v[158:161], v[194:197], v[36:39]
	v_mfma_f32_16x16x32_bf16 v[32:35], v[178:181], v[194:197], v[32:35]
	v_mfma_f32_16x16x32_bf16 v[20:23], v[158:161], v[202:205], v[20:23]
	v_mfma_f32_16x16x32_bf16 v[16:19], v[178:181], v[202:205], v[16:19]
	v_mfma_f32_16x16x32_bf16 v[4:7], v[158:161], v[210:213], v[4:7]
	v_mfma_f32_16x16x32_bf16 v[0:3], v[178:181], v[210:213], v[0:3]
	v_mfma_f32_16x16x32_bf16 v[52:55], v[162:165], v[190:193], v[52:55]
	v_mfma_f32_16x16x32_bf16 v[48:51], v[182:185], v[190:193], v[48:51]
	v_mfma_f32_16x16x32_bf16 v[36:39], v[162:165], v[198:201], v[36:39]
	v_mfma_f32_16x16x32_bf16 v[32:35], v[182:185], v[198:201], v[32:35]
	v_mfma_f32_16x16x32_bf16 v[20:23], v[162:165], v[206:209], v[20:23]
	v_mfma_f32_16x16x32_bf16 v[16:19], v[182:185], v[206:209], v[16:19]
	v_mfma_f32_16x16x32_bf16 v[4:7], v[162:165], v[214:217], v[4:7]
	v_mfma_f32_16x16x32_bf16 v[0:3], v[182:185], v[214:217], v[0:3]
	s_barrier
	s_add_i32 s79, s79, 2
	s_add_u32 s55, s55, 0x100
	s_addc_u32 s78, s78, 0
	s_add_u32 s4, s4, 0x100
	s_addc_u32 s5, s5, 0
	s_cmp_gt_u32 s79, 13
	s_cbranch_scc0 .LBB0_343
	s_and_b64 vcc, exec, s[18:19]
	s_cbranch_vccz .LBB0_346
	s_barrier

.LBB0_646:
	s_cmpk_gt_i32 s58, 0x47
	s_cselect_b64 s[52:53], -1, 0
	s_mov_b64 s[4:5], s[0:1]
	s_and_b64 vcc, exec, s[52:53]
	s_cbranch_vccnz .LBB0_642
	s_mov_b64 s[4:5], s[100:101]
	s_lshl_b32 s6, s31, 2
	s_waitcnt lgkmcnt(0)
	s_add_u32 s4, s4, s6
	s_addc_u32 s5, s5, 0
	s_add_u32 s54, s4, 0x10000
	s_addc_u32 s55, s5, 0
	s_cmp_gt_i32 s58, 7
	s_mov_b64 s[4:5], -1
	s_cbranch_scc0 .LBB0_661
	s_mov_b64 s[8:9], s[0:1]
	s_mov_b64 s[4:5], s[100:101]
	s_add_i32 s10, s58, -8
	v_mov_b32_e32 v146, v244
	s_load_dwordx2 s[8:9], s[8:9], 0x58
	s_waitcnt lgkmcnt(0)
	s_add_u32 s6, s4, 0x5800000
	s_addc_u32 s7, s5, 0
	s_lshl_b32 s11, s10, 7
	s_and_b32 s11, s11, 0x780
	v_ashrrev_i32_e32 v24, 3, v146
	v_lshrrev_b32_e32 v19, 4, v146
	s_or_b32 s59, s11, s90
	v_add_u32_e32 v16, s65, v24
	v_xor_b32_e32 v19, v19, v146
	s_add_u32 s11, s4, s95
	v_add_u32_e32 v18, 8, v16
	v_lshlrev_b32_e32 v19, 3, v19
	s_addc_u32 s12, s5, 0
	s_lshl_b32 s10, s10, 3
	v_and_b32_e32 v26, 56, v19
	v_ashrrev_i32_e32 v19, 31, v18
	s_and_b32 s60, s10, 0x7fffff80
	v_lshlrev_b64 v[20:21], 10, v[18:19]
	v_lshrrev_b32_e32 v18, 1, v18
	s_lshl_b32 s34, s60, 1
	v_xor_b32_e32 v18, v18, v146
	s_add_u32 s16, s11, s34
	v_lshlrev_b32_e32 v18, 3, v18
	s_addc_u32 s17, s12, 0
	v_and_b32_e32 v30, 56, v18
	v_add_u32_e32 v18, s64, v24
	s_add_u32 s12, s16, 0x7800000
	v_ashrrev_i32_e32 v17, 31, v16
	v_add_u32_e32 v31, 8, v18
	s_addc_u32 s13, s17, 0
	s_add_i32 s10, s51, s60
	v_lshlrev_b64 v[16:17], 10, v[16:17]
	v_lshrrev_b32_e32 v27, 1, v31
	v_or_b32_e32 v29, s66, v26
	s_mulk_i32 s10, 0x900
	s_mov_b32 s11, s35
	v_xor_b32_e32 v27, v27, v146
	v_lshl_add_u32 v156, v29, 1, v16
	v_or_b32_e32 v29, s66, v30
	v_and_b32_e32 v152, 31, v146
	s_lshl_b64 s[10:11], s[10:11], 1
	v_lshl_add_u64 v[22:23], s[12:13], 0, v[20:21]
	v_lshl_add_u32 v154, v29, 1, v20
	v_lshlrev_b32_e32 v20, 4, v27
	s_add_u32 s14, s4, s10
	v_mul_lo_u32 v21, v18, s30
	v_lshlrev_b32_e32 v144, 1, v26
	v_and_b32_e32 v26, 0x70, v20
	v_or_b32_e32 v20, s59, v152
	s_addc_u32 s15, s5, s11
	v_or_b32_e32 v150, v144, v21
	v_lshlrev_b32_e32 v20, 11, v20
	v_mov_b32_e32 v21, v145
	v_ashrrev_i32_e32 v153, 5, v146
	s_add_u32 s10, s14, 0x8a00000
	v_mul_lo_u32 v28, v31, s30
	v_lshl_add_u64 v[20:21], s[6:7], 0, v[20:21]
	s_addc_u32 s11, s15, 0
	v_or_b32_e32 v148, v26, v28
	v_lshl_add_u64 v[20:21], v[20:21], 0, s[34:35]
	s_lshl_b32 s34, s66, 1
	v_lshlrev_b32_e32 v28, 3, v153
	v_lshl_add_u64 v[20:21], v[20:21], 0, s[34:35]
	v_ashrrev_i32_e32 v29, 31, v28
	v_lshl_add_u64 v[28:29], v[28:29], 1, v[20:21]
	global_load_dwordx4 v[124:127], v[28:29], off
	global_load_dwordx4 v[120:123], v[28:29], off offset:32
	global_load_dwordx4 v[116:119], v[28:29], off offset:64
	global_load_dwordx4 v[112:115], v[28:29], off offset:96
	v_lshl_add_u64 v[16:17], s[12:13], 0, v[16:17]
	v_lshl_add_u64 v[16:17], v[16:17], 0, s[34:35]
	v_mov_b64_e32 v[24:25], s[10:11]
	v_lshl_add_u64 v[20:21], v[16:17], 0, v[144:145]
	v_lshl_add_u64 v[16:17], v[22:23], 0, s[34:35]
	v_lshlrev_b32_e32 v22, 1, v30
	v_mov_b32_e32 v23, v145
	v_mad_i64_i32 v[18:19], s[18:19], v18, s30, v[24:25]
	v_mov_b32_e32 v27, v145
	v_lshl_add_u64 v[22:23], v[16:17], 0, v[22:23]
	v_mad_i64_i32 v[16:17], s[18:19], v31, s30, v[24:25]
	s_mov_b32 s61, 1
	v_lshl_add_u64 v[18:19], v[18:19], 0, v[144:145]
	v_lshl_add_u64 v[16:17], v[16:17], 0, v[26:27]
	v_lshlrev_b32_e32 v25, 1, v146
	v_lshrrev_b32_e32 v56, 1, v146
	s_mov_b32 m0, s67
	s_nop 0
	global_load_lds_dwordx4 v[20:21], off
	v_and_b32_e32 v24, 19, v146
	v_and_b32_e32 v25, 8, v25
	v_and_b32_e32 v26, 4, v56
	s_add_i32 s18, s67, 0x400
	s_mov_b32 m0, s18
	s_nop 0
	global_load_lds_dwordx4 v[22:23], off
	v_or3_b32 v24, v25, v24, v26
	s_mov_b32 m0, s70
	s_nop 0
	global_load_lds_dwordx4 v[18:19], off
	v_lshrrev_b32_e32 v58, 1, v24
	s_add_i32 s18, s67, 0x4400
	s_mov_b32 m0, s18
	s_nop 0
	global_load_lds_dwordx4 v[16:17], off
	v_lshl_or_b32 v57, v24, 7, s68
	v_bitop3_b32 v24, v58, v153, 7 bitop3:0x6c
	v_lshl_add_u32 v144, v24, 4, v57
	s_waitcnt vmcnt(0) lgkmcnt(0)
	s_barrier
	s_waitcnt vmcnt(3)
	s_waitcnt vmcnt(2)
	s_waitcnt vmcnt(1)
	s_waitcnt vmcnt(0)
	v_lshl_add_u64 v[24:25], v[20:21], 0, s[36:37]
	s_mov_b32 m0, s71
	s_nop 0
	global_load_lds_dwordx4 v[24:25], off
	v_lshl_add_u64 v[24:25], v[22:23], 0, s[36:37]
	s_mov_b32 m0, s72
	s_nop 0
	global_load_lds_dwordx4 v[24:25], off
	v_lshl_add_u64 v[24:25], v[18:19], 0, s[38:39]
	s_mov_b32 m0, s73
	s_nop 0
	global_load_lds_dwordx4 v[24:25], off
	v_lshl_add_u64 v[24:25], v[16:17], 0, s[38:39]
	s_mov_b32 m0, s78
	s_nop 0
	global_load_lds_dwordx4 v[24:25], off
	v_lshl_add_u64 v[20:21], v[20:21], 0, s[40:41]
	s_add_i32 s18, s67, 0x10000
	s_mov_b32 m0, s18
	s_nop 0
	global_load_lds_dwordx4 v[20:21], off
	v_lshl_add_u64 v[20:21], v[22:23], 0, s[40:41]
	s_add_i32 s18, s67, 0x10400
	s_mov_b32 m0, s18
	s_nop 0
	global_load_lds_dwordx4 v[20:21], off
	v_lshl_add_u64 v[18:19], v[18:19], 0, s[42:43]
	s_add_i32 s18, s67, 0x14000
	s_mov_b32 m0, s18
	s_nop 0
	global_load_lds_dwordx4 v[18:19], off
	v_lshl_add_u64 v[16:17], v[16:17], 0, s[42:43]
	s_add_i32 s18, s67, 0x14400
	s_mov_b32 m0, s18
	s_nop 0
	global_load_lds_dwordx4 v[16:17], off
	v_add_u32_e32 v16, 0, v144
	ds_read_b128 v[32:35], v16
	ds_read_b128 v[48:51], v16 offset:4096
	s_waitcnt lgkmcnt(1)
	v_mfma_f32_32x32x16_bf16 v[16:31], v[32:35], v[124:127], v[0:15]
	v_add_u32_e32 v59, 2, v153
	v_bitop3_b32 v32, v58, v59, 7 bitop3:0x6c
	v_lshl_add_u32 v157, v32, 4, v57
	v_add_u32_e32 v52, 0, v157
	v_add_u32_e32 v60, 4, v153
	v_add_u32_e32 v61, 6, v153
	s_add_u32 s14, s14, 0x8a00180
	s_waitcnt lgkmcnt(0)
	v_mfma_f32_32x32x16_bf16 v[32:47], v[48:51], v[124:127], v[0:15]
	ds_read_b128 v[48:51], v52
	ds_read_b128 v[52:55], v52 offset:4096
	s_addc_u32 s15, s15, 0
	v_lshlrev_b32_e32 v166, 7, v152
	s_add_u32 s16, s16, 0x7830000
	v_mov_b32_e32 v158, 0
	s_addc_u32 s17, s17, 0
	s_movk_i32 s96, 0x100
	s_waitcnt lgkmcnt(1)
	v_mfma_f32_32x32x16_bf16 v[16:31], v[48:51], v[120:123], v[16:31]
	v_bitop3_b32 v48, v58, v60, 7 bitop3:0x6c
	v_lshl_add_u32 v159, v48, 4, v57
	s_mov_b32 s97, 0x20000
	v_mov_b32_e32 v62, v158
	v_mov_b32_e32 v63, v158
	v_mov_b32_e32 v64, 0
	v_mov_b32_e32 v65, v158
	s_waitcnt lgkmcnt(0)
	v_mfma_f32_32x32x16_bf16 v[32:47], v[52:55], v[120:123], v[32:47]
	v_add_u32_e32 v52, 0, v159
	ds_read_b128 v[48:51], v52
	ds_read_b128 v[52:55], v52 offset:4096
	v_mov_b32_e32 v66, v158
	v_mov_b32_e32 v67, v158
	v_mov_b32_e32 v68, v158
	v_mov_b32_e32 v69, v158
	v_mov_b32_e32 v70, v158
	s_waitcnt lgkmcnt(1)
	v_mfma_f32_32x32x16_bf16 v[16:31], v[48:51], v[116:119], v[16:31]
	v_bitop3_b32 v48, v58, v61, 7 bitop3:0x6c
	v_lshl_add_u32 v160, v48, 4, v57
	v_bitop3_b32 v57, v56, v153, 7 bitop3:0x6c
	v_lshlrev_b32_e32 v162, 4, v57
	v_add_u32_e32 v167, v162, v166
	v_mov_b32_e32 v57, v158
	v_mov_b32_e32 v58, v158
	s_waitcnt lgkmcnt(0)
	v_mfma_f32_32x32x16_bf16 v[32:47], v[52:55], v[116:119], v[32:47]
	v_add_u32_e32 v52, 0, v160
	ds_read_b128 v[48:51], v52
	ds_read_b128 v[52:55], v52 offset:4096
	v_mov_b32_e32 v71, v158
	v_mov_b32_e32 v72, v158
	v_mov_b32_e32 v73, v158
	v_mov_b32_e32 v74, v158
	s_waitcnt lgkmcnt(1)
	v_mfma_f32_32x32x16_bf16 v[16:31], v[48:51], v[112:115], v[16:31]
	v_bitop3_b32 v48, v59, v56, 7 bitop3:0x78
	v_lshlrev_b32_e32 v163, 4, v48
	v_bitop3_b32 v48, v60, v56, 7 bitop3:0x78
	v_lshlrev_b32_e32 v164, 4, v48
	v_bitop3_b32 v48, v61, v56, 7 bitop3:0x78
	v_lshlrev_b32_e32 v165, 4, v48
	v_add_u32_e32 v168, v163, v166
	s_waitcnt lgkmcnt(0)
	v_mfma_f32_32x32x16_bf16 v[32:47], v[52:55], v[112:115], v[32:47]
	s_nop 2
	v_exp_f32_e32 v194, v16
	v_exp_f32_e32 v195, v17
	v_exp_f32_e32 v196, v18
	v_exp_f32_e32 v197, v19
	v_exp_f32_e32 v198, v20
	v_exp_f32_e32 v200, v21
	v_exp_f32_e32 v199, v22
	s_nop 1
	v_exp_f32_e32 v173, v32
	v_exp_f32_e32 v174, v33
	v_exp_f32_e32 v175, v34
	v_exp_f32_e32 v176, v35
	v_exp_f32_e32 v191, v36
	v_exp_f32_e32 v188, v37
	v_exp_f32_e32 v171, v38
	v_exp_f32_e32 v201, v23
	v_exp_f32_e32 v172, v39
	v_exp_f32_e32 v180, v24
	v_exp_f32_e32 v185, v40
	v_exp_f32_e32 v181, v25
	v_exp_f32_e32 v186, v41
	v_exp_f32_e32 v182, v26
	v_exp_f32_e32 v187, v42
	v_exp_f32_e32 v183, v27
	v_exp_f32_e32 v184, v43
	v_exp_f32_e32 v193, v28
	v_exp_f32_e32 v177, v44
	v_exp_f32_e32 v189, v29
	v_exp_f32_e32 v178, v45
	v_exp_f32_e32 v190, v30
	v_exp_f32_e32 v179, v46
	v_exp_f32_e32 v192, v31
	v_exp_f32_e32 v161, v47
	v_add_u32_e32 v169, v164, v166
	v_add_u32_e32 v170, v165, v166
	v_mov_b32_e32 v16, 0
	v_mov_b32_e32 v17, v158
	v_mov_b32_e32 v18, v158
	v_mov_b32_e32 v19, v158
	v_mov_b32_e32 v20, v158
	v_mov_b32_e32 v21, v158
	v_mov_b32_e32 v22, v158
	v_mov_b32_e32 v23, v158
	v_mov_b32_e32 v24, v158
	v_mov_b32_e32 v25, v158
	v_mov_b32_e32 v26, v158
	v_mov_b32_e32 v27, v158
	v_mov_b32_e32 v28, v158
	v_mov_b32_e32 v29, v158
	v_mov_b32_e32 v30, v158
	v_mov_b32_e32 v31, v158
	v_mov_b32_e32 v32, 0
	v_mov_b32_e32 v33, v158
	v_mov_b32_e32 v34, v158
	v_mov_b32_e32 v35, v158
	v_mov_b32_e32 v36, v158
	v_mov_b32_e32 v37, v158
	v_mov_b32_e32 v38, v158
	v_mov_b32_e32 v39, v158
	v_mov_b32_e32 v40, v158
	v_mov_b32_e32 v41, v158
	v_mov_b32_e32 v42, v158
	v_mov_b32_e32 v43, v158
	v_mov_b32_e32 v44, v158
	v_mov_b32_e32 v45, v158
	v_mov_b32_e32 v46, v158
	v_mov_b32_e32 v47, v158
	v_mov_b32_e32 v48, 0
	v_mov_b32_e32 v49, v158
	v_mov_b32_e32 v50, v158
	v_mov_b32_e32 v51, v158
	v_mov_b32_e32 v52, v158
	v_mov_b32_e32 v53, v158
	v_mov_b32_e32 v54, v158
	v_mov_b32_e32 v55, v158
	v_mov_b32_e32 v56, v158
	v_mov_b32_e32 v59, v158
	v_mov_b32_e32 v60, v158
	v_mov_b32_e32 v61, v158
	v_mov_b32_e32 v75, v158
	v_mov_b32_e32 v76, v158
	v_mov_b32_e32 v77, v158
	v_mov_b32_e32 v78, v158
	v_mov_b32_e32 v79, v158
.LBB0_649:
	s_add_i32 s18, s97, 0xfffe8000
	s_and_b32 s18, s18, 0x18000
	s_add_i32 vcc_hi, s18, 0
	v_add_u32_e32 v132, vcc_hi, v144
	v_add_u32_e32 v136, vcc_hi, v159
	v_add_u32_e32 v133, vcc_hi, v157
	v_add_u32_e32 v137, vcc_hi, v160
	s_waitcnt vmcnt(4) lgkmcnt(0)
	s_barrier
	ds_read_b128 v[96:99], v132
	ds_read_b128 v[100:103], v133
	ds_read_b128 v[104:107], v136
	ds_read_b128 v[108:111], v137
	s_and_b32 s26, s97, 0x18000
	s_add_i32 vcc_lo, s61, 2
	s_add_i32 s18, s26, 0
	ds_read_b128 v[202:205], v132 offset:4096
	ds_read_b128 v[206:209], v133 offset:4096
	s_waitcnt lgkmcnt(5)
	v_mfma_f32_32x32x16_bf16 v[80:95], v[96:99], v[124:127], v[0:15]
	v_cvt_pk_bf16_f32 v128, v194, v195
	v_cvt_pk_bf16_f32 v129, v196, v197
	v_cvt_pk_bf16_f32 v130, v198, v200
	v_cvt_pk_bf16_f32 v131, v199, v201
	ds_read_b128 v[210:213], v136 offset:4096
	ds_read_b128 v[214:217], v137 offset:4096
	s_waitcnt lgkmcnt(6)
	v_mfma_f32_32x32x16_bf16 v[80:95], v[100:103], v[120:123], v[80:95]
	v_cvt_pk_bf16_f32 v132, v180, v181
	v_cvt_pk_bf16_f32 v133, v182, v183
	v_cvt_pk_bf16_f32 v134, v193, v189
	v_cvt_pk_bf16_f32 v135, v190, v192
	v_add_u32_e32 v234, s18, v167
	v_add_u32_e32 v235, s18, v168
	ds_read_b128 v[218:221], v234 offset:16384
	ds_read_b128 v[222:225], v235 offset:16384
	s_waitcnt lgkmcnt(7)
	v_mfma_f32_32x32x16_bf16 v[80:95], v[104:107], v[116:119], v[80:95]
	v_cvt_pk_bf16_f32 v136, v173, v174
	v_cvt_pk_bf16_f32 v137, v175, v176
	v_cvt_pk_bf16_f32 v138, v191, v188
	v_cvt_pk_bf16_f32 v139, v171, v172
	v_add_u32_e32 v236, s18, v169
	v_add_u32_e32 v237, s18, v170
	ds_read_b128 v[226:229], v236 offset:16384
	ds_read_b128 v[230:233], v237 offset:16384
	s_waitcnt lgkmcnt(8)
	v_mfma_f32_32x32x16_bf16 v[80:95], v[108:111], v[112:115], v[80:95]
	v_cvt_pk_bf16_f32 v140, v185, v186
	v_cvt_pk_bf16_f32 v141, v187, v184
	v_cvt_pk_bf16_f32 v142, v177, v178
	v_cvt_pk_bf16_f32 v143, v179, v161
	v_add_f32_e32 v96, 0, v194
	v_add_f32_e32 v96, v195, v96
	v_add_f32_e32 v96, v196, v96
	v_add_f32_e32 v96, v197, v96
	v_add_f32_e32 v96, v198, v96
	v_add_f32_e32 v194, v200, v96
	v_add_f32_e32 v194, v199, v194
	v_add_f32_e32 v194, v201, v194
	s_waitcnt lgkmcnt(7)
	v_mfma_f32_32x32x16_bf16 v[96:111], v[202:205], v[124:127], v[0:15]
	v_exp_f32_e32 v195, v80
	v_exp_f32_e32 v196, v81
	v_exp_f32_e32 v197, v82
	v_exp_f32_e32 v198, v83
	s_waitcnt lgkmcnt(6)
	v_mfma_f32_32x32x16_bf16 v[96:111], v[206:209], v[120:123], v[96:111]
	v_exp_f32_e32 v199, v84
	v_exp_f32_e32 v200, v85
	v_exp_f32_e32 v201, v86
	s_waitcnt lgkmcnt(5)
	v_mfma_f32_32x32x16_bf16 v[96:111], v[210:213], v[116:119], v[96:111]
	v_exp_f32_e32 v238, v87
	s_waitcnt lgkmcnt(4)
	v_mfma_f32_32x32x16_bf16 v[96:111], v[214:217], v[112:115], v[96:111]
	v_exp_f32_e32 v214, v88
	v_exp_f32_e32 v215, v89
	v_exp_f32_e32 v216, v90
	v_exp_f32_e32 v217, v91
	s_waitcnt lgkmcnt(3)
	v_mfma_f32_32x32x16_bf16 v[64:79], v[128:131], v[218:221], v[64:79]
	ds_read_b128 v[80:83], v234 offset:20480
	v_exp_f32_e32 v218, v92
	v_exp_f32_e32 v219, v93
	v_exp_f32_e32 v220, v94
	v_exp_f32_e32 v221, v95
	s_waitcnt lgkmcnt(3)
	v_mfma_f32_32x32x16_bf16 v[64:79], v[132:135], v[222:225], v[64:79]
	v_add_f32_e32 v88, v180, v194
	v_add_f32_e32 v88, v181, v88
	v_add_f32_e32 v88, v182, v88
	v_add_f32_e32 v88, v183, v88
	ds_read_b128 v[84:87], v235 offset:20480
	v_add_f32_e32 v88, v193, v88
	v_add_f32_e32 v88, v189, v88
	v_add_f32_e32 v88, v190, v88
	v_add_f32_e32 v180, v192, v88
	s_waitcnt lgkmcnt(3)
	v_mfma_f32_32x32x16_bf16 v[64:79], v[136:139], v[226:229], v[64:79]
	ds_read_b128 v[88:91], v236 offset:20480
	v_exp_f32_e32 v222, v96
	v_exp_f32_e32 v223, v97
	v_exp_f32_e32 v224, v98
	v_exp_f32_e32 v225, v99
	s_waitcnt lgkmcnt(3)
	v_mfma_f32_32x32x16_bf16 v[64:79], v[140:143], v[230:233], v[64:79]
	v_add_f32_e32 v96, v173, v180
	ds_read_b128 v[92:95], v237 offset:20480
	v_add_f32_e32 v96, v174, v96
	v_add_f32_e32 v96, v175, v96
	v_add_f32_e32 v96, v176, v96
	v_add_f32_e32 v96, v191, v96
	v_add_f32_e32 v96, v188, v96
	s_waitcnt lgkmcnt(3)
	v_mfma_f32_32x32x16_bf16 v[48:63], v[128:131], v[80:83], v[48:63]
	ds_read_b128 v[80:83], v234 offset:24576
	v_exp_f32_e32 v226, v100
	v_exp_f32_e32 v227, v101
	v_exp_f32_e32 v228, v102
	v_exp_f32_e32 v229, v103
	s_waitcnt lgkmcnt(3)
	v_mfma_f32_32x32x16_bf16 v[48:63], v[132:135], v[84:87], v[48:63]
	v_add_f32_e32 v96, v171, v96
	ds_read_b128 v[84:87], v235 offset:24576
	v_add_f32_e32 v96, v172, v96
	v_add_f32_e32 v96, v185, v96
	v_add_f32_e32 v96, v186, v96
	v_add_f32_e32 v96, v187, v96
	v_add_f32_e32 v96, v184, v96
	s_waitcnt lgkmcnt(3)
	v_mfma_f32_32x32x16_bf16 v[48:63], v[136:139], v[88:91], v[48:63]
	ds_read_b128 v[88:91], v236 offset:24576
	v_exp_f32_e32 v230, v104
	v_exp_f32_e32 v231, v105
	v_exp_f32_e32 v232, v106
	v_exp_f32_e32 v233, v107
	s_waitcnt lgkmcnt(3)
	v_mfma_f32_32x32x16_bf16 v[48:63], v[140:143], v[92:95], v[48:63]
	ds_read_b128 v[92:95], v237 offset:24576
	v_add_f32_e32 v96, v177, v96
	v_add_f32_e32 v96, v178, v96
	v_add_f32_e32 v96, v179, v96
	v_add_f32_e32 v96, v161, v96
	s_waitcnt lgkmcnt(3)
	v_mfma_f32_32x32x16_bf16 v[32:47], v[128:131], v[80:83], v[32:47]
	ds_read_b128 v[80:83], v234 offset:28672
	v_exp_f32_e32 v161, v108
	v_exp_f32_e32 v234, v109
	v_exp_f32_e32 v239, v110
	v_exp_f32_e32 v240, v111
	s_waitcnt lgkmcnt(3)
	v_mfma_f32_32x32x16_bf16 v[32:47], v[132:135], v[84:87], v[32:47]
	ds_read_b128 v[84:87], v235 offset:28672
	s_waitcnt lgkmcnt(3)
	v_mfma_f32_32x32x16_bf16 v[32:47], v[136:139], v[88:91], v[32:47]
	ds_read_b128 v[88:91], v236 offset:28672
	s_waitcnt lgkmcnt(3)
	v_mfma_f32_32x32x16_bf16 v[32:47], v[140:143], v[92:95], v[32:47]
	ds_read_b128 v[92:95], v237 offset:28672
	s_waitcnt lgkmcnt(3)
	v_mfma_f32_32x32x16_bf16 v[16:31], v[128:131], v[80:83], v[16:31]
	s_add_i32 s18, s97, 0xffff8000
	s_and_b32 s18, s18, 0x18000
	s_add_i32 s19, s18, s67
	s_mov_b32 m0, s19
	s_nop 0
	global_load_lds_dwordx4 v156, s[16:17]
	s_waitcnt lgkmcnt(2)
	v_mfma_f32_32x32x16_bf16 v[16:31], v[132:135], v[84:87], v[16:31]
	s_addk_i32 s19, 0x400
	s_mov_b32 m0, s19
	s_nop 0
	global_load_lds_dwordx4 v154, s[16:17]
	s_waitcnt lgkmcnt(1)
	v_mfma_f32_32x32x16_bf16 v[16:31], v[136:139], v[88:91], v[16:31]
	s_add_i32 s18, s18, s70
	s_mov_b32 m0, s18
	s_nop 0
	global_load_lds_dwordx4 v150, s[14:15]
	s_waitcnt lgkmcnt(0)
	v_mfma_f32_32x32x16_bf16 v[16:31], v[140:143], v[92:95], v[16:31]
	s_addk_i32 s18, 0x400
	s_mov_b32 m0, s18
	s_nop 0
	global_load_lds_dwordx4 v148, s[14:15]
	s_add_i32 s18, s97, 0xffff0000
	s_and_b32 s18, s18, 0x18000
	s_add_i32 s18, s18, 0
	s_cmp_lt_u32 s61, 33
	s_cselect_b32 s34, s96, 0x8c0
	v_add_u32_e32 v132, s18, v144
	v_add_u32_e32 v133, s18, v157
	v_add_u32_e32 v136, s18, v159
	v_add_u32_e32 v137, s18, v160
	s_lshl_b64 s[18:19], s[34:35], 10
	s_add_u32 s56, s12, s18
	s_addc_u32 s57, s13, s19
	s_add_i32 s77, s26, s67
	v_add_f32_e32 v158, v158, v96
	s_waitcnt vmcnt(4) lgkmcnt(0)
	s_barrier
	s_lshl_b64 s[18:19], s[34:35], 1
	s_add_i32 s34, s77, 0x400
	ds_read_b128 v[96:99], v132
	ds_read_b128 v[100:103], v133
	ds_read_b128 v[104:107], v136
	ds_read_b128 v[108:111], v137
	s_add_u32 s18, s10, s18
	s_addc_u32 s19, s11, s19
	s_add_i32 s27, s26, s70
	s_addk_i32 s96, 0x80
	s_add_i32 s97, s97, 0x10000
	s_add_i32 s26, s27, 0x400
	s_add_u32 s14, s14, 0x100
	s_addc_u32 s15, s15, 0
	s_add_u32 s16, s16, 0x20000
	s_addc_u32 s17, s17, 0
	s_cmp_gt_u32 s61, 32
	ds_read_b128 v[172:175], v132 offset:4096
	ds_read_b128 v[176:179], v133 offset:4096
	s_waitcnt lgkmcnt(5)
	v_mfma_f32_32x32x16_bf16 v[80:95], v[96:99], v[124:127], v[0:15]
	v_cvt_pk_bf16_f32 v128, v195, v196
	v_cvt_pk_bf16_f32 v129, v197, v198
	v_cvt_pk_bf16_f32 v130, v199, v200
	v_cvt_pk_bf16_f32 v131, v201, v238
	ds_read_b128 v[180:183], v136 offset:4096
	ds_read_b128 v[184:187], v137 offset:4096
	s_waitcnt lgkmcnt(6)
	v_mfma_f32_32x32x16_bf16 v[80:95], v[100:103], v[120:123], v[80:95]
	v_cvt_pk_bf16_f32 v132, v214, v215
	v_cvt_pk_bf16_f32 v133, v216, v217
	v_cvt_pk_bf16_f32 v134, v218, v219
	v_cvt_pk_bf16_f32 v135, v220, v221
	v_add_u32_e32 v235, vcc_hi, v167
	ds_read_b128 v[188:191], v235 offset:16384
	v_add_u32_e32 v236, vcc_hi, v168
	ds_read_b128 v[202:205], v236 offset:16384
	s_waitcnt lgkmcnt(7)
	v_mfma_f32_32x32x16_bf16 v[80:95], v[104:107], v[116:119], v[80:95]
	v_cvt_pk_bf16_f32 v136, v222, v223
	v_cvt_pk_bf16_f32 v137, v224, v225
	v_cvt_pk_bf16_f32 v138, v226, v227
	v_cvt_pk_bf16_f32 v139, v228, v229
	v_add_u32_e32 v237, vcc_hi, v169
	v_add_u32_e32 v241, vcc_hi, v170
	ds_read_b128 v[206:209], v237 offset:16384
	ds_read_b128 v[210:213], v241 offset:16384
	s_waitcnt lgkmcnt(8)
	v_mfma_f32_32x32x16_bf16 v[80:95], v[108:111], v[112:115], v[80:95]
	v_cvt_pk_bf16_f32 v140, v230, v231
	v_cvt_pk_bf16_f32 v141, v232, v233
	v_cvt_pk_bf16_f32 v142, v161, v234
	v_cvt_pk_bf16_f32 v143, v239, v240
	v_add_f32_e32 v96, 0, v195
	v_add_f32_e32 v96, v196, v96
	v_add_f32_e32 v96, v197, v96
	v_add_f32_e32 v96, v198, v96
	v_add_f32_e32 v96, v199, v96
	v_add_f32_e32 v171, v200, v96
	v_add_f32_e32 v171, v201, v171
	v_add_f32_e32 v171, v238, v171
	s_waitcnt lgkmcnt(7)
	v_mfma_f32_32x32x16_bf16 v[96:111], v[172:175], v[124:127], v[0:15]
	v_exp_f32_e32 v194, v80
	v_exp_f32_e32 v195, v81
	v_exp_f32_e32 v196, v82
	v_exp_f32_e32 v197, v83
	s_waitcnt lgkmcnt(6)
	v_mfma_f32_32x32x16_bf16 v[96:111], v[176:179], v[120:123], v[96:111]
	v_exp_f32_e32 v198, v84
	v_exp_f32_e32 v200, v85
	v_exp_f32_e32 v199, v86
	v_exp_f32_e32 v201, v87
	s_waitcnt lgkmcnt(5)
	v_mfma_f32_32x32x16_bf16 v[96:111], v[180:183], v[116:119], v[96:111]
	v_exp_f32_e32 v180, v88
	v_exp_f32_e32 v181, v89
	v_exp_f32_e32 v182, v90
	v_exp_f32_e32 v183, v91
	s_waitcnt lgkmcnt(4)
	v_mfma_f32_32x32x16_bf16 v[96:111], v[184:187], v[112:115], v[96:111]
	s_waitcnt lgkmcnt(3)
	v_mfma_f32_32x32x16_bf16 v[64:79], v[128:131], v[188:191], v[64:79]
	ds_read_b128 v[80:83], v235 offset:20480
	v_exp_f32_e32 v193, v92
	v_exp_f32_e32 v189, v93
	v_exp_f32_e32 v190, v94
	v_exp_f32_e32 v192, v95
	s_waitcnt lgkmcnt(3)
	v_mfma_f32_32x32x16_bf16 v[64:79], v[132:135], v[202:205], v[64:79]
	v_add_f32_e32 v88, v214, v171
	v_add_f32_e32 v88, v215, v88
	v_add_f32_e32 v88, v216, v88
	v_add_f32_e32 v88, v217, v88
	ds_read_b128 v[84:87], v236 offset:20480
	v_add_f32_e32 v88, v218, v88
	v_add_f32_e32 v88, v219, v88
	v_add_f32_e32 v88, v220, v88
	v_add_f32_e32 v171, v221, v88
	s_waitcnt lgkmcnt(3)
	v_mfma_f32_32x32x16_bf16 v[64:79], v[136:139], v[206:209], v[64:79]
	ds_read_b128 v[88:91], v237 offset:20480
	v_exp_f32_e32 v173, v96
	v_exp_f32_e32 v174, v97
	v_exp_f32_e32 v175, v98
	v_exp_f32_e32 v176, v99
	s_waitcnt lgkmcnt(3)
	v_mfma_f32_32x32x16_bf16 v[64:79], v[140:143], v[210:213], v[64:79]
	v_add_f32_e32 v96, v222, v171
	ds_read_b128 v[92:95], v241 offset:20480
	v_add_f32_e32 v96, v223, v96
	v_add_f32_e32 v96, v224, v96
	v_add_f32_e32 v96, v225, v96
	v_add_f32_e32 v96, v226, v96
	v_add_f32_e32 v96, v227, v96
	s_waitcnt lgkmcnt(3)
	v_mfma_f32_32x32x16_bf16 v[48:63], v[128:131], v[80:83], v[48:63]
	ds_read_b128 v[80:83], v235 offset:24576
	v_exp_f32_e32 v191, v100
	v_exp_f32_e32 v188, v101
	v_exp_f32_e32 v171, v102
	v_exp_f32_e32 v172, v103
	s_waitcnt lgkmcnt(3)
	v_mfma_f32_32x32x16_bf16 v[48:63], v[132:135], v[84:87], v[48:63]
	v_add_f32_e32 v96, v228, v96
	ds_read_b128 v[84:87], v236 offset:24576
	v_add_f32_e32 v96, v229, v96
	v_add_f32_e32 v96, v230, v96
	v_add_f32_e32 v96, v231, v96
	v_add_f32_e32 v96, v232, v96
	v_add_f32_e32 v96, v233, v96
	s_waitcnt lgkmcnt(3)
	v_mfma_f32_32x32x16_bf16 v[48:63], v[136:139], v[88:91], v[48:63]
	ds_read_b128 v[88:91], v237 offset:24576
	v_exp_f32_e32 v185, v104
	v_exp_f32_e32 v186, v105
	v_exp_f32_e32 v187, v106
	v_exp_f32_e32 v184, v107
	s_waitcnt lgkmcnt(3)
	v_mfma_f32_32x32x16_bf16 v[48:63], v[140:143], v[92:95], v[48:63]
	ds_read_b128 v[92:95], v241 offset:24576
	v_add_f32_e32 v96, v161, v96
	v_add_f32_e32 v96, v234, v96
	v_add_f32_e32 v96, v239, v96
	v_add_f32_e32 v96, v240, v96
	s_waitcnt lgkmcnt(3)
	v_mfma_f32_32x32x16_bf16 v[32:47], v[128:131], v[80:83], v[32:47]
	ds_read_b128 v[80:83], v235 offset:28672
	v_exp_f32_e32 v177, v108
	v_exp_f32_e32 v178, v109
	v_exp_f32_e32 v179, v110
	v_exp_f32_e32 v161, v111
	s_waitcnt lgkmcnt(3)
	v_mfma_f32_32x32x16_bf16 v[32:47], v[132:135], v[84:87], v[32:47]
	ds_read_b128 v[84:87], v236 offset:28672
	s_waitcnt lgkmcnt(3)
	v_mfma_f32_32x32x16_bf16 v[32:47], v[136:139], v[88:91], v[32:47]
	ds_read_b128 v[88:91], v237 offset:28672
	s_waitcnt lgkmcnt(3)
	v_mfma_f32_32x32x16_bf16 v[32:47], v[140:143], v[92:95], v[32:47]
	ds_read_b128 v[92:95], v241 offset:28672
	s_waitcnt lgkmcnt(3)
	v_mfma_f32_32x32x16_bf16 v[16:31], v[128:131], v[80:83], v[16:31]
	s_mov_b32 m0, s77
	s_nop 0
	global_load_lds_dwordx4 v156, s[56:57]
	s_waitcnt lgkmcnt(2)
	v_mfma_f32_32x32x16_bf16 v[16:31], v[132:135], v[84:87], v[16:31]
	s_mov_b32 m0, s34
	s_nop 0
	global_load_lds_dwordx4 v154, s[56:57]
	s_waitcnt lgkmcnt(1)
	v_mfma_f32_32x32x16_bf16 v[16:31], v[136:139], v[88:91], v[16:31]
	s_mov_b32 m0, s27
	s_nop 0
	global_load_lds_dwordx4 v150, s[18:19]
	s_waitcnt lgkmcnt(0)
	v_mfma_f32_32x32x16_bf16 v[16:31], v[140:143], v[92:95], v[16:31]
	s_mov_b32 m0, s26
	s_nop 0
	global_load_lds_dwordx4 v148, s[18:19]
	v_add_f32_e32 v158, v158, v96
	s_mov_b32 s61, vcc_lo
	s_cbranch_scc0 .LBB0_649
	v_or_b32_e32 v80, s75, v146
	v_cmp_eq_u32_e32 vcc, 0, v80
	s_and_saveexec_b64 s[14:15], vcc
	s_cbranch_execz .LBB0_652
	v_mov_b64_e32 v[80:81], s[54:55]
	global_atomic_add v136, v[80:81], v147, off sc0
.LBB0_652:
	s_or_b64 exec, exec, s[14:15]
	s_add_i32 s14, 0, 0x18000
	v_add_u32_e32 v81, s14, v144
	v_add_u32_e32 v139, s14, v159
	v_add_u32_e32 v82, s14, v157
	v_add_u32_e32 v141, s14, v160
	s_waitcnt vmcnt(4) lgkmcnt(0)
	s_barrier
	ds_read_b128 v[96:99], v81
	ds_read_b128 v[100:103], v82
	ds_read_b128 v[104:107], v139
	ds_read_b128 v[108:111], v141
	v_or_b32_e32 v80, 0x4000, v166
	v_add_u32_e32 v142, v162, v80
	v_add_u32_e32 v140, v163, v80
	v_add_u32_e32 v138, v164, v80
	v_add_u32_e32 v137, v165, v80
	ds_read_b128 v[162:165], v81 offset:4096
	ds_read_b128 v[166:169], v82 offset:4096
	s_waitcnt lgkmcnt(5)
	v_mfma_f32_32x32x16_bf16 v[80:95], v[96:99], v[124:127], v[0:15]
	v_cvt_pk_bf16_f32 v128, v194, v195
	v_cvt_pk_bf16_f32 v129, v196, v197
	v_cvt_pk_bf16_f32 v130, v198, v200
	v_cvt_pk_bf16_f32 v131, v199, v201
	s_waitcnt lgkmcnt(4)
	v_mfma_f32_32x32x16_bf16 v[80:95], v[100:103], v[120:123], v[80:95]
	ds_read_b128 v[202:205], v139 offset:4096
	ds_read_b128 v[206:209], v141 offset:4096
	v_cvt_pk_bf16_f32 v132, v180, v181
	v_cvt_pk_bf16_f32 v133, v182, v183
	v_cvt_pk_bf16_f32 v134, v193, v189
	v_cvt_pk_bf16_f32 v135, v190, v192
	s_waitcnt lgkmcnt(5)
	v_mfma_f32_32x32x16_bf16 v[80:95], v[104:107], v[116:119], v[80:95]
	s_add_i32 s15, 0, 0x10000
	v_add_u32_e32 v139, s15, v142
	v_add_u32_e32 v141, s15, v140
	ds_read_b128 v[214:217], v139
	ds_read_b128 v[218:221], v141
	v_cvt_pk_bf16_f32 v210, v173, v174
	v_cvt_pk_bf16_f32 v211, v175, v176
	v_cvt_pk_bf16_f32 v212, v191, v188
	v_cvt_pk_bf16_f32 v213, v171, v172
	s_waitcnt lgkmcnt(6)
	v_mfma_f32_32x32x16_bf16 v[80:95], v[108:111], v[112:115], v[80:95]
	v_add_u32_e32 v143, s15, v138
	v_add_u32_e32 v144, s15, v137
	ds_read_b128 v[226:229], v143
	ds_read_b128 v[230:233], v144
	v_cvt_pk_bf16_f32 v222, v185, v186
	v_cvt_pk_bf16_f32 v223, v187, v184
	v_cvt_pk_bf16_f32 v224, v177, v178
	v_cvt_pk_bf16_f32 v225, v179, v161
	v_add_f32_e32 v96, 0, v194
	v_add_f32_e32 v96, v195, v96
	v_add_f32_e32 v96, v196, v96
	v_add_f32_e32 v96, v197, v96
	v_add_f32_e32 v96, v198, v96
	v_add_f32_e32 v157, v200, v96
	s_waitcnt lgkmcnt(7)
	v_mfma_f32_32x32x16_bf16 v[96:111], v[162:165], v[124:127], v[0:15]
	v_add_f32_e32 v124, v199, v157
	v_add_f32_e32 v124, v201, v124
	s_waitcnt lgkmcnt(6)
	v_mfma_f32_32x32x16_bf16 v[96:111], v[166:169], v[120:123], v[96:111]
	v_exp_f32_e32 v125, v80
	v_exp_f32_e32 v126, v81
	v_exp_f32_e32 v127, v82
	v_exp_f32_e32 v157, v83
	s_waitcnt lgkmcnt(5)
	v_mfma_f32_32x32x16_bf16 v[96:111], v[202:205], v[116:119], v[96:111]
	v_exp_f32_e32 v122, v84
	v_exp_f32_e32 v123, v85
	v_exp_f32_e32 v159, v86
	v_exp_f32_e32 v160, v87
	s_waitcnt lgkmcnt(4)
	v_mfma_f32_32x32x16_bf16 v[96:111], v[206:209], v[112:115], v[96:111]
	v_exp_f32_e32 v162, v88
	v_exp_f32_e32 v163, v89
	v_exp_f32_e32 v164, v90
	v_exp_f32_e32 v165, v91
	s_waitcnt lgkmcnt(3)
	v_mfma_f32_32x32x16_bf16 v[64:79], v[128:131], v[214:217], v[64:79]
	ds_read_b128 v[80:83], v139 offset:4096
	v_exp_f32_e32 v166, v92
	v_exp_f32_e32 v167, v93
	v_exp_f32_e32 v168, v94
	v_exp_f32_e32 v169, v95
	s_waitcnt lgkmcnt(3)
	v_mfma_f32_32x32x16_bf16 v[64:79], v[132:135], v[218:221], v[64:79]
	v_add_f32_e32 v88, v180, v124
	v_add_f32_e32 v88, v181, v88
	ds_read_b128 v[84:87], v141 offset:4096
	v_add_f32_e32 v88, v182, v88
	v_add_f32_e32 v88, v183, v88
	v_add_f32_e32 v88, v193, v88
	v_add_f32_e32 v88, v189, v88
	v_add_f32_e32 v88, v190, v88
	v_add_f32_e32 v112, v192, v88
	s_waitcnt lgkmcnt(3)
	v_mfma_f32_32x32x16_bf16 v[64:79], v[210:213], v[226:229], v[64:79]
	ds_read_b128 v[88:91], v143 offset:4096
	v_exp_f32_e32 v124, v96
	v_exp_f32_e32 v170, v97
	v_exp_f32_e32 v180, v98
	v_exp_f32_e32 v181, v99
	s_waitcnt lgkmcnt(3)
	v_mfma_f32_32x32x16_bf16 v[64:79], v[222:225], v[230:233], v[64:79]
	ds_read_b128 v[92:95], v144 offset:4096
	v_add_f32_e32 v96, v173, v112
	v_add_f32_e32 v96, v174, v96
	v_add_f32_e32 v96, v175, v96
	v_add_f32_e32 v96, v176, v96
	v_add_f32_e32 v96, v191, v96
	v_add_f32_e32 v112, v188, v96
	s_waitcnt lgkmcnt(3)
	v_mfma_f32_32x32x16_bf16 v[48:63], v[128:131], v[80:83], v[48:63]
	ds_read_b128 v[96:99], v139 offset:8192
	v_exp_f32_e32 v173, v100
	v_exp_f32_e32 v174, v101
	v_exp_f32_e32 v175, v102
	v_exp_f32_e32 v176, v103
	s_waitcnt lgkmcnt(3)
	v_mfma_f32_32x32x16_bf16 v[48:63], v[132:135], v[84:87], v[48:63]
	ds_read_b128 v[80:83], v141 offset:8192
	v_add_f32_e32 v100, v171, v112
	v_add_f32_e32 v100, v172, v100
	v_add_f32_e32 v100, v185, v100
	v_add_f32_e32 v100, v186, v100
	v_add_f32_e32 v100, v187, v100
	v_add_f32_e32 v100, v184, v100
	s_waitcnt lgkmcnt(3)
	v_mfma_f32_32x32x16_bf16 v[48:63], v[210:213], v[88:91], v[48:63]
	ds_read_b128 v[84:87], v143 offset:8192
	v_exp_f32_e32 v171, v104
	v_exp_f32_e32 v172, v105
	v_exp_f32_e32 v182, v106
	v_exp_f32_e32 v183, v107
	s_waitcnt lgkmcnt(3)
	v_mfma_f32_32x32x16_bf16 v[48:63], v[222:225], v[92:95], v[48:63]
	ds_read_b128 v[88:91], v144 offset:8192
	v_add_f32_e32 v100, v177, v100
	v_add_f32_e32 v100, v178, v100
	v_add_f32_e32 v177, v179, v100
	s_waitcnt lgkmcnt(3)
	v_mfma_f32_32x32x16_bf16 v[32:47], v[128:131], v[96:99], v[32:47]
	ds_read_b128 v[92:95], v139 offset:12288
	v_exp_f32_e32 v178, v108
	v_exp_f32_e32 v179, v109
	v_exp_f32_e32 v184, v110
	v_exp_f32_e32 v185, v111
	s_waitcnt lgkmcnt(3)
	v_mfma_f32_32x32x16_bf16 v[32:47], v[132:135], v[80:83], v[32:47]
	ds_read_b128 v[96:99], v141 offset:12288
	s_waitcnt lgkmcnt(3)
	v_mfma_f32_32x32x16_bf16 v[32:47], v[210:213], v[84:87], v[32:47]
	ds_read_b128 v[80:83], v143 offset:12288
	s_waitcnt lgkmcnt(3)
	v_mfma_f32_32x32x16_bf16 v[32:47], v[222:225], v[88:91], v[32:47]
	ds_read_b128 v[84:87], v144 offset:12288
	s_waitcnt lgkmcnt(3)
	v_mfma_f32_32x32x16_bf16 v[16:31], v[128:131], v[92:95], v[16:31]
	s_add_u32 s12, s12, 0x230000
	s_addc_u32 s13, s13, 0
	s_mov_b32 m0, s71
	s_nop 0
	global_load_lds_dwordx4 v156, s[12:13]
	s_waitcnt lgkmcnt(2)
	v_mfma_f32_32x32x16_bf16 v[16:31], v[132:135], v[96:99], v[16:31]
	s_mov_b32 m0, s72
	s_nop 0
	global_load_lds_dwordx4 v154, s[12:13]
	s_waitcnt lgkmcnt(1)
	v_mfma_f32_32x32x16_bf16 v[16:31], v[210:213], v[80:83], v[16:31]
	s_add_u32 s10, s10, 0x1180
	s_addc_u32 s11, s11, 0
	s_mov_b32 m0, s73
	s_nop 0
	global_load_lds_dwordx4 v150, s[10:11]
	s_waitcnt lgkmcnt(0)
	v_mfma_f32_32x32x16_bf16 v[16:31], v[222:225], v[84:87], v[16:31]
	s_mov_b32 m0, s78
	s_nop 0
	global_load_lds_dwordx4 v148, s[10:11]
	v_add_u32_e32 v80, s14, v142
	v_cvt_pk_bf16_f32 v98, v125, v126
	v_cvt_pk_bf16_f32 v99, v127, v157
	v_cvt_pk_bf16_f32 v100, v122, v123
	v_cvt_pk_bf16_f32 v101, v159, v160
	ds_read_b128 v[80:83], v80
	v_add_u32_e32 v84, s14, v140
	ds_read_b128 v[84:87], v84
	s_waitcnt lgkmcnt(1)
	v_mfma_f32_32x32x16_bf16 v[64:79], v[98:101], v[80:83], v[64:79]
	v_cvt_pk_bf16_f32 v102, v162, v163
	v_cvt_pk_bf16_f32 v103, v164, v165
	v_cvt_pk_bf16_f32 v104, v166, v167
	v_cvt_pk_bf16_f32 v105, v168, v169
	v_add_u32_e32 v80, s14, v138
	v_cvt_pk_bf16_f32 v106, v124, v170
	v_cvt_pk_bf16_f32 v107, v180, v181
	s_waitcnt lgkmcnt(0)
	v_mfma_f32_32x32x16_bf16 v[64:79], v[102:105], v[84:87], v[64:79]
	v_cvt_pk_bf16_f32 v108, v173, v174
	v_cvt_pk_bf16_f32 v109, v175, v176
	ds_read_b128 v[80:83], v80
	v_add_u32_e32 v84, s14, v137
	ds_read_b128 v[84:87], v84
	v_cvt_pk_bf16_f32 v110, v171, v172
	v_cvt_pk_bf16_f32 v111, v182, v183
	s_waitcnt lgkmcnt(1)
	v_mfma_f32_32x32x16_bf16 v[64:79], v[106:109], v[80:83], v[64:79]
	v_cvt_pk_bf16_f32 v112, v178, v179
	v_cvt_pk_bf16_f32 v113, v184, v185
	v_add_u32_e32 v80, s91, v142
	ds_read_b128 v[80:83], v80
	v_ashrrev_i32_e32 v88, 4, v146
	v_add_u32_e32 v139, s69, v88
	s_lshl_b32 s10, s60, 1
	s_waitcnt lgkmcnt(1)
	v_mfma_f32_32x32x16_bf16 v[64:79], v[110:113], v[84:87], v[64:79]
	v_add_u32_e32 v84, s91, v140
	ds_read_b128 v[84:87], v84
	v_add_u32_e32 v96, s59, v139
	s_add_u32 s4, s4, s10
	s_addc_u32 s5, s5, 0
	v_ashrrev_i32_e32 v97, 31, v96
	v_add_u32_e32 v118, s92, v140
	s_waitcnt lgkmcnt(1)
	v_mfma_f32_32x32x16_bf16 v[48:63], v[98:101], v[80:83], v[48:63]
	v_lshlrev_b32_e32 v80, 3, v146
	v_and_b32_e32 v143, 0x78, v80
	v_add_u32_e32 v80, s91, v138
	ds_read_b128 v[80:83], v80
	v_lshlrev_b32_e32 v144, 1, v143
	v_lshl_add_u64 v[88:89], s[4:5], 0, v[144:145]
	s_mov_b32 s4, 0x9c01000
	s_waitcnt lgkmcnt(1)
	v_mfma_f32_32x32x16_bf16 v[48:63], v[102:105], v[84:87], v[48:63]
	v_lshlrev_b64 v[84:85], 10, v[96:97]
	v_lshl_add_u64 v[114:115], v[88:89], 0, v[84:85]
	v_add_u32_e32 v84, s91, v137
	ds_read_b128 v[84:87], v84
	v_add_f32_e32 v125, 0, v125
	s_waitcnt lgkmcnt(1)
	v_mfma_f32_32x32x16_bf16 v[48:63], v[106:109], v[80:83], v[48:63]
	v_add_co_u32_e64 v80, s[4:5], s4, v114
	s_nop 1
	v_addc_co_u32_e64 v81, s[4:5], 0, v115, s[4:5]
	s_mov_b32 s4, 0x9c03000
	global_load_dwordx4 v[92:95], v[80:81], off offset:-4096
	global_load_dwordx4 v[88:91], v[80:81], off
	v_add_co_u32_e64 v80, s[4:5], s4, v114
	s_waitcnt lgkmcnt(0)
	v_mfma_f32_32x32x16_bf16 v[48:63], v[110:113], v[84:87], v[48:63]
	v_addc_co_u32_e64 v81, s[4:5], 0, v115, s[4:5]
	global_load_dwordx4 v[84:87], v[80:81], off offset:-4096
	s_nop 0
	global_load_dwordx4 v[80:83], v[80:81], off
	v_add_u32_e32 v114, s92, v142
	ds_read_b128 v[114:117], v114
	ds_read_b128 v[118:121], v118
	s_waitcnt lgkmcnt(1)
	v_mfma_f32_32x32x16_bf16 v[32:47], v[98:101], v[114:117], v[32:47]
	v_add_f32_e32 v114, 0, v124
	v_add_f32_e32 v115, v126, v125
	v_add_f32_e32 v114, v170, v114
	v_add_f32_e32 v115, v127, v115
	v_add_f32_e32 v114, v180, v114
	v_add_f32_e32 v115, v157, v115
	v_add_f32_e32 v124, v181, v114
	s_waitcnt lgkmcnt(0)
	v_mfma_f32_32x32x16_bf16 v[32:47], v[102:105], v[118:121], v[32:47]
	v_add_u32_e32 v114, s92, v138
	v_add_f32_e32 v118, v122, v115
	ds_read_b128 v[114:117], v114
	v_add_f32_e32 v123, v123, v118
	v_add_u32_e32 v118, s92, v137
	ds_read_b128 v[118:121], v118
	v_add_f32_e32 v122, v173, v124
	s_waitcnt lgkmcnt(1)
	v_mfma_f32_32x32x16_bf16 v[32:47], v[106:109], v[114:117], v[32:47]
	v_add_f32_e32 v114, v174, v122
	v_add_f32_e32 v115, v159, v123
	v_add_f32_e32 v114, v175, v114
	v_add_f32_e32 v115, v160, v115
	v_add_f32_e32 v114, v176, v114
	v_add_f32_e32 v115, v162, v115
	v_add_f32_e32 v122, v171, v114
	v_add_u32_e32 v114, s93, v142
	s_waitcnt lgkmcnt(0)
	v_mfma_f32_32x32x16_bf16 v[32:47], v[110:113], v[118:121], v[32:47]
	v_add_f32_e32 v118, v163, v115
	ds_read_b128 v[114:117], v114
	v_add_f32_e32 v123, v164, v118
	v_add_u32_e32 v118, s93, v140
	ds_read_b128 v[118:121], v118
	v_add_f32_e32 v122, v172, v122
	s_waitcnt lgkmcnt(1)
	v_mfma_f32_32x32x16_bf16 v[16:31], v[98:101], v[114:117], v[16:31]
	v_add_f32_e32 v98, v182, v122
	v_add_f32_e32 v99, v165, v123
	v_add_f32_e32 v98, v183, v98
	v_add_f32_e32 v99, v166, v99
	v_add_f32_e32 v98, v178, v98
	v_add_f32_e32 v99, v167, v99
	v_add_f32_e32 v114, v179, v98
	s_waitcnt lgkmcnt(0)
	v_mfma_f32_32x32x16_bf16 v[16:31], v[102:105], v[118:121], v[16:31]
	v_add_u32_e32 v98, s93, v138
	v_add_f32_e32 v102, v168, v99
	ds_read_b128 v[98:101], v98
	v_add_f32_e32 v115, v169, v102
	v_add_u32_e32 v102, s93, v137
	ds_read_b128 v[102:105], v102
	v_add_f32_e32 v114, v184, v114
	s_waitcnt lgkmcnt(1)
	v_mfma_f32_32x32x16_bf16 v[16:31], v[106:109], v[98:101], v[16:31]
	v_add_f32_e32 v98, v185, v114
	v_add_f32_e32 v99, v161, v177
	v_add_f32_e32 v98, v115, v98
	v_add_f32_e32 v99, v158, v99
	v_lshlrev_b32_e32 v115, 2, v146
	v_add_f32_e32 v98, v99, v98
	v_xor_b32_e32 v99, 0x80, v115
	s_waitcnt lgkmcnt(0)
	v_mfma_f32_32x32x16_bf16 v[16:31], v[110:113], v[102:105], v[16:31]
	ds_bpermute_b32 v99, v99, v98
	s_waitcnt vmcnt(0) lgkmcnt(0)
	s_barrier
	s_and_saveexec_b64 s[4:5], vcc
	s_cbranch_execz .LBB0_654
	v_mov_b32_e32 v100, s89
	ds_write_b32 v100, v136

.LBB0_818:
	s_add_u32 s5, s70, 0x100
	s_addc_u32 s61, s71, 0
	s_add_u32 s68, s68, 0x40080
	v_mov_b32_e32 v0, 0
	s_addc_u32 s69, s69, 0
	s_mov_b32 s91, -2
	s_waitcnt lgkmcnt(0)
	ds_read_b128 v[104:107], v229
	ds_read_b128 v[108:111], v229 offset:1024
	ds_read_b128 v[128:131], v229 offset:2048
	ds_read_b128 v[132:135], v229 offset:3072
	ds_read_b128 v[144:147], v230
	ds_read_b128 v[148:151], v230 offset:1024
	ds_read_b128 v[152:155], v230 offset:2048
	ds_read_b128 v[156:159], v230 offset:3072
	s_add_u32 s26, s68, 0xfffc0080
	s_addc_u32 s27, s69, -1
	s_cmp_eq_u32 s91, 12
	s_cselect_b32 s73, s63, s27
	s_cselect_b32 s72, s62, s26
	s_cselect_b32 s71, s65, s61
	s_cselect_b32 s70, s64, s5
	s_add_i32 m0, s28, 0xc000
	ds_read_b128 v[160:163], v231
	ds_read_b128 v[164:167], v231 offset:1024
	ds_read_b128 v[168:171], v231 offset:2048
	ds_read_b128 v[172:175], v231 offset:3072
	ds_read_b128 v[176:179], v231 offset:4096
	ds_read_b128 v[180:183], v231 offset:5120
	ds_read_b128 v[184:187], v231 offset:6144
	ds_read_b128 v[188:191], v231 offset:7168
	global_load_lds_dwordx4 v202, s[68:69]
	s_add_i32 m0, s28, 0xe000
	s_nop 0
	global_load_lds_dwordx4 v200, s[68:69]
	s_waitcnt vmcnt(8) lgkmcnt(0)
	s_barrier
	v_mfma_f32_16x16x32_bf16 v[140:143], v[104:107], v[160:163], 0
	v_mfma_f32_16x16x32_bf16 v[136:139], v[128:131], v[160:163], 0
	v_mfma_f32_16x16x32_bf16 v[116:119], v[104:107], v[168:171], 0
	v_mfma_f32_16x16x32_bf16 v[112:115], v[128:131], v[168:171], 0
	v_mfma_f32_16x16x32_bf16 v[92:95], v[104:107], v[176:179], 0
	v_mfma_f32_16x16x32_bf16 v[88:91], v[128:131], v[176:179], 0
	v_mfma_f32_16x16x32_bf16 v[76:79], v[104:107], v[184:187], 0
	v_mfma_f32_16x16x32_bf16 v[72:75], v[128:131], v[184:187], 0
	v_mfma_f32_16x16x32_bf16 v[140:143], v[108:111], v[164:167], v[140:143]
	v_mfma_f32_16x16x32_bf16 v[136:139], v[132:135], v[164:167], v[136:139]
	v_mfma_f32_16x16x32_bf16 v[116:119], v[108:111], v[172:175], v[116:119]
	v_mfma_f32_16x16x32_bf16 v[112:115], v[132:135], v[172:175], v[112:115]
	v_mfma_f32_16x16x32_bf16 v[92:95], v[108:111], v[180:183], v[92:95]
	v_mfma_f32_16x16x32_bf16 v[88:91], v[132:135], v[180:183], v[88:91]
	v_mfma_f32_16x16x32_bf16 v[76:79], v[108:111], v[188:191], v[76:79]
	v_mfma_f32_16x16x32_bf16 v[72:75], v[132:135], v[188:191], v[72:75]
	v_mfma_f32_16x16x32_bf16 v[124:127], v[144:147], v[160:163], 0
	v_mfma_f32_16x16x32_bf16 v[120:123], v[152:155], v[160:163], 0
	v_mfma_f32_16x16x32_bf16 v[100:103], v[144:147], v[168:171], 0
	v_mfma_f32_16x16x32_bf16 v[96:99], v[152:155], v[168:171], 0
	v_mfma_f32_16x16x32_bf16 v[84:87], v[144:147], v[176:179], 0
	v_mfma_f32_16x16x32_bf16 v[80:83], v[152:155], v[176:179], 0
	v_mfma_f32_16x16x32_bf16 v[68:71], v[144:147], v[184:187], 0
	v_mfma_f32_16x16x32_bf16 v[64:67], v[152:155], v[184:187], 0
	v_mfma_f32_16x16x32_bf16 v[124:127], v[148:151], v[164:167], v[124:127]
	v_mfma_f32_16x16x32_bf16 v[120:123], v[156:159], v[164:167], v[120:123]
	v_mfma_f32_16x16x32_bf16 v[100:103], v[148:151], v[172:175], v[100:103]
	v_mfma_f32_16x16x32_bf16 v[96:99], v[156:159], v[172:175], v[96:99]
	v_mfma_f32_16x16x32_bf16 v[84:87], v[148:151], v[180:183], v[84:87]
	v_mfma_f32_16x16x32_bf16 v[80:83], v[156:159], v[180:183], v[80:83]
	v_mfma_f32_16x16x32_bf16 v[68:71], v[148:151], v[188:191], v[68:71]
	v_mfma_f32_16x16x32_bf16 v[64:67], v[156:159], v[188:191], v[64:67]
	s_barrier
	s_add_i32 s26, s83, s3
	v_lshl_add_u64 v[204:205], s[70:71], 0, v[194:195]
	s_mov_b32 m0, s26
	ds_read_b128 v[160:163], v231 offset:16384
	ds_read_b128 v[164:167], v231 offset:17408
	ds_read_b128 v[168:171], v231 offset:18432
	ds_read_b128 v[172:175], v231 offset:19456
	ds_read_b128 v[176:179], v231 offset:20480
	ds_read_b128 v[180:183], v231 offset:21504
	ds_read_b128 v[184:187], v231 offset:22528
	ds_read_b128 v[188:191], v231 offset:23552
	global_load_lds_dwordx4 v[204:205], off
	s_add_i32 m0, s26, 0x2000
	s_add_u32 s26, s70, 0x40000
	v_lshl_add_u64 v[206:207], s[70:71], 0, v[198:199]
	s_addc_u32 s27, s71, 0
	s_add_i32 s77, s84, s3
	global_load_lds_dwordx4 v[206:207], off
	s_mov_b32 m0, s77
	v_lshl_add_u64 v[210:211], s[72:73], 0, v[196:197]
	global_load_lds_dwordx4 v194, s[26:27]
	s_add_i32 m0, s77, 0x2000
	s_nop 0
	global_load_lds_dwordx4 v198, s[26:27]
	v_lshl_add_u64 v[208:209], s[72:73], 0, v[192:193]
	s_mov_b32 m0, s28
	s_nop 0
	global_load_lds_dwordx4 v[208:209], off
	s_mov_b32 m0, s29
	s_nop 0
	global_load_lds_dwordx4 v[210:211], off
	s_waitcnt vmcnt(8) lgkmcnt(0)
	s_barrier
	v_mfma_f32_16x16x32_bf16 v[60:63], v[104:107], v[160:163], 0
	v_mfma_f32_16x16x32_bf16 v[56:59], v[128:131], v[160:163], 0
	v_mfma_f32_16x16x32_bf16 v[44:47], v[104:107], v[168:171], 0
	v_mfma_f32_16x16x32_bf16 v[40:43], v[128:131], v[168:171], 0
	v_mfma_f32_16x16x32_bf16 v[28:31], v[104:107], v[176:179], 0
	v_mfma_f32_16x16x32_bf16 v[24:27], v[128:131], v[176:179], 0
	v_mfma_f32_16x16x32_bf16 v[12:15], v[104:107], v[184:187], 0
	v_mfma_f32_16x16x32_bf16 v[8:11], v[128:131], v[184:187], 0
	v_mfma_f32_16x16x32_bf16 v[60:63], v[108:111], v[164:167], v[60:63]
	v_mfma_f32_16x16x32_bf16 v[56:59], v[132:135], v[164:167], v[56:59]
	v_mfma_f32_16x16x32_bf16 v[44:47], v[108:111], v[172:175], v[44:47]
	v_mfma_f32_16x16x32_bf16 v[40:43], v[132:135], v[172:175], v[40:43]
	v_mfma_f32_16x16x32_bf16 v[28:31], v[108:111], v[180:183], v[28:31]
	v_mfma_f32_16x16x32_bf16 v[24:27], v[132:135], v[180:183], v[24:27]
	v_mfma_f32_16x16x32_bf16 v[12:15], v[108:111], v[188:191], v[12:15]
	v_mfma_f32_16x16x32_bf16 v[8:11], v[132:135], v[188:191], v[8:11]
	v_mfma_f32_16x16x32_bf16 v[52:55], v[144:147], v[160:163], 0
	v_mfma_f32_16x16x32_bf16 v[48:51], v[152:155], v[160:163], 0
	v_mfma_f32_16x16x32_bf16 v[36:39], v[144:147], v[168:171], 0
	v_mfma_f32_16x16x32_bf16 v[32:35], v[152:155], v[168:171], 0
	v_mfma_f32_16x16x32_bf16 v[20:23], v[144:147], v[176:179], 0
	v_mfma_f32_16x16x32_bf16 v[16:19], v[152:155], v[176:179], 0
	v_mfma_f32_16x16x32_bf16 v[4:7], v[144:147], v[184:187], 0
	v_mfma_f32_16x16x32_bf16 v[0:3], v[152:155], v[184:187], 0
	v_mfma_f32_16x16x32_bf16 v[52:55], v[148:151], v[164:167], v[52:55]
	v_mfma_f32_16x16x32_bf16 v[48:51], v[156:159], v[164:167], v[48:51]
	v_mfma_f32_16x16x32_bf16 v[36:39], v[148:151], v[172:175], v[36:39]
	v_mfma_f32_16x16x32_bf16 v[32:35], v[156:159], v[172:175], v[32:35]
	v_mfma_f32_16x16x32_bf16 v[20:23], v[148:151], v[180:183], v[20:23]
	v_mfma_f32_16x16x32_bf16 v[16:19], v[156:159], v[180:183], v[16:19]
	v_mfma_f32_16x16x32_bf16 v[4:7], v[148:151], v[188:191], v[4:7]
	v_mfma_f32_16x16x32_bf16 v[0:3], v[156:159], v[188:191], v[0:3]
	s_barrier
	s_add_i32 s77, 0, 0x18000
	s_add_i32 s92, 0, 0x1c000
	v_add_u32_e32 v132, s77, v228
	v_add_u32_e32 v156, s92, v228
	ds_read_b128 v[104:107], v132
	ds_read_b128 v[108:111], v132 offset:1024
	ds_read_b128 v[128:131], v132 offset:2048
	ds_read_b128 v[132:135], v132 offset:3072
	ds_read_b128 v[144:147], v156
	ds_read_b128 v[148:151], v156 offset:1024
	ds_read_b128 v[152:155], v156 offset:2048
	ds_read_b128 v[156:159], v156 offset:3072
	s_add_u32 s26, s72, 0x40000
	s_addc_u32 s27, s73, 0
	s_mov_b32 m0, s30
	ds_read_b128 v[160:163], v231 offset:32768
	ds_read_b128 v[164:167], v231 offset:33792
	ds_read_b128 v[168:171], v231 offset:34816
	ds_read_b128 v[172:175], v231 offset:35840
	ds_read_b128 v[176:179], v231 offset:36864
	ds_read_b128 v[180:183], v231 offset:37888
	ds_read_b128 v[184:187], v231 offset:38912
	ds_read_b128 v[188:191], v231 offset:39936
	global_load_lds_dwordx4 v192, s[26:27]
	s_mov_b32 m0, s31
	s_nop 0
	global_load_lds_dwordx4 v196, s[26:27]
	s_waitcnt vmcnt(8) lgkmcnt(0)
	s_barrier
	v_mfma_f32_16x16x32_bf16 v[140:143], v[104:107], v[160:163], v[140:143]
	v_mfma_f32_16x16x32_bf16 v[136:139], v[128:131], v[160:163], v[136:139]
	v_mfma_f32_16x16x32_bf16 v[116:119], v[104:107], v[168:171], v[116:119]
	v_mfma_f32_16x16x32_bf16 v[112:115], v[128:131], v[168:171], v[112:115]
	v_mfma_f32_16x16x32_bf16 v[92:95], v[104:107], v[176:179], v[92:95]
	v_mfma_f32_16x16x32_bf16 v[88:91], v[128:131], v[176:179], v[88:91]
	v_mfma_f32_16x16x32_bf16 v[76:79], v[104:107], v[184:187], v[76:79]
	v_mfma_f32_16x16x32_bf16 v[72:75], v[128:131], v[184:187], v[72:75]
	v_mfma_f32_16x16x32_bf16 v[140:143], v[108:111], v[164:167], v[140:143]
	v_mfma_f32_16x16x32_bf16 v[136:139], v[132:135], v[164:167], v[136:139]
	v_mfma_f32_16x16x32_bf16 v[116:119], v[108:111], v[172:175], v[116:119]
	v_mfma_f32_16x16x32_bf16 v[112:115], v[132:135], v[172:175], v[112:115]
	v_mfma_f32_16x16x32_bf16 v[92:95], v[108:111], v[180:183], v[92:95]
	v_mfma_f32_16x16x32_bf16 v[88:91], v[132:135], v[180:183], v[88:91]
	v_mfma_f32_16x16x32_bf16 v[76:79], v[108:111], v[188:191], v[76:79]
	v_mfma_f32_16x16x32_bf16 v[72:75], v[132:135], v[188:191], v[72:75]
	v_mfma_f32_16x16x32_bf16 v[124:127], v[144:147], v[160:163], v[124:127]
	v_mfma_f32_16x16x32_bf16 v[120:123], v[152:155], v[160:163], v[120:123]
	v_mfma_f32_16x16x32_bf16 v[100:103], v[144:147], v[168:171], v[100:103]
	v_mfma_f32_16x16x32_bf16 v[96:99], v[152:155], v[168:171], v[96:99]
	v_mfma_f32_16x16x32_bf16 v[84:87], v[144:147], v[176:179], v[84:87]
	v_mfma_f32_16x16x32_bf16 v[80:83], v[152:155], v[176:179], v[80:83]
	v_mfma_f32_16x16x32_bf16 v[68:71], v[144:147], v[184:187], v[68:71]
	v_mfma_f32_16x16x32_bf16 v[64:67], v[152:155], v[184:187], v[64:67]
	v_mfma_f32_16x16x32_bf16 v[124:127], v[148:151], v[164:167], v[124:127]
	v_mfma_f32_16x16x32_bf16 v[120:123], v[156:159], v[164:167], v[120:123]
	v_mfma_f32_16x16x32_bf16 v[100:103], v[148:151], v[172:175], v[100:103]
	v_mfma_f32_16x16x32_bf16 v[96:99], v[156:159], v[172:175], v[96:99]
	v_mfma_f32_16x16x32_bf16 v[84:87], v[148:151], v[180:183], v[84:87]
	v_mfma_f32_16x16x32_bf16 v[80:83], v[156:159], v[180:183], v[80:83]
	v_mfma_f32_16x16x32_bf16 v[68:71], v[148:151], v[188:191], v[68:71]
	v_mfma_f32_16x16x32_bf16 v[64:67], v[156:159], v[188:191], v[64:67]
	s_barrier
	s_add_i32 s26, s77, s3
	v_lshl_add_u64 v[204:205], v[204:205], 0, s[10:11]
	s_mov_b32 m0, s26
	ds_read_b128 v[160:163], v231 offset:49152
	ds_read_b128 v[164:167], v231 offset:50176
	ds_read_b128 v[168:171], v231 offset:51200
	ds_read_b128 v[172:175], v231 offset:52224
	ds_read_b128 v[176:179], v231 offset:53248
	ds_read_b128 v[180:183], v231 offset:54272
	ds_read_b128 v[184:187], v231 offset:55296
	ds_read_b128 v[188:191], v231 offset:56320
	global_load_lds_dwordx4 v[204:205], off
	s_add_i32 m0, s26, 0x2000
	s_add_u32 s26, s70, 0x40080
	v_lshl_add_u64 v[204:205], v[206:207], 0, s[10:11]
	s_addc_u32 s27, s71, 0
	s_add_i32 s70, s92, s3
	global_load_lds_dwordx4 v[204:205], off
	s_mov_b32 m0, s70
	s_nop 0
	global_load_lds_dwordx4 v194, s[26:27]
	s_add_i32 m0, s70, 0x2000
	s_nop 0
	global_load_lds_dwordx4 v198, s[26:27]
	v_lshl_add_u64 v[204:205], v[208:209], 0, s[10:11]
	s_mov_b32 m0, s81
	s_nop 0
	global_load_lds_dwordx4 v[204:205], off
	v_lshl_add_u64 v[204:205], v[210:211], 0, s[10:11]
	s_mov_b32 m0, s82
	s_nop 0
	global_load_lds_dwordx4 v[204:205], off
	s_waitcnt vmcnt(8) lgkmcnt(0)
	s_barrier
	v_mfma_f32_16x16x32_bf16 v[60:63], v[104:107], v[160:163], v[60:63]
	v_mfma_f32_16x16x32_bf16 v[56:59], v[128:131], v[160:163], v[56:59]
	v_mfma_f32_16x16x32_bf16 v[44:47], v[104:107], v[168:171], v[44:47]
	v_mfma_f32_16x16x32_bf16 v[40:43], v[128:131], v[168:171], v[40:43]
	v_mfma_f32_16x16x32_bf16 v[28:31], v[104:107], v[176:179], v[28:31]
	v_mfma_f32_16x16x32_bf16 v[24:27], v[128:131], v[176:179], v[24:27]
	v_mfma_f32_16x16x32_bf16 v[12:15], v[104:107], v[184:187], v[12:15]
	v_mfma_f32_16x16x32_bf16 v[8:11], v[128:131], v[184:187], v[8:11]
	v_mfma_f32_16x16x32_bf16 v[60:63], v[108:111], v[164:167], v[60:63]
	v_mfma_f32_16x16x32_bf16 v[56:59], v[132:135], v[164:167], v[56:59]
	v_mfma_f32_16x16x32_bf16 v[44:47], v[108:111], v[172:175], v[44:47]
	v_mfma_f32_16x16x32_bf16 v[40:43], v[132:135], v[172:175], v[40:43]
	v_mfma_f32_16x16x32_bf16 v[28:31], v[108:111], v[180:183], v[28:31]
	v_mfma_f32_16x16x32_bf16 v[24:27], v[132:135], v[180:183], v[24:27]
	v_mfma_f32_16x16x32_bf16 v[12:15], v[108:111], v[188:191], v[12:15]
	v_mfma_f32_16x16x32_bf16 v[8:11], v[132:135], v[188:191], v[8:11]
	v_mfma_f32_16x16x32_bf16 v[52:55], v[144:147], v[160:163], v[52:55]
	v_mfma_f32_16x16x32_bf16 v[48:51], v[152:155], v[160:163], v[48:51]
	v_mfma_f32_16x16x32_bf16 v[36:39], v[144:147], v[168:171], v[36:39]
	v_mfma_f32_16x16x32_bf16 v[32:35], v[152:155], v[168:171], v[32:35]
	v_mfma_f32_16x16x32_bf16 v[20:23], v[144:147], v[176:179], v[20:23]
	v_mfma_f32_16x16x32_bf16 v[16:19], v[152:155], v[176:179], v[16:19]
	v_mfma_f32_16x16x32_bf16 v[4:7], v[144:147], v[184:187], v[4:7]
	v_mfma_f32_16x16x32_bf16 v[0:3], v[152:155], v[184:187], v[0:3]
	v_mfma_f32_16x16x32_bf16 v[52:55], v[148:151], v[164:167], v[52:55]
	v_mfma_f32_16x16x32_bf16 v[48:51], v[156:159], v[164:167], v[48:51]
	v_mfma_f32_16x16x32_bf16 v[36:39], v[148:151], v[172:175], v[36:39]
	v_mfma_f32_16x16x32_bf16 v[32:35], v[156:159], v[172:175], v[32:35]
	v_mfma_f32_16x16x32_bf16 v[20:23], v[148:151], v[180:183], v[20:23]
	v_mfma_f32_16x16x32_bf16 v[16:19], v[156:159], v[180:183], v[16:19]
	v_mfma_f32_16x16x32_bf16 v[4:7], v[148:151], v[188:191], v[4:7]
	v_mfma_f32_16x16x32_bf16 v[0:3], v[156:159], v[188:191], v[0:3]
	s_barrier
	s_add_i32 s91, s91, 2
	s_add_u32 s5, s5, 0x100
	s_addc_u32 s61, s61, 0
	s_add_u32 s68, s68, 0x100
	s_addc_u32 s69, s69, 0
.LBB0_819:
	ds_read_b128 v[104:107], v229
	ds_read_b128 v[108:111], v229 offset:1024
	ds_read_b128 v[128:131], v229 offset:2048
	ds_read_b128 v[132:135], v229 offset:3072
	ds_read_b128 v[144:147], v230
	ds_read_b128 v[148:151], v230 offset:1024
	ds_read_b128 v[152:155], v230 offset:2048
	ds_read_b128 v[156:159], v230 offset:3072
	s_add_u32 s26, s68, 0xfffc0080
	s_addc_u32 s27, s69, -1
	s_cmp_eq_u32 s91, 12
	s_cselect_b32 s73, s63, s27
	s_cselect_b32 s72, s62, s26
	s_cselect_b32 s71, s65, s61
	s_cselect_b32 s70, s64, s5
	s_add_i32 m0, s28, 0xc000
	ds_read_b128 v[160:163], v231
	ds_read_b128 v[164:167], v231 offset:1024
	ds_read_b128 v[168:171], v231 offset:2048
	ds_read_b128 v[172:175], v231 offset:3072
	ds_read_b128 v[176:179], v231 offset:4096
	ds_read_b128 v[180:183], v231 offset:5120
	ds_read_b128 v[184:187], v231 offset:6144
	ds_read_b128 v[188:191], v231 offset:7168
	global_load_lds_dwordx4 v202, s[68:69]
	s_add_i32 m0, s28, 0xe000
	s_nop 0
	global_load_lds_dwordx4 v200, s[68:69]
	s_waitcnt vmcnt(8) lgkmcnt(0)
	s_barrier
	v_mfma_f32_16x16x32_bf16 v[140:143], v[104:107], v[160:163], v[140:143]
	v_mfma_f32_16x16x32_bf16 v[136:139], v[128:131], v[160:163], v[136:139]
	v_mfma_f32_16x16x32_bf16 v[116:119], v[104:107], v[168:171], v[116:119]
	v_mfma_f32_16x16x32_bf16 v[112:115], v[128:131], v[168:171], v[112:115]
	v_mfma_f32_16x16x32_bf16 v[92:95], v[104:107], v[176:179], v[92:95]
	v_mfma_f32_16x16x32_bf16 v[88:91], v[128:131], v[176:179], v[88:91]
	v_mfma_f32_16x16x32_bf16 v[76:79], v[104:107], v[184:187], v[76:79]
	v_mfma_f32_16x16x32_bf16 v[72:75], v[128:131], v[184:187], v[72:75]
	v_mfma_f32_16x16x32_bf16 v[140:143], v[108:111], v[164:167], v[140:143]
	v_mfma_f32_16x16x32_bf16 v[136:139], v[132:135], v[164:167], v[136:139]
	v_mfma_f32_16x16x32_bf16 v[116:119], v[108:111], v[172:175], v[116:119]
	v_mfma_f32_16x16x32_bf16 v[112:115], v[132:135], v[172:175], v[112:115]
	v_mfma_f32_16x16x32_bf16 v[92:95], v[108:111], v[180:183], v[92:95]
	v_mfma_f32_16x16x32_bf16 v[88:91], v[132:135], v[180:183], v[88:91]
	v_mfma_f32_16x16x32_bf16 v[76:79], v[108:111], v[188:191], v[76:79]
	v_mfma_f32_16x16x32_bf16 v[72:75], v[132:135], v[188:191], v[72:75]
	v_mfma_f32_16x16x32_bf16 v[124:127], v[144:147], v[160:163], v[124:127]
	v_mfma_f32_16x16x32_bf16 v[120:123], v[152:155], v[160:163], v[120:123]
	v_mfma_f32_16x16x32_bf16 v[100:103], v[144:147], v[168:171], v[100:103]
	v_mfma_f32_16x16x32_bf16 v[96:99], v[152:155], v[168:171], v[96:99]
	v_mfma_f32_16x16x32_bf16 v[84:87], v[144:147], v[176:179], v[84:87]
	v_mfma_f32_16x16x32_bf16 v[80:83], v[152:155], v[176:179], v[80:83]
	v_mfma_f32_16x16x32_bf16 v[68:71], v[144:147], v[184:187], v[68:71]
	v_mfma_f32_16x16x32_bf16 v[64:67], v[152:155], v[184:187], v[64:67]
	v_mfma_f32_16x16x32_bf16 v[124:127], v[148:151], v[164:167], v[124:127]
	v_mfma_f32_16x16x32_bf16 v[120:123], v[156:159], v[164:167], v[120:123]
	v_mfma_f32_16x16x32_bf16 v[100:103], v[148:151], v[172:175], v[100:103]
	v_mfma_f32_16x16x32_bf16 v[96:99], v[156:159], v[172:175], v[96:99]
	v_mfma_f32_16x16x32_bf16 v[84:87], v[148:151], v[180:183], v[84:87]
	v_mfma_f32_16x16x32_bf16 v[80:83], v[156:159], v[180:183], v[80:83]
	v_mfma_f32_16x16x32_bf16 v[68:71], v[148:151], v[188:191], v[68:71]
	v_mfma_f32_16x16x32_bf16 v[64:67], v[156:159], v[188:191], v[64:67]
	s_barrier
	s_add_i32 s26, s83, s3
	v_lshl_add_u64 v[204:205], s[70:71], 0, v[194:195]
	s_mov_b32 m0, s26
	ds_read_b128 v[160:163], v231 offset:16384
	ds_read_b128 v[164:167], v231 offset:17408
	ds_read_b128 v[168:171], v231 offset:18432
	ds_read_b128 v[172:175], v231 offset:19456
	ds_read_b128 v[176:179], v231 offset:20480
	ds_read_b128 v[180:183], v231 offset:21504
	ds_read_b128 v[184:187], v231 offset:22528
	ds_read_b128 v[188:191], v231 offset:23552
	global_load_lds_dwordx4 v[204:205], off
	s_add_i32 m0, s26, 0x2000
	s_add_u32 s26, s70, 0x40000
	v_lshl_add_u64 v[206:207], s[70:71], 0, v[198:199]
	s_addc_u32 s27, s71, 0
	s_add_i32 s77, s84, s3
	global_load_lds_dwordx4 v[206:207], off
	s_mov_b32 m0, s77
	v_lshl_add_u64 v[210:211], s[72:73], 0, v[196:197]
	global_load_lds_dwordx4 v194, s[26:27]
	s_add_i32 m0, s77, 0x2000
	s_nop 0
	global_load_lds_dwordx4 v198, s[26:27]
	v_lshl_add_u64 v[208:209], s[72:73], 0, v[192:193]
	s_mov_b32 m0, s28
	s_nop 0
	global_load_lds_dwordx4 v[208:209], off
	s_mov_b32 m0, s29
	s_nop 0
	global_load_lds_dwordx4 v[210:211], off
	s_waitcnt vmcnt(8) lgkmcnt(0)
	s_barrier
	v_mfma_f32_16x16x32_bf16 v[60:63], v[104:107], v[160:163], v[60:63]
	v_mfma_f32_16x16x32_bf16 v[56:59], v[128:131], v[160:163], v[56:59]
	v_mfma_f32_16x16x32_bf16 v[44:47], v[104:107], v[168:171], v[44:47]
	v_mfma_f32_16x16x32_bf16 v[40:43], v[128:131], v[168:171], v[40:43]
	v_mfma_f32_16x16x32_bf16 v[28:31], v[104:107], v[176:179], v[28:31]
	v_mfma_f32_16x16x32_bf16 v[24:27], v[128:131], v[176:179], v[24:27]
	v_mfma_f32_16x16x32_bf16 v[12:15], v[104:107], v[184:187], v[12:15]
	v_mfma_f32_16x16x32_bf16 v[8:11], v[128:131], v[184:187], v[8:11]
	v_mfma_f32_16x16x32_bf16 v[60:63], v[108:111], v[164:167], v[60:63]
	v_mfma_f32_16x16x32_bf16 v[56:59], v[132:135], v[164:167], v[56:59]
	v_mfma_f32_16x16x32_bf16 v[44:47], v[108:111], v[172:175], v[44:47]
	v_mfma_f32_16x16x32_bf16 v[40:43], v[132:135], v[172:175], v[40:43]
	v_mfma_f32_16x16x32_bf16 v[28:31], v[108:111], v[180:183], v[28:31]
	v_mfma_f32_16x16x32_bf16 v[24:27], v[132:135], v[180:183], v[24:27]
	v_mfma_f32_16x16x32_bf16 v[12:15], v[108:111], v[188:191], v[12:15]
	v_mfma_f32_16x16x32_bf16 v[8:11], v[132:135], v[188:191], v[8:11]
	v_mfma_f32_16x16x32_bf16 v[52:55], v[144:147], v[160:163], v[52:55]
	v_mfma_f32_16x16x32_bf16 v[48:51], v[152:155], v[160:163], v[48:51]
	v_mfma_f32_16x16x32_bf16 v[36:39], v[144:147], v[168:171], v[36:39]
	v_mfma_f32_16x16x32_bf16 v[32:35], v[152:155], v[168:171], v[32:35]
	v_mfma_f32_16x16x32_bf16 v[20:23], v[144:147], v[176:179], v[20:23]
	v_mfma_f32_16x16x32_bf16 v[16:19], v[152:155], v[176:179], v[16:19]
	v_mfma_f32_16x16x32_bf16 v[4:7], v[144:147], v[184:187], v[4:7]
	v_mfma_f32_16x16x32_bf16 v[0:3], v[152:155], v[184:187], v[0:3]
	v_mfma_f32_16x16x32_bf16 v[52:55], v[148:151], v[164:167], v[52:55]
	v_mfma_f32_16x16x32_bf16 v[48:51], v[156:159], v[164:167], v[48:51]
	v_mfma_f32_16x16x32_bf16 v[36:39], v[148:151], v[172:175], v[36:39]
	v_mfma_f32_16x16x32_bf16 v[32:35], v[156:159], v[172:175], v[32:35]
	v_mfma_f32_16x16x32_bf16 v[20:23], v[148:151], v[180:183], v[20:23]
	v_mfma_f32_16x16x32_bf16 v[16:19], v[156:159], v[180:183], v[16:19]
	v_mfma_f32_16x16x32_bf16 v[4:7], v[148:151], v[188:191], v[4:7]
	v_mfma_f32_16x16x32_bf16 v[0:3], v[156:159], v[188:191], v[0:3]
	s_barrier
	s_add_i32 s77, 0, 0x18000
	s_add_i32 s92, 0, 0x1c000
	v_add_u32_e32 v132, s77, v228
	v_add_u32_e32 v156, s92, v228
	ds_read_b128 v[104:107], v132
	ds_read_b128 v[108:111], v132 offset:1024
	ds_read_b128 v[128:131], v132 offset:2048
	ds_read_b128 v[132:135], v132 offset:3072
	ds_read_b128 v[144:147], v156
	ds_read_b128 v[148:151], v156 offset:1024
	ds_read_b128 v[152:155], v156 offset:2048
	ds_read_b128 v[156:159], v156 offset:3072
	s_add_u32 s26, s72, 0x40000
	s_addc_u32 s27, s73, 0
	s_mov_b32 m0, s30
	ds_read_b128 v[160:163], v231 offset:32768
	ds_read_b128 v[164:167], v231 offset:33792
	ds_read_b128 v[168:171], v231 offset:34816
	ds_read_b128 v[172:175], v231 offset:35840
	ds_read_b128 v[176:179], v231 offset:36864
	ds_read_b128 v[180:183], v231 offset:37888
	ds_read_b128 v[184:187], v231 offset:38912
	ds_read_b128 v[188:191], v231 offset:39936
	global_load_lds_dwordx4 v192, s[26:27]
	s_mov_b32 m0, s31
	s_nop 0
	global_load_lds_dwordx4 v196, s[26:27]
	s_waitcnt vmcnt(8) lgkmcnt(0)
	s_barrier
	v_mfma_f32_16x16x32_bf16 v[140:143], v[104:107], v[160:163], v[140:143]
	v_mfma_f32_16x16x32_bf16 v[136:139], v[128:131], v[160:163], v[136:139]
	v_mfma_f32_16x16x32_bf16 v[116:119], v[104:107], v[168:171], v[116:119]
	v_mfma_f32_16x16x32_bf16 v[112:115], v[128:131], v[168:171], v[112:115]
	v_mfma_f32_16x16x32_bf16 v[92:95], v[104:107], v[176:179], v[92:95]
	v_mfma_f32_16x16x32_bf16 v[88:91], v[128:131], v[176:179], v[88:91]
	v_mfma_f32_16x16x32_bf16 v[76:79], v[104:107], v[184:187], v[76:79]
	v_mfma_f32_16x16x32_bf16 v[72:75], v[128:131], v[184:187], v[72:75]
	v_mfma_f32_16x16x32_bf16 v[140:143], v[108:111], v[164:167], v[140:143]
	v_mfma_f32_16x16x32_bf16 v[136:139], v[132:135], v[164:167], v[136:139]
	v_mfma_f32_16x16x32_bf16 v[116:119], v[108:111], v[172:175], v[116:119]
	v_mfma_f32_16x16x32_bf16 v[112:115], v[132:135], v[172:175], v[112:115]
	v_mfma_f32_16x16x32_bf16 v[92:95], v[108:111], v[180:183], v[92:95]
	v_mfma_f32_16x16x32_bf16 v[88:91], v[132:135], v[180:183], v[88:91]
	v_mfma_f32_16x16x32_bf16 v[76:79], v[108:111], v[188:191], v[76:79]
	v_mfma_f32_16x16x32_bf16 v[72:75], v[132:135], v[188:191], v[72:75]
	v_mfma_f32_16x16x32_bf16 v[124:127], v[144:147], v[160:163], v[124:127]
	v_mfma_f32_16x16x32_bf16 v[120:123], v[152:155], v[160:163], v[120:123]
	v_mfma_f32_16x16x32_bf16 v[100:103], v[144:147], v[168:171], v[100:103]
	v_mfma_f32_16x16x32_bf16 v[96:99], v[152:155], v[168:171], v[96:99]
	v_mfma_f32_16x16x32_bf16 v[84:87], v[144:147], v[176:179], v[84:87]
	v_mfma_f32_16x16x32_bf16 v[80:83], v[152:155], v[176:179], v[80:83]
	v_mfma_f32_16x16x32_bf16 v[68:71], v[144:147], v[184:187], v[68:71]
	v_mfma_f32_16x16x32_bf16 v[64:67], v[152:155], v[184:187], v[64:67]
	v_mfma_f32_16x16x32_bf16 v[124:127], v[148:151], v[164:167], v[124:127]
	v_mfma_f32_16x16x32_bf16 v[120:123], v[156:159], v[164:167], v[120:123]
	v_mfma_f32_16x16x32_bf16 v[100:103], v[148:151], v[172:175], v[100:103]
	v_mfma_f32_16x16x32_bf16 v[96:99], v[156:159], v[172:175], v[96:99]
	v_mfma_f32_16x16x32_bf16 v[84:87], v[148:151], v[180:183], v[84:87]
	v_mfma_f32_16x16x32_bf16 v[80:83], v[156:159], v[180:183], v[80:83]
	v_mfma_f32_16x16x32_bf16 v[68:71], v[148:151], v[188:191], v[68:71]
	v_mfma_f32_16x16x32_bf16 v[64:67], v[156:159], v[188:191], v[64:67]
	s_barrier
	s_add_i32 s26, s77, s3
	v_lshl_add_u64 v[204:205], v[204:205], 0, s[10:11]
	s_mov_b32 m0, s26
	ds_read_b128 v[160:163], v231 offset:49152
	ds_read_b128 v[164:167], v231 offset:50176
	ds_read_b128 v[168:171], v231 offset:51200
	ds_read_b128 v[172:175], v231 offset:52224
	ds_read_b128 v[176:179], v231 offset:53248
	ds_read_b128 v[180:183], v231 offset:54272
	ds_read_b128 v[184:187], v231 offset:55296
	ds_read_b128 v[188:191], v231 offset:56320
	global_load_lds_dwordx4 v[204:205], off
	s_add_i32 m0, s26, 0x2000
	s_add_u32 s26, s70, 0x40080
	v_lshl_add_u64 v[204:205], v[206:207], 0, s[10:11]
	s_addc_u32 s27, s71, 0
	s_add_i32 s70, s92, s3
	global_load_lds_dwordx4 v[204:205], off
	s_mov_b32 m0, s70
	s_nop 0
	global_load_lds_dwordx4 v194, s[26:27]
	s_add_i32 m0, s70, 0x2000
	s_nop 0
	global_load_lds_dwordx4 v198, s[26:27]
	v_lshl_add_u64 v[204:205], v[208:209], 0, s[10:11]
	s_mov_b32 m0, s81
	s_nop 0
	global_load_lds_dwordx4 v[204:205], off
	v_lshl_add_u64 v[204:205], v[210:211], 0, s[10:11]
	s_mov_b32 m0, s82
	s_nop 0
	global_load_lds_dwordx4 v[204:205], off
	s_waitcnt vmcnt(8) lgkmcnt(0)
	s_barrier
	v_mfma_f32_16x16x32_bf16 v[60:63], v[104:107], v[160:163], v[60:63]
	v_mfma_f32_16x16x32_bf16 v[56:59], v[128:131], v[160:163], v[56:59]
	v_mfma_f32_16x16x32_bf16 v[44:47], v[104:107], v[168:171], v[44:47]
	v_mfma_f32_16x16x32_bf16 v[40:43], v[128:131], v[168:171], v[40:43]
	v_mfma_f32_16x16x32_bf16 v[28:31], v[104:107], v[176:179], v[28:31]
	v_mfma_f32_16x16x32_bf16 v[24:27], v[128:131], v[176:179], v[24:27]
	v_mfma_f32_16x16x32_bf16 v[12:15], v[104:107], v[184:187], v[12:15]
	v_mfma_f32_16x16x32_bf16 v[8:11], v[128:131], v[184:187], v[8:11]
	v_mfma_f32_16x16x32_bf16 v[60:63], v[108:111], v[164:167], v[60:63]
	v_mfma_f32_16x16x32_bf16 v[56:59], v[132:135], v[164:167], v[56:59]
	v_mfma_f32_16x16x32_bf16 v[44:47], v[108:111], v[172:175], v[44:47]
	v_mfma_f32_16x16x32_bf16 v[40:43], v[132:135], v[172:175], v[40:43]
	v_mfma_f32_16x16x32_bf16 v[28:31], v[108:111], v[180:183], v[28:31]
	v_mfma_f32_16x16x32_bf16 v[24:27], v[132:135], v[180:183], v[24:27]
	v_mfma_f32_16x16x32_bf16 v[12:15], v[108:111], v[188:191], v[12:15]
	v_mfma_f32_16x16x32_bf16 v[8:11], v[132:135], v[188:191], v[8:11]
	v_mfma_f32_16x16x32_bf16 v[52:55], v[144:147], v[160:163], v[52:55]
	v_mfma_f32_16x16x32_bf16 v[48:51], v[152:155], v[160:163], v[48:51]
	v_mfma_f32_16x16x32_bf16 v[36:39], v[144:147], v[168:171], v[36:39]
	v_mfma_f32_16x16x32_bf16 v[32:35], v[152:155], v[168:171], v[32:35]
	v_mfma_f32_16x16x32_bf16 v[20:23], v[144:147], v[176:179], v[20:23]
	v_mfma_f32_16x16x32_bf16 v[16:19], v[152:155], v[176:179], v[16:19]
	v_mfma_f32_16x16x32_bf16 v[4:7], v[144:147], v[184:187], v[4:7]
	v_mfma_f32_16x16x32_bf16 v[0:3], v[152:155], v[184:187], v[0:3]
	v_mfma_f32_16x16x32_bf16 v[52:55], v[148:151], v[164:167], v[52:55]
	v_mfma_f32_16x16x32_bf16 v[48:51], v[156:159], v[164:167], v[48:51]
	v_mfma_f32_16x16x32_bf16 v[36:39], v[148:151], v[172:175], v[36:39]
	v_mfma_f32_16x16x32_bf16 v[32:35], v[156:159], v[172:175], v[32:35]
	v_mfma_f32_16x16x32_bf16 v[20:23], v[148:151], v[180:183], v[20:23]
	v_mfma_f32_16x16x32_bf16 v[16:19], v[156:159], v[180:183], v[16:19]
	v_mfma_f32_16x16x32_bf16 v[4:7], v[148:151], v[188:191], v[4:7]
	v_mfma_f32_16x16x32_bf16 v[0:3], v[156:159], v[188:191], v[0:3]
	s_barrier
	s_add_i32 s91, s91, 2
	s_add_u32 s5, s5, 0x100
	s_addc_u32 s61, s61, 0
	s_add_u32 s68, s68, 0x100
	s_addc_u32 s69, s69, 0
	s_cmp_gt_u32 s91, 13
	s_cbranch_scc0 .LBB0_819
	s_and_b64 vcc, exec, s[8:9]
	s_cbranch_vccz .LBB0_822
	s_barrier

.LBB0_952:
	s_add_u32 s7, s10, 0x100
	s_addc_u32 s31, s11, 0
	s_add_u32 s8, s8, 0x40080
	v_mov_b32_e32 v2, 0
	s_addc_u32 s9, s9, 0
	s_mov_b32 s51, -2
	ds_read_b128 v[130:133], v167
	ds_read_b128 v[134:137], v167 offset:1024
	ds_read_b128 v[138:141], v167 offset:2048
	ds_read_b128 v[142:145], v167 offset:3072
	ds_read_b128 v[160:163], v168
	ds_read_b128 v[172:175], v168 offset:1024
	ds_read_b128 v[176:179], v168 offset:2048
	ds_read_b128 v[180:183], v168 offset:3072
	s_add_u32 s10, s8, 0xfffc0080
	s_addc_u32 s11, s9, -1
	s_cmp_eq_u32 s51, 12
	s_cselect_b32 s59, s53, s11
	s_cselect_b32 s58, s52, s10
	s_cselect_b32 s11, s57, s31
	s_cselect_b32 s10, s56, s7
	s_add_i32 m0, s84, 0xc000
	ds_read_b128 v[184:187], v169
	ds_read_b128 v[188:191], v169 offset:1024
	ds_read_b128 v[192:195], v169 offset:2048
	ds_read_b128 v[196:199], v169 offset:3072
	ds_read_b128 v[200:203], v169 offset:4096
	ds_read_b128 v[204:207], v169 offset:5120
	ds_read_b128 v[208:211], v169 offset:6144
	ds_read_b128 v[212:215], v169 offset:7168
	global_load_lds_dwordx4 v158, s[8:9]
	s_add_i32 m0, s84, 0xe000
	s_nop 0
	global_load_lds_dwordx4 v156, s[8:9]
	s_waitcnt vmcnt(8) lgkmcnt(0)
	s_barrier
	v_mfma_f32_16x16x32_bf16 v[126:129], v[130:133], v[184:187], 0
	v_mfma_f32_16x16x32_bf16 v[122:125], v[138:141], v[184:187], 0
	v_mfma_f32_16x16x32_bf16 v[110:113], v[130:133], v[192:195], 0
	v_mfma_f32_16x16x32_bf16 v[106:109], v[138:141], v[192:195], 0
	v_mfma_f32_16x16x32_bf16 v[94:97], v[130:133], v[200:203], 0
	v_mfma_f32_16x16x32_bf16 v[90:93], v[138:141], v[200:203], 0
	v_mfma_f32_16x16x32_bf16 v[78:81], v[130:133], v[208:211], 0
	v_mfma_f32_16x16x32_bf16 v[74:77], v[138:141], v[208:211], 0
	v_mfma_f32_16x16x32_bf16 v[126:129], v[134:137], v[188:191], v[126:129]
	v_mfma_f32_16x16x32_bf16 v[122:125], v[142:145], v[188:191], v[122:125]
	v_mfma_f32_16x16x32_bf16 v[110:113], v[134:137], v[196:199], v[110:113]
	v_mfma_f32_16x16x32_bf16 v[106:109], v[142:145], v[196:199], v[106:109]
	v_mfma_f32_16x16x32_bf16 v[94:97], v[134:137], v[204:207], v[94:97]
	v_mfma_f32_16x16x32_bf16 v[90:93], v[142:145], v[204:207], v[90:93]
	v_mfma_f32_16x16x32_bf16 v[78:81], v[134:137], v[212:215], v[78:81]
	v_mfma_f32_16x16x32_bf16 v[74:77], v[142:145], v[212:215], v[74:77]
	v_mfma_f32_16x16x32_bf16 v[118:121], v[160:163], v[184:187], 0
	v_mfma_f32_16x16x32_bf16 v[114:117], v[176:179], v[184:187], 0
	v_mfma_f32_16x16x32_bf16 v[102:105], v[160:163], v[192:195], 0
	v_mfma_f32_16x16x32_bf16 v[98:101], v[176:179], v[192:195], 0
	v_mfma_f32_16x16x32_bf16 v[86:89], v[160:163], v[200:203], 0
	v_mfma_f32_16x16x32_bf16 v[82:85], v[176:179], v[200:203], 0
	v_mfma_f32_16x16x32_bf16 v[70:73], v[160:163], v[208:211], 0
	v_mfma_f32_16x16x32_bf16 v[66:69], v[176:179], v[208:211], 0
	v_mfma_f32_16x16x32_bf16 v[118:121], v[172:175], v[188:191], v[118:121]
	v_mfma_f32_16x16x32_bf16 v[114:117], v[180:183], v[188:191], v[114:117]
	v_mfma_f32_16x16x32_bf16 v[102:105], v[172:175], v[196:199], v[102:105]
	v_mfma_f32_16x16x32_bf16 v[98:101], v[180:183], v[196:199], v[98:101]
	v_mfma_f32_16x16x32_bf16 v[86:89], v[172:175], v[204:207], v[86:89]
	v_mfma_f32_16x16x32_bf16 v[82:85], v[180:183], v[204:207], v[82:85]
	v_mfma_f32_16x16x32_bf16 v[70:73], v[172:175], v[212:215], v[70:73]
	v_mfma_f32_16x16x32_bf16 v[66:69], v[180:183], v[212:215], v[66:69]
	s_barrier
	s_add_i32 s26, s94, s39
	v_lshl_add_u64 v[164:165], s[10:11], 0, v[148:149]
	s_mov_b32 m0, s26
	ds_read_b128 v[184:187], v169 offset:16384
	ds_read_b128 v[188:191], v169 offset:17408
	ds_read_b128 v[192:195], v169 offset:18432
	ds_read_b128 v[196:199], v169 offset:19456
	ds_read_b128 v[200:203], v169 offset:20480
	ds_read_b128 v[204:207], v169 offset:21504
	ds_read_b128 v[208:211], v169 offset:22528
	ds_read_b128 v[212:215], v169 offset:23552
	global_load_lds_dwordx4 v[164:165], off
	s_add_i32 m0, s26, 0x2000
	s_add_u32 s26, s10, 0x40000
	v_lshl_add_u64 v[216:217], s[10:11], 0, v[152:153]
	s_addc_u32 s27, s11, 0
	s_add_i32 s60, s95, s39
	global_load_lds_dwordx4 v[216:217], off
	s_mov_b32 m0, s60
	v_lshl_add_u64 v[220:221], s[58:59], 0, v[150:151]
	global_load_lds_dwordx4 v148, s[26:27]
	s_add_i32 m0, s60, 0x2000
	s_nop 0
	global_load_lds_dwordx4 v152, s[26:27]
	v_lshl_add_u64 v[218:219], s[58:59], 0, v[146:147]
	s_mov_b32 m0, s84
	s_nop 0
	global_load_lds_dwordx4 v[218:219], off
	s_mov_b32 m0, s85
	s_nop 0
	global_load_lds_dwordx4 v[220:221], off
	s_waitcnt vmcnt(8) lgkmcnt(0)
	s_barrier
	v_mfma_f32_16x16x32_bf16 v[62:65], v[130:133], v[184:187], 0
	v_mfma_f32_16x16x32_bf16 v[58:61], v[138:141], v[184:187], 0
	v_mfma_f32_16x16x32_bf16 v[46:49], v[130:133], v[192:195], 0
	v_mfma_f32_16x16x32_bf16 v[42:45], v[138:141], v[192:195], 0
	v_mfma_f32_16x16x32_bf16 v[30:33], v[130:133], v[200:203], 0
	v_mfma_f32_16x16x32_bf16 v[26:29], v[138:141], v[200:203], 0
	v_mfma_f32_16x16x32_bf16 v[14:17], v[130:133], v[208:211], 0
	v_mfma_f32_16x16x32_bf16 v[10:13], v[138:141], v[208:211], 0
	v_mfma_f32_16x16x32_bf16 v[62:65], v[134:137], v[188:191], v[62:65]
	v_mfma_f32_16x16x32_bf16 v[58:61], v[142:145], v[188:191], v[58:61]
	v_mfma_f32_16x16x32_bf16 v[46:49], v[134:137], v[196:199], v[46:49]
	v_mfma_f32_16x16x32_bf16 v[42:45], v[142:145], v[196:199], v[42:45]
	v_mfma_f32_16x16x32_bf16 v[30:33], v[134:137], v[204:207], v[30:33]
	v_mfma_f32_16x16x32_bf16 v[26:29], v[142:145], v[204:207], v[26:29]
	v_mfma_f32_16x16x32_bf16 v[14:17], v[134:137], v[212:215], v[14:17]
	v_mfma_f32_16x16x32_bf16 v[10:13], v[142:145], v[212:215], v[10:13]
	v_mfma_f32_16x16x32_bf16 v[54:57], v[160:163], v[184:187], 0
	v_mfma_f32_16x16x32_bf16 v[50:53], v[176:179], v[184:187], 0
	v_mfma_f32_16x16x32_bf16 v[38:41], v[160:163], v[192:195], 0
	v_mfma_f32_16x16x32_bf16 v[34:37], v[176:179], v[192:195], 0
	v_mfma_f32_16x16x32_bf16 v[22:25], v[160:163], v[200:203], 0
	v_mfma_f32_16x16x32_bf16 v[18:21], v[176:179], v[200:203], 0
	v_mfma_f32_16x16x32_bf16 v[6:9], v[160:163], v[208:211], 0
	v_mfma_f32_16x16x32_bf16 v[2:5], v[176:179], v[208:211], 0
	v_mfma_f32_16x16x32_bf16 v[54:57], v[172:175], v[188:191], v[54:57]
	v_mfma_f32_16x16x32_bf16 v[50:53], v[180:183], v[188:191], v[50:53]
	v_mfma_f32_16x16x32_bf16 v[38:41], v[172:175], v[196:199], v[38:41]
	v_mfma_f32_16x16x32_bf16 v[34:37], v[180:183], v[196:199], v[34:37]
	v_mfma_f32_16x16x32_bf16 v[22:25], v[172:175], v[204:207], v[22:25]
	v_mfma_f32_16x16x32_bf16 v[18:21], v[180:183], v[204:207], v[18:21]
	v_mfma_f32_16x16x32_bf16 v[6:9], v[172:175], v[212:215], v[6:9]
	v_mfma_f32_16x16x32_bf16 v[2:5], v[180:183], v[212:215], v[2:5]
	s_barrier
	s_add_i32 s60, 0, 0x18000
	v_add_u32_e32 v1, s60, v166
	s_add_i32 s61, 0, 0x1c000
	ds_read_b128 v[130:133], v1
	ds_read_b128 v[134:137], v1 offset:1024
	ds_read_b128 v[138:141], v1 offset:2048
	ds_read_b128 v[142:145], v1 offset:3072
	v_add_u32_e32 v1, s61, v166
	ds_read_b128 v[160:163], v1
	ds_read_b128 v[172:175], v1 offset:1024
	ds_read_b128 v[176:179], v1 offset:2048
	ds_read_b128 v[180:183], v1 offset:3072
	s_add_u32 s26, s58, 0x40000
	s_addc_u32 s27, s59, 0
	s_mov_b32 m0, s86
	ds_read_b128 v[184:187], v169 offset:32768
	ds_read_b128 v[188:191], v169 offset:33792
	ds_read_b128 v[192:195], v169 offset:34816
	ds_read_b128 v[196:199], v169 offset:35840
	ds_read_b128 v[200:203], v169 offset:36864
	ds_read_b128 v[204:207], v169 offset:37888
	ds_read_b128 v[208:211], v169 offset:38912
	ds_read_b128 v[212:215], v169 offset:39936
	global_load_lds_dwordx4 v146, s[26:27]
	s_mov_b32 m0, s87
	s_nop 0
	global_load_lds_dwordx4 v150, s[26:27]
	s_waitcnt vmcnt(8) lgkmcnt(0)
	s_barrier
	v_mfma_f32_16x16x32_bf16 v[126:129], v[130:133], v[184:187], v[126:129]
	v_mfma_f32_16x16x32_bf16 v[122:125], v[138:141], v[184:187], v[122:125]
	v_mfma_f32_16x16x32_bf16 v[110:113], v[130:133], v[192:195], v[110:113]
	v_mfma_f32_16x16x32_bf16 v[106:109], v[138:141], v[192:195], v[106:109]
	v_mfma_f32_16x16x32_bf16 v[94:97], v[130:133], v[200:203], v[94:97]
	v_mfma_f32_16x16x32_bf16 v[90:93], v[138:141], v[200:203], v[90:93]
	v_mfma_f32_16x16x32_bf16 v[78:81], v[130:133], v[208:211], v[78:81]
	v_mfma_f32_16x16x32_bf16 v[74:77], v[138:141], v[208:211], v[74:77]
	v_mfma_f32_16x16x32_bf16 v[126:129], v[134:137], v[188:191], v[126:129]
	v_mfma_f32_16x16x32_bf16 v[122:125], v[142:145], v[188:191], v[122:125]
	v_mfma_f32_16x16x32_bf16 v[110:113], v[134:137], v[196:199], v[110:113]
	v_mfma_f32_16x16x32_bf16 v[106:109], v[142:145], v[196:199], v[106:109]
	v_mfma_f32_16x16x32_bf16 v[94:97], v[134:137], v[204:207], v[94:97]
	v_mfma_f32_16x16x32_bf16 v[90:93], v[142:145], v[204:207], v[90:93]
	v_mfma_f32_16x16x32_bf16 v[78:81], v[134:137], v[212:215], v[78:81]
	v_mfma_f32_16x16x32_bf16 v[74:77], v[142:145], v[212:215], v[74:77]
	v_mfma_f32_16x16x32_bf16 v[118:121], v[160:163], v[184:187], v[118:121]
	v_mfma_f32_16x16x32_bf16 v[114:117], v[176:179], v[184:187], v[114:117]
	v_mfma_f32_16x16x32_bf16 v[102:105], v[160:163], v[192:195], v[102:105]
	v_mfma_f32_16x16x32_bf16 v[98:101], v[176:179], v[192:195], v[98:101]
	v_mfma_f32_16x16x32_bf16 v[86:89], v[160:163], v[200:203], v[86:89]
	v_mfma_f32_16x16x32_bf16 v[82:85], v[176:179], v[200:203], v[82:85]
	v_mfma_f32_16x16x32_bf16 v[70:73], v[160:163], v[208:211], v[70:73]
	v_mfma_f32_16x16x32_bf16 v[66:69], v[176:179], v[208:211], v[66:69]
	v_mfma_f32_16x16x32_bf16 v[118:121], v[172:175], v[188:191], v[118:121]
	v_mfma_f32_16x16x32_bf16 v[114:117], v[180:183], v[188:191], v[114:117]
	v_mfma_f32_16x16x32_bf16 v[102:105], v[172:175], v[196:199], v[102:105]
	v_mfma_f32_16x16x32_bf16 v[98:101], v[180:183], v[196:199], v[98:101]
	v_mfma_f32_16x16x32_bf16 v[86:89], v[172:175], v[204:207], v[86:89]
	v_mfma_f32_16x16x32_bf16 v[82:85], v[180:183], v[204:207], v[82:85]
	v_mfma_f32_16x16x32_bf16 v[70:73], v[172:175], v[212:215], v[70:73]
	v_mfma_f32_16x16x32_bf16 v[66:69], v[180:183], v[212:215], v[66:69]
	s_barrier
	s_add_i32 s26, s60, s39
	v_lshl_add_u64 v[164:165], v[164:165], 0, s[18:19]
	s_mov_b32 m0, s26
	ds_read_b128 v[184:187], v169 offset:49152
	ds_read_b128 v[188:191], v169 offset:50176
	ds_read_b128 v[192:195], v169 offset:51200
	ds_read_b128 v[196:199], v169 offset:52224
	ds_read_b128 v[200:203], v169 offset:53248
	ds_read_b128 v[204:207], v169 offset:54272
	ds_read_b128 v[208:211], v169 offset:55296
	ds_read_b128 v[212:215], v169 offset:56320
	global_load_lds_dwordx4 v[164:165], off
	s_add_i32 m0, s26, 0x2000
	s_add_u32 s10, s10, 0x40080
	v_lshl_add_u64 v[164:165], v[216:217], 0, s[18:19]
	s_addc_u32 s11, s11, 0
	s_add_i32 s26, s61, s39
	global_load_lds_dwordx4 v[164:165], off
	s_mov_b32 m0, s26
	s_nop 0
	global_load_lds_dwordx4 v148, s[10:11]
	s_add_i32 m0, s26, 0x2000
	s_nop 0
	global_load_lds_dwordx4 v152, s[10:11]
	v_lshl_add_u64 v[164:165], v[218:219], 0, s[18:19]
	s_mov_b32 m0, s91
	s_nop 0
	global_load_lds_dwordx4 v[164:165], off
	v_lshl_add_u64 v[164:165], v[220:221], 0, s[18:19]
	s_mov_b32 m0, s92
	s_nop 0
	global_load_lds_dwordx4 v[164:165], off
	s_waitcnt vmcnt(8) lgkmcnt(0)
	s_barrier
	v_mfma_f32_16x16x32_bf16 v[62:65], v[130:133], v[184:187], v[62:65]
	v_mfma_f32_16x16x32_bf16 v[58:61], v[138:141], v[184:187], v[58:61]
	v_mfma_f32_16x16x32_bf16 v[46:49], v[130:133], v[192:195], v[46:49]
	v_mfma_f32_16x16x32_bf16 v[42:45], v[138:141], v[192:195], v[42:45]
	v_mfma_f32_16x16x32_bf16 v[30:33], v[130:133], v[200:203], v[30:33]
	v_mfma_f32_16x16x32_bf16 v[26:29], v[138:141], v[200:203], v[26:29]
	v_mfma_f32_16x16x32_bf16 v[14:17], v[130:133], v[208:211], v[14:17]
	v_mfma_f32_16x16x32_bf16 v[10:13], v[138:141], v[208:211], v[10:13]
	v_mfma_f32_16x16x32_bf16 v[62:65], v[134:137], v[188:191], v[62:65]
	v_mfma_f32_16x16x32_bf16 v[58:61], v[142:145], v[188:191], v[58:61]
	v_mfma_f32_16x16x32_bf16 v[46:49], v[134:137], v[196:199], v[46:49]
	v_mfma_f32_16x16x32_bf16 v[42:45], v[142:145], v[196:199], v[42:45]
	v_mfma_f32_16x16x32_bf16 v[30:33], v[134:137], v[204:207], v[30:33]
	v_mfma_f32_16x16x32_bf16 v[26:29], v[142:145], v[204:207], v[26:29]
	v_mfma_f32_16x16x32_bf16 v[14:17], v[134:137], v[212:215], v[14:17]
	v_mfma_f32_16x16x32_bf16 v[10:13], v[142:145], v[212:215], v[10:13]
	v_mfma_f32_16x16x32_bf16 v[54:57], v[160:163], v[184:187], v[54:57]
	v_mfma_f32_16x16x32_bf16 v[50:53], v[176:179], v[184:187], v[50:53]
	v_mfma_f32_16x16x32_bf16 v[38:41], v[160:163], v[192:195], v[38:41]
	v_mfma_f32_16x16x32_bf16 v[34:37], v[176:179], v[192:195], v[34:37]
	v_mfma_f32_16x16x32_bf16 v[22:25], v[160:163], v[200:203], v[22:25]
	v_mfma_f32_16x16x32_bf16 v[18:21], v[176:179], v[200:203], v[18:21]
	v_mfma_f32_16x16x32_bf16 v[6:9], v[160:163], v[208:211], v[6:9]
	v_mfma_f32_16x16x32_bf16 v[2:5], v[176:179], v[208:211], v[2:5]
	v_mfma_f32_16x16x32_bf16 v[54:57], v[172:175], v[188:191], v[54:57]
	v_mfma_f32_16x16x32_bf16 v[50:53], v[180:183], v[188:191], v[50:53]
	v_mfma_f32_16x16x32_bf16 v[38:41], v[172:175], v[196:199], v[38:41]
	v_mfma_f32_16x16x32_bf16 v[34:37], v[180:183], v[196:199], v[34:37]
	v_mfma_f32_16x16x32_bf16 v[22:25], v[172:175], v[204:207], v[22:25]
	v_mfma_f32_16x16x32_bf16 v[18:21], v[180:183], v[204:207], v[18:21]
	v_mfma_f32_16x16x32_bf16 v[6:9], v[172:175], v[212:215], v[6:9]
	v_mfma_f32_16x16x32_bf16 v[2:5], v[180:183], v[212:215], v[2:5]
	s_barrier
	s_add_i32 s51, s51, 2
	s_add_u32 s7, s7, 0x100
	s_addc_u32 s31, s31, 0
	s_add_u32 s8, s8, 0x100
	s_addc_u32 s9, s9, 0
.LBB0_953:
	ds_read_b128 v[130:133], v167
	ds_read_b128 v[134:137], v167 offset:1024
	ds_read_b128 v[138:141], v167 offset:2048
	ds_read_b128 v[142:145], v167 offset:3072
	ds_read_b128 v[160:163], v168
	ds_read_b128 v[172:175], v168 offset:1024
	ds_read_b128 v[176:179], v168 offset:2048
	ds_read_b128 v[180:183], v168 offset:3072
	s_add_u32 s10, s8, 0xfffc0080
	s_addc_u32 s11, s9, -1
	s_cmp_eq_u32 s51, 12
	s_cselect_b32 s59, s53, s11
	s_cselect_b32 s58, s52, s10
	s_cselect_b32 s11, s57, s31
	s_cselect_b32 s10, s56, s7
	s_add_i32 m0, s84, 0xc000
	ds_read_b128 v[184:187], v169
	ds_read_b128 v[188:191], v169 offset:1024
	ds_read_b128 v[192:195], v169 offset:2048
	ds_read_b128 v[196:199], v169 offset:3072
	ds_read_b128 v[200:203], v169 offset:4096
	ds_read_b128 v[204:207], v169 offset:5120
	ds_read_b128 v[208:211], v169 offset:6144
	ds_read_b128 v[212:215], v169 offset:7168
	global_load_lds_dwordx4 v158, s[8:9]
	s_add_i32 m0, s84, 0xe000
	s_nop 0
	global_load_lds_dwordx4 v156, s[8:9]
	s_waitcnt vmcnt(8) lgkmcnt(0)
	s_barrier
	v_mfma_f32_16x16x32_bf16 v[126:129], v[130:133], v[184:187], v[126:129]
	v_mfma_f32_16x16x32_bf16 v[122:125], v[138:141], v[184:187], v[122:125]
	v_mfma_f32_16x16x32_bf16 v[110:113], v[130:133], v[192:195], v[110:113]
	v_mfma_f32_16x16x32_bf16 v[106:109], v[138:141], v[192:195], v[106:109]
	v_mfma_f32_16x16x32_bf16 v[94:97], v[130:133], v[200:203], v[94:97]
	v_mfma_f32_16x16x32_bf16 v[90:93], v[138:141], v[200:203], v[90:93]
	v_mfma_f32_16x16x32_bf16 v[78:81], v[130:133], v[208:211], v[78:81]
	v_mfma_f32_16x16x32_bf16 v[74:77], v[138:141], v[208:211], v[74:77]
	v_mfma_f32_16x16x32_bf16 v[126:129], v[134:137], v[188:191], v[126:129]
	v_mfma_f32_16x16x32_bf16 v[122:125], v[142:145], v[188:191], v[122:125]
	v_mfma_f32_16x16x32_bf16 v[110:113], v[134:137], v[196:199], v[110:113]
	v_mfma_f32_16x16x32_bf16 v[106:109], v[142:145], v[196:199], v[106:109]
	v_mfma_f32_16x16x32_bf16 v[94:97], v[134:137], v[204:207], v[94:97]
	v_mfma_f32_16x16x32_bf16 v[90:93], v[142:145], v[204:207], v[90:93]
	v_mfma_f32_16x16x32_bf16 v[78:81], v[134:137], v[212:215], v[78:81]
	v_mfma_f32_16x16x32_bf16 v[74:77], v[142:145], v[212:215], v[74:77]
	v_mfma_f32_16x16x32_bf16 v[118:121], v[160:163], v[184:187], v[118:121]
	v_mfma_f32_16x16x32_bf16 v[114:117], v[176:179], v[184:187], v[114:117]
	v_mfma_f32_16x16x32_bf16 v[102:105], v[160:163], v[192:195], v[102:105]
	v_mfma_f32_16x16x32_bf16 v[98:101], v[176:179], v[192:195], v[98:101]
	v_mfma_f32_16x16x32_bf16 v[86:89], v[160:163], v[200:203], v[86:89]
	v_mfma_f32_16x16x32_bf16 v[82:85], v[176:179], v[200:203], v[82:85]
	v_mfma_f32_16x16x32_bf16 v[70:73], v[160:163], v[208:211], v[70:73]
	v_mfma_f32_16x16x32_bf16 v[66:69], v[176:179], v[208:211], v[66:69]
	v_mfma_f32_16x16x32_bf16 v[118:121], v[172:175], v[188:191], v[118:121]
	v_mfma_f32_16x16x32_bf16 v[114:117], v[180:183], v[188:191], v[114:117]
	v_mfma_f32_16x16x32_bf16 v[102:105], v[172:175], v[196:199], v[102:105]
	v_mfma_f32_16x16x32_bf16 v[98:101], v[180:183], v[196:199], v[98:101]
	v_mfma_f32_16x16x32_bf16 v[86:89], v[172:175], v[204:207], v[86:89]
	v_mfma_f32_16x16x32_bf16 v[82:85], v[180:183], v[204:207], v[82:85]
	v_mfma_f32_16x16x32_bf16 v[70:73], v[172:175], v[212:215], v[70:73]
	v_mfma_f32_16x16x32_bf16 v[66:69], v[180:183], v[212:215], v[66:69]
	s_barrier
	s_add_i32 s26, s94, s39
	v_lshl_add_u64 v[164:165], s[10:11], 0, v[148:149]
	s_mov_b32 m0, s26
	ds_read_b128 v[184:187], v169 offset:16384
	ds_read_b128 v[188:191], v169 offset:17408
	ds_read_b128 v[192:195], v169 offset:18432
	ds_read_b128 v[196:199], v169 offset:19456
	ds_read_b128 v[200:203], v169 offset:20480
	ds_read_b128 v[204:207], v169 offset:21504
	ds_read_b128 v[208:211], v169 offset:22528
	ds_read_b128 v[212:215], v169 offset:23552
	global_load_lds_dwordx4 v[164:165], off
	s_add_i32 m0, s26, 0x2000
	s_add_u32 s26, s10, 0x40000
	v_lshl_add_u64 v[216:217], s[10:11], 0, v[152:153]
	s_addc_u32 s27, s11, 0
	s_add_i32 s60, s95, s39
	global_load_lds_dwordx4 v[216:217], off
	s_mov_b32 m0, s60
	v_lshl_add_u64 v[220:221], s[58:59], 0, v[150:151]
	global_load_lds_dwordx4 v148, s[26:27]
	s_add_i32 m0, s60, 0x2000
	s_nop 0
	global_load_lds_dwordx4 v152, s[26:27]
	v_lshl_add_u64 v[218:219], s[58:59], 0, v[146:147]
	s_mov_b32 m0, s84
	s_nop 0
	global_load_lds_dwordx4 v[218:219], off
	s_mov_b32 m0, s85
	s_nop 0
	global_load_lds_dwordx4 v[220:221], off
	s_waitcnt vmcnt(8) lgkmcnt(0)
	s_barrier
	v_mfma_f32_16x16x32_bf16 v[62:65], v[130:133], v[184:187], v[62:65]
	v_mfma_f32_16x16x32_bf16 v[58:61], v[138:141], v[184:187], v[58:61]
	v_mfma_f32_16x16x32_bf16 v[46:49], v[130:133], v[192:195], v[46:49]
	v_mfma_f32_16x16x32_bf16 v[42:45], v[138:141], v[192:195], v[42:45]
	v_mfma_f32_16x16x32_bf16 v[30:33], v[130:133], v[200:203], v[30:33]
	v_mfma_f32_16x16x32_bf16 v[26:29], v[138:141], v[200:203], v[26:29]
	v_mfma_f32_16x16x32_bf16 v[14:17], v[130:133], v[208:211], v[14:17]
	v_mfma_f32_16x16x32_bf16 v[10:13], v[138:141], v[208:211], v[10:13]
	v_mfma_f32_16x16x32_bf16 v[62:65], v[134:137], v[188:191], v[62:65]
	v_mfma_f32_16x16x32_bf16 v[58:61], v[142:145], v[188:191], v[58:61]
	v_mfma_f32_16x16x32_bf16 v[46:49], v[134:137], v[196:199], v[46:49]
	v_mfma_f32_16x16x32_bf16 v[42:45], v[142:145], v[196:199], v[42:45]
	v_mfma_f32_16x16x32_bf16 v[30:33], v[134:137], v[204:207], v[30:33]
	v_mfma_f32_16x16x32_bf16 v[26:29], v[142:145], v[204:207], v[26:29]
	v_mfma_f32_16x16x32_bf16 v[14:17], v[134:137], v[212:215], v[14:17]
	v_mfma_f32_16x16x32_bf16 v[10:13], v[142:145], v[212:215], v[10:13]
	v_mfma_f32_16x16x32_bf16 v[54:57], v[160:163], v[184:187], v[54:57]
	v_mfma_f32_16x16x32_bf16 v[50:53], v[176:179], v[184:187], v[50:53]
	v_mfma_f32_16x16x32_bf16 v[38:41], v[160:163], v[192:195], v[38:41]
	v_mfma_f32_16x16x32_bf16 v[34:37], v[176:179], v[192:195], v[34:37]
	v_mfma_f32_16x16x32_bf16 v[22:25], v[160:163], v[200:203], v[22:25]
	v_mfma_f32_16x16x32_bf16 v[18:21], v[176:179], v[200:203], v[18:21]
	v_mfma_f32_16x16x32_bf16 v[6:9], v[160:163], v[208:211], v[6:9]
	v_mfma_f32_16x16x32_bf16 v[2:5], v[176:179], v[208:211], v[2:5]
	v_mfma_f32_16x16x32_bf16 v[54:57], v[172:175], v[188:191], v[54:57]
	v_mfma_f32_16x16x32_bf16 v[50:53], v[180:183], v[188:191], v[50:53]
	v_mfma_f32_16x16x32_bf16 v[38:41], v[172:175], v[196:199], v[38:41]
	v_mfma_f32_16x16x32_bf16 v[34:37], v[180:183], v[196:199], v[34:37]
	v_mfma_f32_16x16x32_bf16 v[22:25], v[172:175], v[204:207], v[22:25]
	v_mfma_f32_16x16x32_bf16 v[18:21], v[180:183], v[204:207], v[18:21]
	v_mfma_f32_16x16x32_bf16 v[6:9], v[172:175], v[212:215], v[6:9]
	v_mfma_f32_16x16x32_bf16 v[2:5], v[180:183], v[212:215], v[2:5]
	s_barrier
	s_add_i32 s60, 0, 0x18000
	v_add_u32_e32 v1, s60, v166
	s_add_i32 s61, 0, 0x1c000
	ds_read_b128 v[130:133], v1
	ds_read_b128 v[134:137], v1 offset:1024
	ds_read_b128 v[138:141], v1 offset:2048
	ds_read_b128 v[142:145], v1 offset:3072
	v_add_u32_e32 v1, s61, v166
	ds_read_b128 v[160:163], v1
	ds_read_b128 v[172:175], v1 offset:1024
	ds_read_b128 v[176:179], v1 offset:2048
	ds_read_b128 v[180:183], v1 offset:3072
	s_add_u32 s26, s58, 0x40000
	s_addc_u32 s27, s59, 0
	s_mov_b32 m0, s86
	ds_read_b128 v[184:187], v169 offset:32768
	ds_read_b128 v[188:191], v169 offset:33792
	ds_read_b128 v[192:195], v169 offset:34816
	ds_read_b128 v[196:199], v169 offset:35840
	ds_read_b128 v[200:203], v169 offset:36864
	ds_read_b128 v[204:207], v169 offset:37888
	ds_read_b128 v[208:211], v169 offset:38912
	ds_read_b128 v[212:215], v169 offset:39936
	global_load_lds_dwordx4 v146, s[26:27]
	s_mov_b32 m0, s87
	s_nop 0
	global_load_lds_dwordx4 v150, s[26:27]
	s_waitcnt vmcnt(8) lgkmcnt(0)
	s_barrier
	v_mfma_f32_16x16x32_bf16 v[126:129], v[130:133], v[184:187], v[126:129]
	v_mfma_f32_16x16x32_bf16 v[122:125], v[138:141], v[184:187], v[122:125]
	v_mfma_f32_16x16x32_bf16 v[110:113], v[130:133], v[192:195], v[110:113]
	v_mfma_f32_16x16x32_bf16 v[106:109], v[138:141], v[192:195], v[106:109]
	v_mfma_f32_16x16x32_bf16 v[94:97], v[130:133], v[200:203], v[94:97]
	v_mfma_f32_16x16x32_bf16 v[90:93], v[138:141], v[200:203], v[90:93]
	v_mfma_f32_16x16x32_bf16 v[78:81], v[130:133], v[208:211], v[78:81]
	v_mfma_f32_16x16x32_bf16 v[74:77], v[138:141], v[208:211], v[74:77]
	v_mfma_f32_16x16x32_bf16 v[126:129], v[134:137], v[188:191], v[126:129]
	v_mfma_f32_16x16x32_bf16 v[122:125], v[142:145], v[188:191], v[122:125]
	v_mfma_f32_16x16x32_bf16 v[110:113], v[134:137], v[196:199], v[110:113]
	v_mfma_f32_16x16x32_bf16 v[106:109], v[142:145], v[196:199], v[106:109]
	v_mfma_f32_16x16x32_bf16 v[94:97], v[134:137], v[204:207], v[94:97]
	v_mfma_f32_16x16x32_bf16 v[90:93], v[142:145], v[204:207], v[90:93]
	v_mfma_f32_16x16x32_bf16 v[78:81], v[134:137], v[212:215], v[78:81]
	v_mfma_f32_16x16x32_bf16 v[74:77], v[142:145], v[212:215], v[74:77]
	v_mfma_f32_16x16x32_bf16 v[118:121], v[160:163], v[184:187], v[118:121]
	v_mfma_f32_16x16x32_bf16 v[114:117], v[176:179], v[184:187], v[114:117]
	v_mfma_f32_16x16x32_bf16 v[102:105], v[160:163], v[192:195], v[102:105]
	v_mfma_f32_16x16x32_bf16 v[98:101], v[176:179], v[192:195], v[98:101]
	v_mfma_f32_16x16x32_bf16 v[86:89], v[160:163], v[200:203], v[86:89]
	v_mfma_f32_16x16x32_bf16 v[82:85], v[176:179], v[200:203], v[82:85]
	v_mfma_f32_16x16x32_bf16 v[70:73], v[160:163], v[208:211], v[70:73]
	v_mfma_f32_16x16x32_bf16 v[66:69], v[176:179], v[208:211], v[66:69]
	v_mfma_f32_16x16x32_bf16 v[118:121], v[172:175], v[188:191], v[118:121]
	v_mfma_f32_16x16x32_bf16 v[114:117], v[180:183], v[188:191], v[114:117]
	v_mfma_f32_16x16x32_bf16 v[102:105], v[172:175], v[196:199], v[102:105]
	v_mfma_f32_16x16x32_bf16 v[98:101], v[180:183], v[196:199], v[98:101]
	v_mfma_f32_16x16x32_bf16 v[86:89], v[172:175], v[204:207], v[86:89]
	v_mfma_f32_16x16x32_bf16 v[82:85], v[180:183], v[204:207], v[82:85]
	v_mfma_f32_16x16x32_bf16 v[70:73], v[172:175], v[212:215], v[70:73]
	v_mfma_f32_16x16x32_bf16 v[66:69], v[180:183], v[212:215], v[66:69]
	s_barrier
	s_add_i32 s26, s60, s39
	v_lshl_add_u64 v[164:165], v[164:165], 0, s[18:19]
	s_mov_b32 m0, s26
	ds_read_b128 v[184:187], v169 offset:49152
	ds_read_b128 v[188:191], v169 offset:50176
	ds_read_b128 v[192:195], v169 offset:51200
	ds_read_b128 v[196:199], v169 offset:52224
	ds_read_b128 v[200:203], v169 offset:53248
	ds_read_b128 v[204:207], v169 offset:54272
	ds_read_b128 v[208:211], v169 offset:55296
	ds_read_b128 v[212:215], v169 offset:56320
	global_load_lds_dwordx4 v[164:165], off
	s_add_i32 m0, s26, 0x2000
	s_add_u32 s10, s10, 0x40080
	v_lshl_add_u64 v[164:165], v[216:217], 0, s[18:19]
	s_addc_u32 s11, s11, 0
	s_add_i32 s26, s61, s39
	global_load_lds_dwordx4 v[164:165], off
	s_mov_b32 m0, s26
	s_nop 0
	global_load_lds_dwordx4 v148, s[10:11]
	s_add_i32 m0, s26, 0x2000
	s_nop 0
	global_load_lds_dwordx4 v152, s[10:11]
	v_lshl_add_u64 v[164:165], v[218:219], 0, s[18:19]
	s_mov_b32 m0, s91
	s_nop 0
	global_load_lds_dwordx4 v[164:165], off
	v_lshl_add_u64 v[164:165], v[220:221], 0, s[18:19]
	s_mov_b32 m0, s92
	s_nop 0
	global_load_lds_dwordx4 v[164:165], off
	s_waitcnt vmcnt(8) lgkmcnt(0)
	s_barrier
	v_mfma_f32_16x16x32_bf16 v[62:65], v[130:133], v[184:187], v[62:65]
	v_mfma_f32_16x16x32_bf16 v[58:61], v[138:141], v[184:187], v[58:61]
	v_mfma_f32_16x16x32_bf16 v[46:49], v[130:133], v[192:195], v[46:49]
	v_mfma_f32_16x16x32_bf16 v[42:45], v[138:141], v[192:195], v[42:45]
	v_mfma_f32_16x16x32_bf16 v[30:33], v[130:133], v[200:203], v[30:33]
	v_mfma_f32_16x16x32_bf16 v[26:29], v[138:141], v[200:203], v[26:29]
	v_mfma_f32_16x16x32_bf16 v[14:17], v[130:133], v[208:211], v[14:17]
	v_mfma_f32_16x16x32_bf16 v[10:13], v[138:141], v[208:211], v[10:13]
	v_mfma_f32_16x16x32_bf16 v[62:65], v[134:137], v[188:191], v[62:65]
	v_mfma_f32_16x16x32_bf16 v[58:61], v[142:145], v[188:191], v[58:61]
	v_mfma_f32_16x16x32_bf16 v[46:49], v[134:137], v[196:199], v[46:49]
	v_mfma_f32_16x16x32_bf16 v[42:45], v[142:145], v[196:199], v[42:45]
	v_mfma_f32_16x16x32_bf16 v[30:33], v[134:137], v[204:207], v[30:33]
	v_mfma_f32_16x16x32_bf16 v[26:29], v[142:145], v[204:207], v[26:29]
	v_mfma_f32_16x16x32_bf16 v[14:17], v[134:137], v[212:215], v[14:17]
	v_mfma_f32_16x16x32_bf16 v[10:13], v[142:145], v[212:215], v[10:13]
	v_mfma_f32_16x16x32_bf16 v[54:57], v[160:163], v[184:187], v[54:57]
	v_mfma_f32_16x16x32_bf16 v[50:53], v[176:179], v[184:187], v[50:53]
	v_mfma_f32_16x16x32_bf16 v[38:41], v[160:163], v[192:195], v[38:41]
	v_mfma_f32_16x16x32_bf16 v[34:37], v[176:179], v[192:195], v[34:37]
	v_mfma_f32_16x16x32_bf16 v[22:25], v[160:163], v[200:203], v[22:25]
	v_mfma_f32_16x16x32_bf16 v[18:21], v[176:179], v[200:203], v[18:21]
	v_mfma_f32_16x16x32_bf16 v[6:9], v[160:163], v[208:211], v[6:9]
	v_mfma_f32_16x16x32_bf16 v[2:5], v[176:179], v[208:211], v[2:5]
	v_mfma_f32_16x16x32_bf16 v[54:57], v[172:175], v[188:191], v[54:57]
	v_mfma_f32_16x16x32_bf16 v[50:53], v[180:183], v[188:191], v[50:53]
	v_mfma_f32_16x16x32_bf16 v[38:41], v[172:175], v[196:199], v[38:41]
	v_mfma_f32_16x16x32_bf16 v[34:37], v[180:183], v[196:199], v[34:37]
	v_mfma_f32_16x16x32_bf16 v[22:25], v[172:175], v[204:207], v[22:25]
	v_mfma_f32_16x16x32_bf16 v[18:21], v[180:183], v[204:207], v[18:21]
	v_mfma_f32_16x16x32_bf16 v[6:9], v[172:175], v[212:215], v[6:9]
	v_mfma_f32_16x16x32_bf16 v[2:5], v[180:183], v[212:215], v[2:5]
	s_barrier
	s_add_i32 s51, s51, 2
	s_add_u32 s7, s7, 0x100
	s_addc_u32 s31, s31, 0
	s_add_u32 s8, s8, 0x100
	s_addc_u32 s9, s9, 0
	s_cmp_gt_u32 s51, 13
	s_cbranch_scc0 .LBB0_953
	s_and_b64 vcc, exec, s[14:15]
	s_cbranch_vccz .LBB0_956
	s_barrier

.LBB0_1290:
	s_add_u32 s8, s56, 0x100
	s_addc_u32 s45, s57, 0
	s_add_u32 s6, s52, 0x40080
	v_mov_b32_e32 v8, 0
	s_addc_u32 s7, s53, 0
	s_mov_b32 s55, -2
	s_waitcnt lgkmcnt(0)
	ds_read_b128 v[0:3], v96
	ds_read_b128 v[4:7], v96 offset:1024
	ds_read_b128 v[84:87], v96 offset:2048
	ds_read_b128 v[100:103], v96 offset:3072
	s_add_u32 s26, s6, 0xfffc0080
	s_addc_u32 s27, s7, -1
	s_cmp_eq_u32 s55, 12
	s_cselect_b32 s53, s47, s27
	s_cselect_b32 s52, s46, s26
	s_cselect_b32 s27, s49, s45
	s_cselect_b32 s26, s48, s8
	s_add_i32 m0, s28, 0xc000
	ds_read_b128 v[104:107], v97
	ds_read_b128 v[108:111], v97 offset:1024
	ds_read_b128 v[112:115], v97 offset:2048
	ds_read_b128 v[116:119], v97 offset:3072
	ds_read_b128 v[120:123], v97 offset:4096
	ds_read_b128 v[124:127], v97 offset:5120
	ds_read_b128 v[128:131], v97 offset:6144
	ds_read_b128 v[132:135], v97 offset:7168
	global_load_lds_dwordx4 v82, s[6:7]
	s_add_i32 m0, s28, 0xe000
	s_nop 0
	global_load_lds_dwordx4 v80, s[6:7]
	s_waitcnt vmcnt(6) lgkmcnt(0)
	s_barrier
	v_mfma_f32_16x16x32_bf16 v[68:71], v[0:3], v[104:107], 0
	v_mfma_f32_16x16x32_bf16 v[64:67], v[84:87], v[104:107], 0
	v_mfma_f32_16x16x32_bf16 v[60:63], v[0:3], v[112:115], 0
	v_mfma_f32_16x16x32_bf16 v[56:59], v[84:87], v[112:115], 0
	v_mfma_f32_16x16x32_bf16 v[52:55], v[0:3], v[120:123], 0
	v_mfma_f32_16x16x32_bf16 v[48:51], v[84:87], v[120:123], 0
	v_mfma_f32_16x16x32_bf16 v[44:47], v[0:3], v[128:131], 0
	v_mfma_f32_16x16x32_bf16 v[40:43], v[84:87], v[128:131], 0
	v_mfma_f32_16x16x32_bf16 v[68:71], v[4:7], v[108:111], v[68:71]
	v_mfma_f32_16x16x32_bf16 v[64:67], v[100:103], v[108:111], v[64:67]
	v_mfma_f32_16x16x32_bf16 v[60:63], v[4:7], v[116:119], v[60:63]
	v_mfma_f32_16x16x32_bf16 v[56:59], v[100:103], v[116:119], v[56:59]
	v_mfma_f32_16x16x32_bf16 v[52:55], v[4:7], v[124:127], v[52:55]
	v_mfma_f32_16x16x32_bf16 v[48:51], v[100:103], v[124:127], v[48:51]
	v_mfma_f32_16x16x32_bf16 v[44:47], v[4:7], v[132:135], v[44:47]
	v_mfma_f32_16x16x32_bf16 v[40:43], v[100:103], v[132:135], v[40:43]
	s_barrier
	s_add_i32 s56, s68, s39
	v_lshl_add_u64 v[88:89], s[26:27], 0, v[74:75]
	s_mov_b32 m0, s56
	ds_read_b128 v[104:107], v97 offset:16384
	ds_read_b128 v[108:111], v97 offset:17408
	ds_read_b128 v[112:115], v97 offset:18432
	ds_read_b128 v[116:119], v97 offset:19456
	ds_read_b128 v[120:123], v97 offset:20480
	ds_read_b128 v[124:127], v97 offset:21504
	ds_read_b128 v[128:131], v97 offset:22528
	ds_read_b128 v[132:135], v97 offset:23552
	global_load_lds_dwordx4 v[88:89], off
	v_lshl_add_u64 v[136:137], s[26:27], 0, v[78:79]
	s_add_i32 m0, s56, 0x2000
	v_lshl_add_u64 v[138:139], s[52:53], 0, v[72:73]
	global_load_lds_dwordx4 v[136:137], off
	s_mov_b32 m0, s28
	v_lshl_add_u64 v[140:141], s[52:53], 0, v[76:77]
	global_load_lds_dwordx4 v[138:139], off
	s_mov_b32 m0, s29
	s_nop 0
	global_load_lds_dwordx4 v[140:141], off
	s_waitcnt vmcnt(6) lgkmcnt(0)
	s_barrier
	v_mfma_f32_16x16x32_bf16 v[36:39], v[0:3], v[104:107], 0
	v_mfma_f32_16x16x32_bf16 v[32:35], v[84:87], v[104:107], 0
	v_mfma_f32_16x16x32_bf16 v[28:31], v[0:3], v[112:115], 0
	v_mfma_f32_16x16x32_bf16 v[24:27], v[84:87], v[112:115], 0
	v_mfma_f32_16x16x32_bf16 v[20:23], v[0:3], v[120:123], 0
	v_mfma_f32_16x16x32_bf16 v[16:19], v[84:87], v[120:123], 0
	v_mfma_f32_16x16x32_bf16 v[0:3], v[0:3], v[128:131], 0
	v_mfma_f32_16x16x32_bf16 v[36:39], v[4:7], v[108:111], v[36:39]
	v_mfma_f32_16x16x32_bf16 v[32:35], v[100:103], v[108:111], v[32:35]
	v_mfma_f32_16x16x32_bf16 v[28:31], v[4:7], v[116:119], v[28:31]
	v_mfma_f32_16x16x32_bf16 v[24:27], v[100:103], v[116:119], v[24:27]
	v_mfma_f32_16x16x32_bf16 v[20:23], v[4:7], v[124:127], v[20:23]
	v_mfma_f32_16x16x32_bf16 v[16:19], v[100:103], v[124:127], v[16:19]
	v_mfma_f32_16x16x32_bf16 v[0:3], v[4:7], v[132:135], v[0:3]
	v_mfma_f32_16x16x32_bf16 v[4:7], v[84:87], v[128:131], 0
	v_mfma_f32_16x16x32_bf16 v[4:7], v[100:103], v[132:135], v[4:7]
	s_barrier
	s_add_i32 s56, 0, 0x18000
	v_add_u32_e32 v90, s56, v91
	ds_read_b128 v[8:11], v90
	ds_read_b128 v[12:15], v90 offset:1024
	ds_read_b128 v[84:87], v90 offset:2048
	ds_read_b128 v[100:103], v90 offset:3072
	s_add_u32 s26, s52, 0x40000
	s_addc_u32 s27, s53, 0
	s_mov_b32 m0, s30
	ds_read_b128 v[104:107], v97 offset:32768
	ds_read_b128 v[108:111], v97 offset:33792
	ds_read_b128 v[112:115], v97 offset:34816
	ds_read_b128 v[116:119], v97 offset:35840
	ds_read_b128 v[120:123], v97 offset:36864
	ds_read_b128 v[124:127], v97 offset:37888
	ds_read_b128 v[128:131], v97 offset:38912
	ds_read_b128 v[132:135], v97 offset:39936
	global_load_lds_dwordx4 v72, s[26:27]
	s_mov_b32 m0, s31
	s_nop 0
	global_load_lds_dwordx4 v76, s[26:27]
	s_waitcnt vmcnt(6) lgkmcnt(0)
	s_barrier
	v_mfma_f32_16x16x32_bf16 v[68:71], v[8:11], v[104:107], v[68:71]
	v_mfma_f32_16x16x32_bf16 v[64:67], v[84:87], v[104:107], v[64:67]
	v_mfma_f32_16x16x32_bf16 v[60:63], v[8:11], v[112:115], v[60:63]
	v_mfma_f32_16x16x32_bf16 v[56:59], v[84:87], v[112:115], v[56:59]
	v_mfma_f32_16x16x32_bf16 v[52:55], v[8:11], v[120:123], v[52:55]
	v_mfma_f32_16x16x32_bf16 v[48:51], v[84:87], v[120:123], v[48:51]
	v_mfma_f32_16x16x32_bf16 v[44:47], v[8:11], v[128:131], v[44:47]
	v_mfma_f32_16x16x32_bf16 v[40:43], v[84:87], v[128:131], v[40:43]
	v_mfma_f32_16x16x32_bf16 v[68:71], v[12:15], v[108:111], v[68:71]
	v_mfma_f32_16x16x32_bf16 v[64:67], v[100:103], v[108:111], v[64:67]
	v_mfma_f32_16x16x32_bf16 v[60:63], v[12:15], v[116:119], v[60:63]
	v_mfma_f32_16x16x32_bf16 v[56:59], v[100:103], v[116:119], v[56:59]
	v_mfma_f32_16x16x32_bf16 v[52:55], v[12:15], v[124:127], v[52:55]
	v_mfma_f32_16x16x32_bf16 v[48:51], v[100:103], v[124:127], v[48:51]
	v_mfma_f32_16x16x32_bf16 v[44:47], v[12:15], v[132:135], v[44:47]
	v_mfma_f32_16x16x32_bf16 v[40:43], v[100:103], v[132:135], v[40:43]
	s_barrier
	s_add_i32 s26, s56, s39
	v_lshl_add_u64 v[88:89], v[88:89], 0, s[10:11]
	s_mov_b32 m0, s26
	ds_read_b128 v[104:107], v97 offset:49152
	ds_read_b128 v[108:111], v97 offset:50176
	ds_read_b128 v[112:115], v97 offset:51200
	ds_read_b128 v[116:119], v97 offset:52224
	ds_read_b128 v[120:123], v97 offset:53248
	ds_read_b128 v[124:127], v97 offset:54272
	ds_read_b128 v[128:131], v97 offset:55296
	ds_read_b128 v[132:135], v97 offset:56320
	global_load_lds_dwordx4 v[88:89], off
	v_lshl_add_u64 v[88:89], v[136:137], 0, s[10:11]
	s_add_i32 m0, s26, 0x2000
	s_nop 0
	global_load_lds_dwordx4 v[88:89], off
	v_lshl_add_u64 v[88:89], v[138:139], 0, s[10:11]
	s_mov_b32 m0, s62
	s_nop 0
	global_load_lds_dwordx4 v[88:89], off
	v_lshl_add_u64 v[88:89], v[140:141], 0, s[10:11]
	s_mov_b32 m0, s63
	s_nop 0
	global_load_lds_dwordx4 v[88:89], off
	s_waitcnt vmcnt(6) lgkmcnt(0)
	s_barrier
	v_mfma_f32_16x16x32_bf16 v[36:39], v[8:11], v[104:107], v[36:39]
	v_mfma_f32_16x16x32_bf16 v[28:31], v[8:11], v[112:115], v[28:31]
	v_mfma_f32_16x16x32_bf16 v[20:23], v[8:11], v[120:123], v[20:23]
	v_mfma_f32_16x16x32_bf16 v[0:3], v[8:11], v[128:131], v[0:3]
	v_mfma_f32_16x16x32_bf16 v[36:39], v[12:15], v[108:111], v[36:39]
	v_mfma_f32_16x16x32_bf16 v[32:35], v[84:87], v[104:107], v[32:35]
	v_mfma_f32_16x16x32_bf16 v[28:31], v[12:15], v[116:119], v[28:31]
	v_mfma_f32_16x16x32_bf16 v[24:27], v[84:87], v[112:115], v[24:27]
	v_mfma_f32_16x16x32_bf16 v[20:23], v[12:15], v[124:127], v[20:23]
	v_mfma_f32_16x16x32_bf16 v[16:19], v[84:87], v[120:123], v[16:19]
	v_mfma_f32_16x16x32_bf16 v[12:15], v[12:15], v[132:135], v[0:3]
	v_mfma_f32_16x16x32_bf16 v[0:3], v[84:87], v[128:131], v[4:7]
	v_mfma_f32_16x16x32_bf16 v[32:35], v[100:103], v[108:111], v[32:35]
	v_mfma_f32_16x16x32_bf16 v[24:27], v[100:103], v[116:119], v[24:27]
	v_mfma_f32_16x16x32_bf16 v[16:19], v[100:103], v[124:127], v[16:19]
	v_mfma_f32_16x16x32_bf16 v[8:11], v[100:103], v[132:135], v[0:3]
	s_barrier
	s_add_i32 s55, s55, 2
	s_add_u32 s8, s8, 0x100
	s_addc_u32 s45, s45, 0
	s_add_u32 s6, s6, 0x100
	s_addc_u32 s7, s7, 0
.LBB0_1291:
	s_waitcnt lgkmcnt(0)
	ds_read_b128 v[0:3], v96
	ds_read_b128 v[4:7], v96 offset:1024
	ds_read_b128 v[84:87], v96 offset:2048
	ds_read_b128 v[100:103], v96 offset:3072
	s_add_u32 s26, s6, 0xfffc0080
	s_addc_u32 s27, s7, -1
	s_cmp_eq_u32 s55, 12
	s_cselect_b32 s53, s47, s27
	s_cselect_b32 s52, s46, s26
	s_cselect_b32 s27, s49, s45
	s_cselect_b32 s26, s48, s8
	s_add_i32 m0, s28, 0xc000
	ds_read_b128 v[104:107], v97
	ds_read_b128 v[108:111], v97 offset:1024
	ds_read_b128 v[112:115], v97 offset:2048
	ds_read_b128 v[116:119], v97 offset:3072
	ds_read_b128 v[120:123], v97 offset:4096
	ds_read_b128 v[124:127], v97 offset:5120
	ds_read_b128 v[128:131], v97 offset:6144
	ds_read_b128 v[132:135], v97 offset:7168
	global_load_lds_dwordx4 v82, s[6:7]
	s_add_i32 m0, s28, 0xe000
	s_nop 0
	global_load_lds_dwordx4 v80, s[6:7]
	s_waitcnt vmcnt(6) lgkmcnt(0)
	s_barrier
	v_mfma_f32_16x16x32_bf16 v[68:71], v[0:3], v[104:107], v[68:71]
	v_mfma_f32_16x16x32_bf16 v[64:67], v[84:87], v[104:107], v[64:67]
	v_mfma_f32_16x16x32_bf16 v[60:63], v[0:3], v[112:115], v[60:63]
	v_mfma_f32_16x16x32_bf16 v[56:59], v[84:87], v[112:115], v[56:59]
	v_mfma_f32_16x16x32_bf16 v[52:55], v[0:3], v[120:123], v[52:55]
	v_mfma_f32_16x16x32_bf16 v[48:51], v[84:87], v[120:123], v[48:51]
	v_mfma_f32_16x16x32_bf16 v[44:47], v[0:3], v[128:131], v[44:47]
	v_mfma_f32_16x16x32_bf16 v[40:43], v[84:87], v[128:131], v[40:43]
	v_mfma_f32_16x16x32_bf16 v[68:71], v[4:7], v[108:111], v[68:71]
	v_mfma_f32_16x16x32_bf16 v[64:67], v[100:103], v[108:111], v[64:67]
	v_mfma_f32_16x16x32_bf16 v[60:63], v[4:7], v[116:119], v[60:63]
	v_mfma_f32_16x16x32_bf16 v[56:59], v[100:103], v[116:119], v[56:59]
	v_mfma_f32_16x16x32_bf16 v[52:55], v[4:7], v[124:127], v[52:55]
	v_mfma_f32_16x16x32_bf16 v[48:51], v[100:103], v[124:127], v[48:51]
	v_mfma_f32_16x16x32_bf16 v[44:47], v[4:7], v[132:135], v[44:47]
	v_mfma_f32_16x16x32_bf16 v[40:43], v[100:103], v[132:135], v[40:43]
	s_barrier
	s_add_i32 s56, s68, s39
	v_lshl_add_u64 v[88:89], s[26:27], 0, v[74:75]
	s_mov_b32 m0, s56
	ds_read_b128 v[104:107], v97 offset:16384
	ds_read_b128 v[108:111], v97 offset:17408
	ds_read_b128 v[112:115], v97 offset:18432
	ds_read_b128 v[116:119], v97 offset:19456
	ds_read_b128 v[120:123], v97 offset:20480
	ds_read_b128 v[124:127], v97 offset:21504
	ds_read_b128 v[128:131], v97 offset:22528
	ds_read_b128 v[132:135], v97 offset:23552
	global_load_lds_dwordx4 v[88:89], off
	v_lshl_add_u64 v[136:137], s[26:27], 0, v[78:79]
	s_add_i32 m0, s56, 0x2000
	v_lshl_add_u64 v[138:139], s[52:53], 0, v[72:73]
	global_load_lds_dwordx4 v[136:137], off
	s_mov_b32 m0, s28
	v_lshl_add_u64 v[140:141], s[52:53], 0, v[76:77]
	global_load_lds_dwordx4 v[138:139], off
	s_mov_b32 m0, s29
	s_nop 0
	global_load_lds_dwordx4 v[140:141], off
	s_waitcnt vmcnt(6) lgkmcnt(0)
	s_barrier
	v_mfma_f32_16x16x32_bf16 v[36:39], v[0:3], v[104:107], v[36:39]
	v_mfma_f32_16x16x32_bf16 v[32:35], v[84:87], v[104:107], v[32:35]
	v_mfma_f32_16x16x32_bf16 v[28:31], v[0:3], v[112:115], v[28:31]
	v_mfma_f32_16x16x32_bf16 v[24:27], v[84:87], v[112:115], v[24:27]
	v_mfma_f32_16x16x32_bf16 v[20:23], v[0:3], v[120:123], v[20:23]
	v_mfma_f32_16x16x32_bf16 v[16:19], v[84:87], v[120:123], v[16:19]
	v_mfma_f32_16x16x32_bf16 v[0:3], v[0:3], v[128:131], v[12:15]
	v_mfma_f32_16x16x32_bf16 v[36:39], v[4:7], v[108:111], v[36:39]
	v_mfma_f32_16x16x32_bf16 v[32:35], v[100:103], v[108:111], v[32:35]
	v_mfma_f32_16x16x32_bf16 v[28:31], v[4:7], v[116:119], v[28:31]
	v_mfma_f32_16x16x32_bf16 v[24:27], v[100:103], v[116:119], v[24:27]
	v_mfma_f32_16x16x32_bf16 v[20:23], v[4:7], v[124:127], v[20:23]
	v_mfma_f32_16x16x32_bf16 v[16:19], v[100:103], v[124:127], v[16:19]
	v_mfma_f32_16x16x32_bf16 v[0:3], v[4:7], v[132:135], v[0:3]
	v_mfma_f32_16x16x32_bf16 v[4:7], v[84:87], v[128:131], v[8:11]
	v_mfma_f32_16x16x32_bf16 v[4:7], v[100:103], v[132:135], v[4:7]
	s_barrier
	s_add_i32 s56, 0, 0x18000
	v_add_u32_e32 v90, s56, v91
	ds_read_b128 v[8:11], v90
	ds_read_b128 v[12:15], v90 offset:1024
	ds_read_b128 v[84:87], v90 offset:2048
	ds_read_b128 v[100:103], v90 offset:3072
	s_add_u32 s26, s52, 0x40000
	s_addc_u32 s27, s53, 0
	s_mov_b32 m0, s30
	ds_read_b128 v[104:107], v97 offset:32768
	ds_read_b128 v[108:111], v97 offset:33792
	ds_read_b128 v[112:115], v97 offset:34816
	ds_read_b128 v[116:119], v97 offset:35840
	ds_read_b128 v[120:123], v97 offset:36864
	ds_read_b128 v[124:127], v97 offset:37888
	ds_read_b128 v[128:131], v97 offset:38912
	ds_read_b128 v[132:135], v97 offset:39936
	global_load_lds_dwordx4 v72, s[26:27]
	s_mov_b32 m0, s31
	s_nop 0
	global_load_lds_dwordx4 v76, s[26:27]
	s_waitcnt vmcnt(6) lgkmcnt(0)
	s_barrier
	v_mfma_f32_16x16x32_bf16 v[68:71], v[8:11], v[104:107], v[68:71]
	v_mfma_f32_16x16x32_bf16 v[64:67], v[84:87], v[104:107], v[64:67]
	v_mfma_f32_16x16x32_bf16 v[60:63], v[8:11], v[112:115], v[60:63]
	v_mfma_f32_16x16x32_bf16 v[56:59], v[84:87], v[112:115], v[56:59]
	v_mfma_f32_16x16x32_bf16 v[52:55], v[8:11], v[120:123], v[52:55]
	v_mfma_f32_16x16x32_bf16 v[48:51], v[84:87], v[120:123], v[48:51]
	v_mfma_f32_16x16x32_bf16 v[44:47], v[8:11], v[128:131], v[44:47]
	v_mfma_f32_16x16x32_bf16 v[40:43], v[84:87], v[128:131], v[40:43]
	v_mfma_f32_16x16x32_bf16 v[68:71], v[12:15], v[108:111], v[68:71]
	v_mfma_f32_16x16x32_bf16 v[64:67], v[100:103], v[108:111], v[64:67]
	v_mfma_f32_16x16x32_bf16 v[60:63], v[12:15], v[116:119], v[60:63]
	v_mfma_f32_16x16x32_bf16 v[56:59], v[100:103], v[116:119], v[56:59]
	v_mfma_f32_16x16x32_bf16 v[52:55], v[12:15], v[124:127], v[52:55]
	v_mfma_f32_16x16x32_bf16 v[48:51], v[100:103], v[124:127], v[48:51]
	v_mfma_f32_16x16x32_bf16 v[44:47], v[12:15], v[132:135], v[44:47]
	v_mfma_f32_16x16x32_bf16 v[40:43], v[100:103], v[132:135], v[40:43]
	s_barrier
	s_add_i32 s26, s56, s39
	v_lshl_add_u64 v[88:89], v[88:89], 0, s[10:11]
	s_mov_b32 m0, s26
	ds_read_b128 v[104:107], v97 offset:49152
	ds_read_b128 v[108:111], v97 offset:50176
	ds_read_b128 v[112:115], v97 offset:51200
	ds_read_b128 v[116:119], v97 offset:52224
	ds_read_b128 v[120:123], v97 offset:53248
	ds_read_b128 v[124:127], v97 offset:54272
	ds_read_b128 v[128:131], v97 offset:55296
	ds_read_b128 v[132:135], v97 offset:56320
	global_load_lds_dwordx4 v[88:89], off
	v_lshl_add_u64 v[88:89], v[136:137], 0, s[10:11]
	s_add_i32 m0, s26, 0x2000
	s_nop 0
	global_load_lds_dwordx4 v[88:89], off
	v_lshl_add_u64 v[88:89], v[138:139], 0, s[10:11]
	s_mov_b32 m0, s62
	s_nop 0
	global_load_lds_dwordx4 v[88:89], off
	v_lshl_add_u64 v[88:89], v[140:141], 0, s[10:11]
	s_mov_b32 m0, s63
	s_nop 0
	global_load_lds_dwordx4 v[88:89], off
	s_waitcnt vmcnt(6) lgkmcnt(0)
	s_barrier
	v_mfma_f32_16x16x32_bf16 v[36:39], v[8:11], v[104:107], v[36:39]
	v_mfma_f32_16x16x32_bf16 v[28:31], v[8:11], v[112:115], v[28:31]
	v_mfma_f32_16x16x32_bf16 v[20:23], v[8:11], v[120:123], v[20:23]
	v_mfma_f32_16x16x32_bf16 v[0:3], v[8:11], v[128:131], v[0:3]
	v_mfma_f32_16x16x32_bf16 v[36:39], v[12:15], v[108:111], v[36:39]
	v_mfma_f32_16x16x32_bf16 v[32:35], v[84:87], v[104:107], v[32:35]
	v_mfma_f32_16x16x32_bf16 v[28:31], v[12:15], v[116:119], v[28:31]
	v_mfma_f32_16x16x32_bf16 v[24:27], v[84:87], v[112:115], v[24:27]
	v_mfma_f32_16x16x32_bf16 v[20:23], v[12:15], v[124:127], v[20:23]
	v_mfma_f32_16x16x32_bf16 v[16:19], v[84:87], v[120:123], v[16:19]
	v_mfma_f32_16x16x32_bf16 v[12:15], v[12:15], v[132:135], v[0:3]
	v_mfma_f32_16x16x32_bf16 v[0:3], v[84:87], v[128:131], v[4:7]
	v_mfma_f32_16x16x32_bf16 v[32:35], v[100:103], v[108:111], v[32:35]
	v_mfma_f32_16x16x32_bf16 v[24:27], v[100:103], v[116:119], v[24:27]
	v_mfma_f32_16x16x32_bf16 v[16:19], v[100:103], v[124:127], v[16:19]
	v_mfma_f32_16x16x32_bf16 v[8:11], v[100:103], v[132:135], v[0:3]
	s_barrier
	s_add_i32 s55, s55, 2
	s_add_u32 s8, s8, 0x100
	s_addc_u32 s45, s45, 0
	s_add_u32 s6, s6, 0x100
	s_addc_u32 s7, s7, 0
	s_cmp_gt_u32 s55, 13
	s_cbranch_scc0 .LBB0_1291
	s_and_b64 vcc, exec, s[14:15]
	s_cbranch_vccz .LBB0_1294
	s_barrier

.LBB0_1518:
	s_add_u32 s23, s6, 0x100
	s_addc_u32 s60, s7, 0
	s_add_u32 s4, s4, 0x40080
	v_mov_b32_e32 v0, 0
	s_addc_u32 s5, s5, 0
	s_mov_b32 s61, -2
	ds_read_b128 v[128:131], v246
	ds_read_b128 v[132:135], v246 offset:1024
	ds_read_b128 v[136:139], v246 offset:2048
	ds_read_b128 v[140:143], v246 offset:3072
	ds_read_b128 v[144:147], v247
	ds_read_b128 v[148:151], v247 offset:1024
	ds_read_b128 v[152:155], v247 offset:2048
	ds_read_b128 v[156:159], v247 offset:3072
	s_add_u32 s6, s4, 0xfffc0080
	s_addc_u32 s7, s5, -1
	s_cmp_eq_u32 s61, 12
	s_cselect_b32 s35, s25, s7
	s_cselect_b32 s34, s24, s6
	s_cselect_b32 s7, s27, s60
	s_cselect_b32 s6, s26, s23
	s_add_i32 m0, s36, 0xc000
	ds_read_b128 v[160:163], v248
	ds_read_b128 v[164:167], v248 offset:1024
	ds_read_b128 v[168:171], v248 offset:2048
	ds_read_b128 v[172:175], v248 offset:3072
	ds_read_b128 v[176:179], v248 offset:4096
	ds_read_b128 v[180:183], v248 offset:5120
	ds_read_b128 v[184:187], v248 offset:6144
	ds_read_b128 v[188:191], v248 offset:7168
	global_load_lds_dwordx4 v218, s[4:5]
	s_add_i32 m0, s36, 0xe000
	s_nop 0
	global_load_lds_dwordx4 v216, s[4:5]
	s_waitcnt vmcnt(8) lgkmcnt(0)
	s_barrier
	v_mfma_f32_16x16x32_bf16 v[124:127], v[128:131], v[160:163], 0
	v_mfma_f32_16x16x32_bf16 v[120:123], v[136:139], v[160:163], 0
	v_mfma_f32_16x16x32_bf16 v[112:115], v[128:131], v[168:171], 0
	v_mfma_f32_16x16x32_bf16 v[104:107], v[136:139], v[168:171], 0
	v_mfma_f32_16x16x32_bf16 v[96:99], v[128:131], v[176:179], 0
	v_mfma_f32_16x16x32_bf16 v[88:91], v[136:139], v[176:179], 0
	v_mfma_f32_16x16x32_bf16 v[80:83], v[128:131], v[184:187], 0
	v_mfma_f32_16x16x32_bf16 v[72:75], v[136:139], v[184:187], 0
	v_mfma_f32_16x16x32_bf16 v[124:127], v[132:135], v[164:167], v[124:127]
	v_mfma_f32_16x16x32_bf16 v[120:123], v[140:143], v[164:167], v[120:123]
	v_mfma_f32_16x16x32_bf16 v[112:115], v[132:135], v[172:175], v[112:115]
	v_mfma_f32_16x16x32_bf16 v[104:107], v[140:143], v[172:175], v[104:107]
	v_mfma_f32_16x16x32_bf16 v[96:99], v[132:135], v[180:183], v[96:99]
	v_mfma_f32_16x16x32_bf16 v[88:91], v[140:143], v[180:183], v[88:91]
	v_mfma_f32_16x16x32_bf16 v[80:83], v[132:135], v[188:191], v[80:83]
	v_mfma_f32_16x16x32_bf16 v[72:75], v[140:143], v[188:191], v[72:75]
	v_mfma_f32_16x16x32_bf16 v[116:119], v[144:147], v[160:163], 0
	v_mfma_f32_16x16x32_bf16 v[108:111], v[152:155], v[160:163], 0
	v_mfma_f32_16x16x32_bf16 v[100:103], v[144:147], v[168:171], 0
	v_mfma_f32_16x16x32_bf16 v[92:95], v[152:155], v[168:171], 0
	v_mfma_f32_16x16x32_bf16 v[84:87], v[144:147], v[176:179], 0
	v_mfma_f32_16x16x32_bf16 v[76:79], v[152:155], v[176:179], 0
	v_mfma_f32_16x16x32_bf16 v[68:71], v[144:147], v[184:187], 0
	v_mfma_f32_16x16x32_bf16 v[64:67], v[152:155], v[184:187], 0
	v_mfma_f32_16x16x32_bf16 v[116:119], v[148:151], v[164:167], v[116:119]
	v_mfma_f32_16x16x32_bf16 v[108:111], v[156:159], v[164:167], v[108:111]
	v_mfma_f32_16x16x32_bf16 v[100:103], v[148:151], v[172:175], v[100:103]
	v_mfma_f32_16x16x32_bf16 v[92:95], v[156:159], v[172:175], v[92:95]
	v_mfma_f32_16x16x32_bf16 v[84:87], v[148:151], v[180:183], v[84:87]
	v_mfma_f32_16x16x32_bf16 v[76:79], v[156:159], v[180:183], v[76:79]
	v_mfma_f32_16x16x32_bf16 v[68:71], v[148:151], v[188:191], v[68:71]
	v_mfma_f32_16x16x32_bf16 v[64:67], v[156:159], v[188:191], v[64:67]
	s_barrier
	s_add_i32 s62, s48, s3
	v_lshl_add_u64 v[192:193], s[6:7], 0, v[212:213]
	s_mov_b32 m0, s62
	ds_read_b128 v[160:163], v248 offset:16384
	ds_read_b128 v[164:167], v248 offset:17408
	ds_read_b128 v[168:171], v248 offset:18432
	ds_read_b128 v[172:175], v248 offset:19456
	ds_read_b128 v[176:179], v248 offset:20480
	ds_read_b128 v[180:183], v248 offset:21504
	ds_read_b128 v[184:187], v248 offset:22528
	ds_read_b128 v[188:191], v248 offset:23552
	global_load_lds_dwordx4 v[192:193], off
	s_add_i32 m0, s62, 0x2000
	s_add_u32 s62, s6, 0x40000
	v_lshl_add_u64 v[194:195], s[6:7], 0, v[208:209]
	s_addc_u32 s63, s7, 0
	s_add_i32 s64, s49, s3
	global_load_lds_dwordx4 v[194:195], off
	s_mov_b32 m0, s64
	v_lshl_add_u64 v[198:199], s[34:35], 0, v[210:211]
	global_load_lds_dwordx4 v212, s[62:63]
	s_add_i32 m0, s64, 0x2000
	s_nop 0
	global_load_lds_dwordx4 v208, s[62:63]
	v_lshl_add_u64 v[196:197], s[34:35], 0, v[214:215]
	s_mov_b32 m0, s36
	s_nop 0
	global_load_lds_dwordx4 v[196:197], off
	s_mov_b32 m0, s37
	s_nop 0
	global_load_lds_dwordx4 v[198:199], off
	s_waitcnt vmcnt(8) lgkmcnt(0)
	s_barrier
	v_mfma_f32_16x16x32_bf16 v[60:63], v[128:131], v[160:163], 0
	v_mfma_f32_16x16x32_bf16 v[56:59], v[136:139], v[160:163], 0
	v_mfma_f32_16x16x32_bf16 v[48:51], v[128:131], v[168:171], 0
	v_mfma_f32_16x16x32_bf16 v[40:43], v[136:139], v[168:171], 0
	v_mfma_f32_16x16x32_bf16 v[32:35], v[128:131], v[176:179], 0
	v_mfma_f32_16x16x32_bf16 v[24:27], v[136:139], v[176:179], 0
	v_mfma_f32_16x16x32_bf16 v[16:19], v[128:131], v[184:187], 0
	v_mfma_f32_16x16x32_bf16 v[8:11], v[136:139], v[184:187], 0
	v_mfma_f32_16x16x32_bf16 v[60:63], v[132:135], v[164:167], v[60:63]
	v_mfma_f32_16x16x32_bf16 v[56:59], v[140:143], v[164:167], v[56:59]
	v_mfma_f32_16x16x32_bf16 v[48:51], v[132:135], v[172:175], v[48:51]
	v_mfma_f32_16x16x32_bf16 v[40:43], v[140:143], v[172:175], v[40:43]
	v_mfma_f32_16x16x32_bf16 v[32:35], v[132:135], v[180:183], v[32:35]
	v_mfma_f32_16x16x32_bf16 v[24:27], v[140:143], v[180:183], v[24:27]
	v_mfma_f32_16x16x32_bf16 v[16:19], v[132:135], v[188:191], v[16:19]
	v_mfma_f32_16x16x32_bf16 v[8:11], v[140:143], v[188:191], v[8:11]
	v_mfma_f32_16x16x32_bf16 v[52:55], v[144:147], v[160:163], 0
	v_mfma_f32_16x16x32_bf16 v[44:47], v[152:155], v[160:163], 0
	v_mfma_f32_16x16x32_bf16 v[36:39], v[144:147], v[168:171], 0
	v_mfma_f32_16x16x32_bf16 v[28:31], v[152:155], v[168:171], 0
	v_mfma_f32_16x16x32_bf16 v[20:23], v[144:147], v[176:179], 0
	v_mfma_f32_16x16x32_bf16 v[12:15], v[152:155], v[176:179], 0
	v_mfma_f32_16x16x32_bf16 v[4:7], v[144:147], v[184:187], 0
	v_mfma_f32_16x16x32_bf16 v[0:3], v[152:155], v[184:187], 0
	v_mfma_f32_16x16x32_bf16 v[52:55], v[148:151], v[164:167], v[52:55]
	v_mfma_f32_16x16x32_bf16 v[44:47], v[156:159], v[164:167], v[44:47]
	v_mfma_f32_16x16x32_bf16 v[36:39], v[148:151], v[172:175], v[36:39]
	v_mfma_f32_16x16x32_bf16 v[28:31], v[156:159], v[172:175], v[28:31]
	v_mfma_f32_16x16x32_bf16 v[20:23], v[148:151], v[180:183], v[20:23]
	v_mfma_f32_16x16x32_bf16 v[12:15], v[156:159], v[180:183], v[12:15]
	v_mfma_f32_16x16x32_bf16 v[4:7], v[148:151], v[188:191], v[4:7]
	v_mfma_f32_16x16x32_bf16 v[0:3], v[156:159], v[188:191], v[0:3]
	s_barrier
	s_add_i32 s62, 0, 0x18000
	s_add_i32 s63, 0, 0x1c000
	v_add_u32_e32 v140, s62, v245
	v_add_u32_e32 v156, s63, v245
	ds_read_b128 v[128:131], v140
	ds_read_b128 v[132:135], v140 offset:1024
	ds_read_b128 v[136:139], v140 offset:2048
	ds_read_b128 v[140:143], v140 offset:3072
	ds_read_b128 v[144:147], v156
	ds_read_b128 v[148:151], v156 offset:1024
	ds_read_b128 v[152:155], v156 offset:2048
	ds_read_b128 v[156:159], v156 offset:3072
	s_add_u32 s34, s34, 0x40000
	s_addc_u32 s35, s35, 0
	s_mov_b32 m0, s38
	ds_read_b128 v[160:163], v248 offset:32768
	ds_read_b128 v[164:167], v248 offset:33792
	ds_read_b128 v[168:171], v248 offset:34816
	ds_read_b128 v[172:175], v248 offset:35840
	ds_read_b128 v[176:179], v248 offset:36864
	ds_read_b128 v[180:183], v248 offset:37888
	ds_read_b128 v[184:187], v248 offset:38912
	ds_read_b128 v[188:191], v248 offset:39936
	global_load_lds_dwordx4 v214, s[34:35]
	s_mov_b32 m0, s39
	s_nop 0
	global_load_lds_dwordx4 v210, s[34:35]
	s_waitcnt vmcnt(8) lgkmcnt(0)
	s_barrier
	v_mfma_f32_16x16x32_bf16 v[124:127], v[128:131], v[160:163], v[124:127]
	v_mfma_f32_16x16x32_bf16 v[120:123], v[136:139], v[160:163], v[120:123]
	v_mfma_f32_16x16x32_bf16 v[112:115], v[128:131], v[168:171], v[112:115]
	v_mfma_f32_16x16x32_bf16 v[104:107], v[136:139], v[168:171], v[104:107]
	v_mfma_f32_16x16x32_bf16 v[96:99], v[128:131], v[176:179], v[96:99]
	v_mfma_f32_16x16x32_bf16 v[88:91], v[136:139], v[176:179], v[88:91]
	v_mfma_f32_16x16x32_bf16 v[80:83], v[128:131], v[184:187], v[80:83]
	v_mfma_f32_16x16x32_bf16 v[72:75], v[136:139], v[184:187], v[72:75]
	v_mfma_f32_16x16x32_bf16 v[124:127], v[132:135], v[164:167], v[124:127]
	v_mfma_f32_16x16x32_bf16 v[120:123], v[140:143], v[164:167], v[120:123]
	v_mfma_f32_16x16x32_bf16 v[112:115], v[132:135], v[172:175], v[112:115]
	v_mfma_f32_16x16x32_bf16 v[104:107], v[140:143], v[172:175], v[104:107]
	v_mfma_f32_16x16x32_bf16 v[96:99], v[132:135], v[180:183], v[96:99]
	v_mfma_f32_16x16x32_bf16 v[88:91], v[140:143], v[180:183], v[88:91]
	v_mfma_f32_16x16x32_bf16 v[80:83], v[132:135], v[188:191], v[80:83]
	v_mfma_f32_16x16x32_bf16 v[72:75], v[140:143], v[188:191], v[72:75]
	v_mfma_f32_16x16x32_bf16 v[116:119], v[144:147], v[160:163], v[116:119]
	v_mfma_f32_16x16x32_bf16 v[108:111], v[152:155], v[160:163], v[108:111]
	v_mfma_f32_16x16x32_bf16 v[100:103], v[144:147], v[168:171], v[100:103]
	v_mfma_f32_16x16x32_bf16 v[92:95], v[152:155], v[168:171], v[92:95]
	v_mfma_f32_16x16x32_bf16 v[84:87], v[144:147], v[176:179], v[84:87]
	v_mfma_f32_16x16x32_bf16 v[76:79], v[152:155], v[176:179], v[76:79]
	v_mfma_f32_16x16x32_bf16 v[68:71], v[144:147], v[184:187], v[68:71]
	v_mfma_f32_16x16x32_bf16 v[64:67], v[152:155], v[184:187], v[64:67]
	v_mfma_f32_16x16x32_bf16 v[116:119], v[148:151], v[164:167], v[116:119]
	v_mfma_f32_16x16x32_bf16 v[108:111], v[156:159], v[164:167], v[108:111]
	v_mfma_f32_16x16x32_bf16 v[100:103], v[148:151], v[172:175], v[100:103]
	v_mfma_f32_16x16x32_bf16 v[92:95], v[156:159], v[172:175], v[92:95]
	v_mfma_f32_16x16x32_bf16 v[84:87], v[148:151], v[180:183], v[84:87]
	v_mfma_f32_16x16x32_bf16 v[76:79], v[156:159], v[180:183], v[76:79]
	v_mfma_f32_16x16x32_bf16 v[68:71], v[148:151], v[188:191], v[68:71]
	v_mfma_f32_16x16x32_bf16 v[64:67], v[156:159], v[188:191], v[64:67]
	s_barrier
	s_add_i32 s34, s62, s3
	v_lshl_add_u64 v[192:193], v[192:193], 0, s[10:11]
	s_mov_b32 m0, s34
	ds_read_b128 v[160:163], v248 offset:49152
	ds_read_b128 v[164:167], v248 offset:50176
	ds_read_b128 v[168:171], v248 offset:51200
	ds_read_b128 v[172:175], v248 offset:52224
	ds_read_b128 v[176:179], v248 offset:53248
	ds_read_b128 v[180:183], v248 offset:54272
	ds_read_b128 v[184:187], v248 offset:55296
	ds_read_b128 v[188:191], v248 offset:56320
	global_load_lds_dwordx4 v[192:193], off
	s_add_i32 m0, s34, 0x2000
	s_add_u32 s6, s6, 0x40080
	v_lshl_add_u64 v[192:193], v[194:195], 0, s[10:11]
	s_addc_u32 s7, s7, 0
	s_add_i32 s34, s63, s3
	global_load_lds_dwordx4 v[192:193], off
	s_mov_b32 m0, s34
	s_nop 0
	global_load_lds_dwordx4 v212, s[6:7]
	s_add_i32 m0, s34, 0x2000
	s_nop 0
	global_load_lds_dwordx4 v208, s[6:7]
	v_lshl_add_u64 v[192:193], v[196:197], 0, s[10:11]
	s_mov_b32 m0, s44
	s_nop 0
	global_load_lds_dwordx4 v[192:193], off
	v_lshl_add_u64 v[192:193], v[198:199], 0, s[10:11]
	s_mov_b32 m0, s45
	s_nop 0
	global_load_lds_dwordx4 v[192:193], off
	s_waitcnt vmcnt(8) lgkmcnt(0)
	s_barrier
	v_mfma_f32_16x16x32_bf16 v[60:63], v[128:131], v[160:163], v[60:63]
	v_mfma_f32_16x16x32_bf16 v[56:59], v[136:139], v[160:163], v[56:59]
	v_mfma_f32_16x16x32_bf16 v[48:51], v[128:131], v[168:171], v[48:51]
	v_mfma_f32_16x16x32_bf16 v[40:43], v[136:139], v[168:171], v[40:43]
	v_mfma_f32_16x16x32_bf16 v[32:35], v[128:131], v[176:179], v[32:35]
	v_mfma_f32_16x16x32_bf16 v[24:27], v[136:139], v[176:179], v[24:27]
	v_mfma_f32_16x16x32_bf16 v[16:19], v[128:131], v[184:187], v[16:19]
	v_mfma_f32_16x16x32_bf16 v[8:11], v[136:139], v[184:187], v[8:11]
	v_mfma_f32_16x16x32_bf16 v[60:63], v[132:135], v[164:167], v[60:63]
	v_mfma_f32_16x16x32_bf16 v[56:59], v[140:143], v[164:167], v[56:59]
	v_mfma_f32_16x16x32_bf16 v[48:51], v[132:135], v[172:175], v[48:51]
	v_mfma_f32_16x16x32_bf16 v[40:43], v[140:143], v[172:175], v[40:43]
	v_mfma_f32_16x16x32_bf16 v[32:35], v[132:135], v[180:183], v[32:35]
	v_mfma_f32_16x16x32_bf16 v[24:27], v[140:143], v[180:183], v[24:27]
	v_mfma_f32_16x16x32_bf16 v[16:19], v[132:135], v[188:191], v[16:19]
	v_mfma_f32_16x16x32_bf16 v[8:11], v[140:143], v[188:191], v[8:11]
	v_mfma_f32_16x16x32_bf16 v[52:55], v[144:147], v[160:163], v[52:55]
	v_mfma_f32_16x16x32_bf16 v[44:47], v[152:155], v[160:163], v[44:47]
	v_mfma_f32_16x16x32_bf16 v[36:39], v[144:147], v[168:171], v[36:39]
	v_mfma_f32_16x16x32_bf16 v[28:31], v[152:155], v[168:171], v[28:31]
	v_mfma_f32_16x16x32_bf16 v[20:23], v[144:147], v[176:179], v[20:23]
	v_mfma_f32_16x16x32_bf16 v[12:15], v[152:155], v[176:179], v[12:15]
	v_mfma_f32_16x16x32_bf16 v[4:7], v[144:147], v[184:187], v[4:7]
	v_mfma_f32_16x16x32_bf16 v[0:3], v[152:155], v[184:187], v[0:3]
	v_mfma_f32_16x16x32_bf16 v[52:55], v[148:151], v[164:167], v[52:55]
	v_mfma_f32_16x16x32_bf16 v[44:47], v[156:159], v[164:167], v[44:47]
	v_mfma_f32_16x16x32_bf16 v[36:39], v[148:151], v[172:175], v[36:39]
	v_mfma_f32_16x16x32_bf16 v[28:31], v[156:159], v[172:175], v[28:31]
	v_mfma_f32_16x16x32_bf16 v[20:23], v[148:151], v[180:183], v[20:23]
	v_mfma_f32_16x16x32_bf16 v[12:15], v[156:159], v[180:183], v[12:15]
	v_mfma_f32_16x16x32_bf16 v[4:7], v[148:151], v[188:191], v[4:7]
	v_mfma_f32_16x16x32_bf16 v[0:3], v[156:159], v[188:191], v[0:3]
	s_barrier
	s_add_i32 s61, s61, 2
	s_add_u32 s23, s23, 0x100
	s_addc_u32 s60, s60, 0
	s_add_u32 s4, s4, 0x100
	s_addc_u32 s5, s5, 0
.LBB0_1519:
	ds_read_b128 v[128:131], v246
	ds_read_b128 v[132:135], v246 offset:1024
	ds_read_b128 v[136:139], v246 offset:2048
	ds_read_b128 v[140:143], v246 offset:3072
	ds_read_b128 v[144:147], v247
	ds_read_b128 v[148:151], v247 offset:1024
	ds_read_b128 v[152:155], v247 offset:2048
	ds_read_b128 v[156:159], v247 offset:3072
	s_add_u32 s6, s4, 0xfffc0080
	s_addc_u32 s7, s5, -1
	s_cmp_eq_u32 s61, 12
	s_cselect_b32 s35, s25, s7
	s_cselect_b32 s34, s24, s6
	s_cselect_b32 s7, s27, s60
	s_cselect_b32 s6, s26, s23
	s_add_i32 m0, s36, 0xc000
	ds_read_b128 v[160:163], v248
	ds_read_b128 v[164:167], v248 offset:1024
	ds_read_b128 v[168:171], v248 offset:2048
	ds_read_b128 v[172:175], v248 offset:3072
	ds_read_b128 v[176:179], v248 offset:4096
	ds_read_b128 v[180:183], v248 offset:5120
	ds_read_b128 v[184:187], v248 offset:6144
	ds_read_b128 v[188:191], v248 offset:7168
	global_load_lds_dwordx4 v218, s[4:5]
	s_add_i32 m0, s36, 0xe000
	s_nop 0
	global_load_lds_dwordx4 v216, s[4:5]
	s_waitcnt vmcnt(8) lgkmcnt(0)
	s_barrier
	v_mfma_f32_16x16x32_bf16 v[124:127], v[128:131], v[160:163], v[124:127]
	v_mfma_f32_16x16x32_bf16 v[120:123], v[136:139], v[160:163], v[120:123]
	v_mfma_f32_16x16x32_bf16 v[112:115], v[128:131], v[168:171], v[112:115]
	v_mfma_f32_16x16x32_bf16 v[104:107], v[136:139], v[168:171], v[104:107]
	v_mfma_f32_16x16x32_bf16 v[96:99], v[128:131], v[176:179], v[96:99]
	v_mfma_f32_16x16x32_bf16 v[88:91], v[136:139], v[176:179], v[88:91]
	v_mfma_f32_16x16x32_bf16 v[80:83], v[128:131], v[184:187], v[80:83]
	v_mfma_f32_16x16x32_bf16 v[72:75], v[136:139], v[184:187], v[72:75]
	v_mfma_f32_16x16x32_bf16 v[124:127], v[132:135], v[164:167], v[124:127]
	v_mfma_f32_16x16x32_bf16 v[120:123], v[140:143], v[164:167], v[120:123]
	v_mfma_f32_16x16x32_bf16 v[112:115], v[132:135], v[172:175], v[112:115]
	v_mfma_f32_16x16x32_bf16 v[104:107], v[140:143], v[172:175], v[104:107]
	v_mfma_f32_16x16x32_bf16 v[96:99], v[132:135], v[180:183], v[96:99]
	v_mfma_f32_16x16x32_bf16 v[88:91], v[140:143], v[180:183], v[88:91]
	v_mfma_f32_16x16x32_bf16 v[80:83], v[132:135], v[188:191], v[80:83]
	v_mfma_f32_16x16x32_bf16 v[72:75], v[140:143], v[188:191], v[72:75]
	v_mfma_f32_16x16x32_bf16 v[116:119], v[144:147], v[160:163], v[116:119]
	v_mfma_f32_16x16x32_bf16 v[108:111], v[152:155], v[160:163], v[108:111]
	v_mfma_f32_16x16x32_bf16 v[100:103], v[144:147], v[168:171], v[100:103]
	v_mfma_f32_16x16x32_bf16 v[92:95], v[152:155], v[168:171], v[92:95]
	v_mfma_f32_16x16x32_bf16 v[84:87], v[144:147], v[176:179], v[84:87]
	v_mfma_f32_16x16x32_bf16 v[76:79], v[152:155], v[176:179], v[76:79]
	v_mfma_f32_16x16x32_bf16 v[68:71], v[144:147], v[184:187], v[68:71]
	v_mfma_f32_16x16x32_bf16 v[64:67], v[152:155], v[184:187], v[64:67]
	v_mfma_f32_16x16x32_bf16 v[116:119], v[148:151], v[164:167], v[116:119]
	v_mfma_f32_16x16x32_bf16 v[108:111], v[156:159], v[164:167], v[108:111]
	v_mfma_f32_16x16x32_bf16 v[100:103], v[148:151], v[172:175], v[100:103]
	v_mfma_f32_16x16x32_bf16 v[92:95], v[156:159], v[172:175], v[92:95]
	v_mfma_f32_16x16x32_bf16 v[84:87], v[148:151], v[180:183], v[84:87]
	v_mfma_f32_16x16x32_bf16 v[76:79], v[156:159], v[180:183], v[76:79]
	v_mfma_f32_16x16x32_bf16 v[68:71], v[148:151], v[188:191], v[68:71]
	v_mfma_f32_16x16x32_bf16 v[64:67], v[156:159], v[188:191], v[64:67]
	s_barrier
	s_add_i32 s62, s48, s3
	v_lshl_add_u64 v[192:193], s[6:7], 0, v[212:213]
	s_mov_b32 m0, s62
	ds_read_b128 v[160:163], v248 offset:16384
	ds_read_b128 v[164:167], v248 offset:17408
	ds_read_b128 v[168:171], v248 offset:18432
	ds_read_b128 v[172:175], v248 offset:19456
	ds_read_b128 v[176:179], v248 offset:20480
	ds_read_b128 v[180:183], v248 offset:21504
	ds_read_b128 v[184:187], v248 offset:22528
	ds_read_b128 v[188:191], v248 offset:23552
	global_load_lds_dwordx4 v[192:193], off
	s_add_i32 m0, s62, 0x2000
	s_add_u32 s62, s6, 0x40000
	v_lshl_add_u64 v[194:195], s[6:7], 0, v[208:209]
	s_addc_u32 s63, s7, 0
	s_add_i32 s64, s49, s3
	global_load_lds_dwordx4 v[194:195], off
	s_mov_b32 m0, s64
	v_lshl_add_u64 v[198:199], s[34:35], 0, v[210:211]
	global_load_lds_dwordx4 v212, s[62:63]
	s_add_i32 m0, s64, 0x2000
	s_nop 0
	global_load_lds_dwordx4 v208, s[62:63]
	v_lshl_add_u64 v[196:197], s[34:35], 0, v[214:215]
	s_mov_b32 m0, s36
	s_nop 0
	global_load_lds_dwordx4 v[196:197], off
	s_mov_b32 m0, s37
	s_nop 0
	global_load_lds_dwordx4 v[198:199], off
	s_waitcnt vmcnt(8) lgkmcnt(0)
	s_barrier
	v_mfma_f32_16x16x32_bf16 v[60:63], v[128:131], v[160:163], v[60:63]
	v_mfma_f32_16x16x32_bf16 v[56:59], v[136:139], v[160:163], v[56:59]
	v_mfma_f32_16x16x32_bf16 v[48:51], v[128:131], v[168:171], v[48:51]
	v_mfma_f32_16x16x32_bf16 v[40:43], v[136:139], v[168:171], v[40:43]
	v_mfma_f32_16x16x32_bf16 v[32:35], v[128:131], v[176:179], v[32:35]
	v_mfma_f32_16x16x32_bf16 v[24:27], v[136:139], v[176:179], v[24:27]
	v_mfma_f32_16x16x32_bf16 v[16:19], v[128:131], v[184:187], v[16:19]
	v_mfma_f32_16x16x32_bf16 v[8:11], v[136:139], v[184:187], v[8:11]
	v_mfma_f32_16x16x32_bf16 v[60:63], v[132:135], v[164:167], v[60:63]
	v_mfma_f32_16x16x32_bf16 v[56:59], v[140:143], v[164:167], v[56:59]
	v_mfma_f32_16x16x32_bf16 v[48:51], v[132:135], v[172:175], v[48:51]
	v_mfma_f32_16x16x32_bf16 v[40:43], v[140:143], v[172:175], v[40:43]
	v_mfma_f32_16x16x32_bf16 v[32:35], v[132:135], v[180:183], v[32:35]
	v_mfma_f32_16x16x32_bf16 v[24:27], v[140:143], v[180:183], v[24:27]
	v_mfma_f32_16x16x32_bf16 v[16:19], v[132:135], v[188:191], v[16:19]
	v_mfma_f32_16x16x32_bf16 v[8:11], v[140:143], v[188:191], v[8:11]
	v_mfma_f32_16x16x32_bf16 v[52:55], v[144:147], v[160:163], v[52:55]
	v_mfma_f32_16x16x32_bf16 v[44:47], v[152:155], v[160:163], v[44:47]
	v_mfma_f32_16x16x32_bf16 v[36:39], v[144:147], v[168:171], v[36:39]
	v_mfma_f32_16x16x32_bf16 v[28:31], v[152:155], v[168:171], v[28:31]
	v_mfma_f32_16x16x32_bf16 v[20:23], v[144:147], v[176:179], v[20:23]
	v_mfma_f32_16x16x32_bf16 v[12:15], v[152:155], v[176:179], v[12:15]
	v_mfma_f32_16x16x32_bf16 v[4:7], v[144:147], v[184:187], v[4:7]
	v_mfma_f32_16x16x32_bf16 v[0:3], v[152:155], v[184:187], v[0:3]
	v_mfma_f32_16x16x32_bf16 v[52:55], v[148:151], v[164:167], v[52:55]
	v_mfma_f32_16x16x32_bf16 v[44:47], v[156:159], v[164:167], v[44:47]
	v_mfma_f32_16x16x32_bf16 v[36:39], v[148:151], v[172:175], v[36:39]
	v_mfma_f32_16x16x32_bf16 v[28:31], v[156:159], v[172:175], v[28:31]
	v_mfma_f32_16x16x32_bf16 v[20:23], v[148:151], v[180:183], v[20:23]
	v_mfma_f32_16x16x32_bf16 v[12:15], v[156:159], v[180:183], v[12:15]
	v_mfma_f32_16x16x32_bf16 v[4:7], v[148:151], v[188:191], v[4:7]
	v_mfma_f32_16x16x32_bf16 v[0:3], v[156:159], v[188:191], v[0:3]
	s_barrier
	s_add_i32 s62, 0, 0x18000
	s_add_i32 s63, 0, 0x1c000
	v_add_u32_e32 v140, s62, v245
	v_add_u32_e32 v156, s63, v245
	ds_read_b128 v[128:131], v140
	ds_read_b128 v[132:135], v140 offset:1024
	ds_read_b128 v[136:139], v140 offset:2048
	ds_read_b128 v[140:143], v140 offset:3072
	ds_read_b128 v[144:147], v156
	ds_read_b128 v[148:151], v156 offset:1024
	ds_read_b128 v[152:155], v156 offset:2048
	ds_read_b128 v[156:159], v156 offset:3072
	s_add_u32 s34, s34, 0x40000
	s_addc_u32 s35, s35, 0
	s_mov_b32 m0, s38
	ds_read_b128 v[160:163], v248 offset:32768
	ds_read_b128 v[164:167], v248 offset:33792
	ds_read_b128 v[168:171], v248 offset:34816
	ds_read_b128 v[172:175], v248 offset:35840
	ds_read_b128 v[176:179], v248 offset:36864
	ds_read_b128 v[180:183], v248 offset:37888
	ds_read_b128 v[184:187], v248 offset:38912
	ds_read_b128 v[188:191], v248 offset:39936
	global_load_lds_dwordx4 v214, s[34:35]
	s_mov_b32 m0, s39
	s_nop 0
	global_load_lds_dwordx4 v210, s[34:35]
	s_waitcnt vmcnt(8) lgkmcnt(0)
	s_barrier
	v_mfma_f32_16x16x32_bf16 v[124:127], v[128:131], v[160:163], v[124:127]
	v_mfma_f32_16x16x32_bf16 v[120:123], v[136:139], v[160:163], v[120:123]
	v_mfma_f32_16x16x32_bf16 v[112:115], v[128:131], v[168:171], v[112:115]
	v_mfma_f32_16x16x32_bf16 v[104:107], v[136:139], v[168:171], v[104:107]
	v_mfma_f32_16x16x32_bf16 v[96:99], v[128:131], v[176:179], v[96:99]
	v_mfma_f32_16x16x32_bf16 v[88:91], v[136:139], v[176:179], v[88:91]
	v_mfma_f32_16x16x32_bf16 v[80:83], v[128:131], v[184:187], v[80:83]
	v_mfma_f32_16x16x32_bf16 v[72:75], v[136:139], v[184:187], v[72:75]
	v_mfma_f32_16x16x32_bf16 v[124:127], v[132:135], v[164:167], v[124:127]
	v_mfma_f32_16x16x32_bf16 v[120:123], v[140:143], v[164:167], v[120:123]
	v_mfma_f32_16x16x32_bf16 v[112:115], v[132:135], v[172:175], v[112:115]
	v_mfma_f32_16x16x32_bf16 v[104:107], v[140:143], v[172:175], v[104:107]
	v_mfma_f32_16x16x32_bf16 v[96:99], v[132:135], v[180:183], v[96:99]
	v_mfma_f32_16x16x32_bf16 v[88:91], v[140:143], v[180:183], v[88:91]
	v_mfma_f32_16x16x32_bf16 v[80:83], v[132:135], v[188:191], v[80:83]
	v_mfma_f32_16x16x32_bf16 v[72:75], v[140:143], v[188:191], v[72:75]
	v_mfma_f32_16x16x32_bf16 v[116:119], v[144:147], v[160:163], v[116:119]
	v_mfma_f32_16x16x32_bf16 v[108:111], v[152:155], v[160:163], v[108:111]
	v_mfma_f32_16x16x32_bf16 v[100:103], v[144:147], v[168:171], v[100:103]
	v_mfma_f32_16x16x32_bf16 v[92:95], v[152:155], v[168:171], v[92:95]
	v_mfma_f32_16x16x32_bf16 v[84:87], v[144:147], v[176:179], v[84:87]
	v_mfma_f32_16x16x32_bf16 v[76:79], v[152:155], v[176:179], v[76:79]
	v_mfma_f32_16x16x32_bf16 v[68:71], v[144:147], v[184:187], v[68:71]
	v_mfma_f32_16x16x32_bf16 v[64:67], v[152:155], v[184:187], v[64:67]
	v_mfma_f32_16x16x32_bf16 v[116:119], v[148:151], v[164:167], v[116:119]
	v_mfma_f32_16x16x32_bf16 v[108:111], v[156:159], v[164:167], v[108:111]
	v_mfma_f32_16x16x32_bf16 v[100:103], v[148:151], v[172:175], v[100:103]
	v_mfma_f32_16x16x32_bf16 v[92:95], v[156:159], v[172:175], v[92:95]
	v_mfma_f32_16x16x32_bf16 v[84:87], v[148:151], v[180:183], v[84:87]
	v_mfma_f32_16x16x32_bf16 v[76:79], v[156:159], v[180:183], v[76:79]
	v_mfma_f32_16x16x32_bf16 v[68:71], v[148:151], v[188:191], v[68:71]
	v_mfma_f32_16x16x32_bf16 v[64:67], v[156:159], v[188:191], v[64:67]
	s_barrier
	s_add_i32 s34, s62, s3
	v_lshl_add_u64 v[192:193], v[192:193], 0, s[10:11]
	s_mov_b32 m0, s34
	ds_read_b128 v[160:163], v248 offset:49152
	ds_read_b128 v[164:167], v248 offset:50176
	ds_read_b128 v[168:171], v248 offset:51200
	ds_read_b128 v[172:175], v248 offset:52224
	ds_read_b128 v[176:179], v248 offset:53248
	ds_read_b128 v[180:183], v248 offset:54272
	ds_read_b128 v[184:187], v248 offset:55296
	ds_read_b128 v[188:191], v248 offset:56320
	global_load_lds_dwordx4 v[192:193], off
	s_add_i32 m0, s34, 0x2000
	s_add_u32 s6, s6, 0x40080
	v_lshl_add_u64 v[192:193], v[194:195], 0, s[10:11]
	s_addc_u32 s7, s7, 0
	s_add_i32 s34, s63, s3
	global_load_lds_dwordx4 v[192:193], off
	s_mov_b32 m0, s34
	s_nop 0
	global_load_lds_dwordx4 v212, s[6:7]
	s_add_i32 m0, s34, 0x2000
	s_nop 0
	global_load_lds_dwordx4 v208, s[6:7]
	v_lshl_add_u64 v[192:193], v[196:197], 0, s[10:11]
	s_mov_b32 m0, s44
	s_nop 0
	global_load_lds_dwordx4 v[192:193], off
	v_lshl_add_u64 v[192:193], v[198:199], 0, s[10:11]
	s_mov_b32 m0, s45
	s_nop 0
	global_load_lds_dwordx4 v[192:193], off
	s_waitcnt vmcnt(8) lgkmcnt(0)
	s_barrier
	v_mfma_f32_16x16x32_bf16 v[60:63], v[128:131], v[160:163], v[60:63]
	v_mfma_f32_16x16x32_bf16 v[56:59], v[136:139], v[160:163], v[56:59]
	v_mfma_f32_16x16x32_bf16 v[48:51], v[128:131], v[168:171], v[48:51]
	v_mfma_f32_16x16x32_bf16 v[40:43], v[136:139], v[168:171], v[40:43]
	v_mfma_f32_16x16x32_bf16 v[32:35], v[128:131], v[176:179], v[32:35]
	v_mfma_f32_16x16x32_bf16 v[24:27], v[136:139], v[176:179], v[24:27]
	v_mfma_f32_16x16x32_bf16 v[16:19], v[128:131], v[184:187], v[16:19]
	v_mfma_f32_16x16x32_bf16 v[8:11], v[136:139], v[184:187], v[8:11]
	v_mfma_f32_16x16x32_bf16 v[60:63], v[132:135], v[164:167], v[60:63]
	v_mfma_f32_16x16x32_bf16 v[56:59], v[140:143], v[164:167], v[56:59]
	v_mfma_f32_16x16x32_bf16 v[48:51], v[132:135], v[172:175], v[48:51]
	v_mfma_f32_16x16x32_bf16 v[40:43], v[140:143], v[172:175], v[40:43]
	v_mfma_f32_16x16x32_bf16 v[32:35], v[132:135], v[180:183], v[32:35]
	v_mfma_f32_16x16x32_bf16 v[24:27], v[140:143], v[180:183], v[24:27]
	v_mfma_f32_16x16x32_bf16 v[16:19], v[132:135], v[188:191], v[16:19]
	v_mfma_f32_16x16x32_bf16 v[8:11], v[140:143], v[188:191], v[8:11]
	v_mfma_f32_16x16x32_bf16 v[52:55], v[144:147], v[160:163], v[52:55]
	v_mfma_f32_16x16x32_bf16 v[44:47], v[152:155], v[160:163], v[44:47]
	v_mfma_f32_16x16x32_bf16 v[36:39], v[144:147], v[168:171], v[36:39]
	v_mfma_f32_16x16x32_bf16 v[28:31], v[152:155], v[168:171], v[28:31]
	v_mfma_f32_16x16x32_bf16 v[20:23], v[144:147], v[176:179], v[20:23]
	v_mfma_f32_16x16x32_bf16 v[12:15], v[152:155], v[176:179], v[12:15]
	v_mfma_f32_16x16x32_bf16 v[4:7], v[144:147], v[184:187], v[4:7]
	v_mfma_f32_16x16x32_bf16 v[0:3], v[152:155], v[184:187], v[0:3]
	v_mfma_f32_16x16x32_bf16 v[52:55], v[148:151], v[164:167], v[52:55]
	v_mfma_f32_16x16x32_bf16 v[44:47], v[156:159], v[164:167], v[44:47]
	v_mfma_f32_16x16x32_bf16 v[36:39], v[148:151], v[172:175], v[36:39]
	v_mfma_f32_16x16x32_bf16 v[28:31], v[156:159], v[172:175], v[28:31]
	v_mfma_f32_16x16x32_bf16 v[20:23], v[148:151], v[180:183], v[20:23]
	v_mfma_f32_16x16x32_bf16 v[12:15], v[156:159], v[180:183], v[12:15]
	v_mfma_f32_16x16x32_bf16 v[4:7], v[148:151], v[188:191], v[4:7]
	v_mfma_f32_16x16x32_bf16 v[0:3], v[156:159], v[188:191], v[0:3]
	s_barrier
	s_add_i32 s61, s61, 2
	s_add_u32 s23, s23, 0x100
	s_addc_u32 s60, s60, 0
	s_add_u32 s4, s4, 0x100
	s_addc_u32 s5, s5, 0
	s_cmp_gt_u32 s61, 13
	s_cbranch_scc0 .LBB0_1519
	s_and_b64 vcc, exec, s[12:13]
	s_cbranch_vccz .LBB0_1522
	s_barrier
